# as previous plus GEMM epilogue stores use sc1 write-through instead of nt
# baseline (speedup 1.0000x reference)
.LBB0_178:
	v_mov_b32_e32 v136, v139
	s_lshl_b32 s29, s38, 8
	s_add_i32 s29, s29, s62
	v_and_or_b32 v145, v136, 15, s29
	s_lshl_b32 s29, s73, 7
	v_lshrrev_b32_e32 v136, 1, v136
	v_and_or_b32 v136, v136, 24, s29
	v_or_b32_e32 v146, s63, v136
	v_mul_f32_e32 v136, 0xbfb8aa3b, v124
	v_exp_f32_e32 v136, v136
	v_mul_f32_e32 v137, 0xbfb8aa3b, v125
	v_exp_f32_e32 v137, v137
	v_ashrrev_i32_e32 v147, 31, v146
	v_add_f32_e32 v136, 1.0, v136
	v_rcp_f32_e32 v148, v136
	v_add_f32_e32 v136, 1.0, v137
	v_rcp_f32_e32 v149, v136
	v_mov_b64_e32 v[136:137], s[16:17]
	v_mad_i64_i32 v[150:151], s[40:41], v145, s65, v[136:137]
	v_pk_mul_f32 v[124:125], v[124:125], v[148:149]
	v_mul_f32_e32 v148, 0xbfb8aa3b, v126
	v_mul_f32_e32 v149, 0xbfb8aa3b, v127
	v_exp_f32_e32 v148, v148
	v_exp_f32_e32 v149, v149
	v_pk_mul_f32 v[120:121], v[124:125], v[120:121]
	s_andn2_b64 vcc, exec, s[4:5]
	v_add_f32_e32 v124, 1.0, v148
	v_add_f32_e32 v125, 1.0, v149
	v_mul_f32_e32 v148, 0xbfb8aa3b, v112
	v_mul_f32_e32 v149, 0xbfb8aa3b, v113
	v_rcp_f32_e32 v124, v124
	v_rcp_f32_e32 v125, v125
	v_exp_f32_e32 v148, v148
	v_exp_f32_e32 v149, v149
	s_mov_b64 s[4:5], -1
	v_pk_mul_f32 v[124:125], v[126:127], v[124:125]
	v_add_f32_e32 v126, 1.0, v148
	v_add_f32_e32 v127, 1.0, v149
	v_mul_f32_e32 v148, 0xbfb8aa3b, v114
	v_mul_f32_e32 v149, 0xbfb8aa3b, v115
	v_exp_f32_e32 v148, v148
	v_exp_f32_e32 v149, v149
	v_rcp_f32_e32 v126, v126
	v_rcp_f32_e32 v127, v127
	v_add_f32_e32 v148, 1.0, v148
	v_add_f32_e32 v149, 1.0, v149
	v_rcp_f32_e32 v148, v148
	v_rcp_f32_e32 v149, v149
	v_pk_mul_f32 v[112:113], v[112:113], v[126:127]
	v_pk_mul_f32 v[122:123], v[124:125], v[122:123]
	v_pk_mul_f32 v[116:117], v[112:113], v[116:117]
	v_pk_mul_f32 v[112:113], v[114:115], v[148:149]
	v_cvt_pk_bf16_f32 v116, v116, v117
	v_pk_mul_f32 v[118:119], v[112:113], v[118:119]
	v_lshlrev_b64 v[112:113], 1, v[146:147]
	v_cvt_pk_bf16_f32 v117, v118, v119
	v_mul_f32_e32 v118, 0xbfb8aa3b, v108
	v_mul_f32_e32 v119, 0xbfb8aa3b, v109
	v_exp_f32_e32 v118, v118
	v_exp_f32_e32 v119, v119
	v_lshl_add_u64 v[124:125], v[150:151], 0, v[112:113]
	v_cvt_pk_bf16_f32 v114, v120, v121
	v_cvt_pk_bf16_f32 v115, v122, v123
	global_store_dwordx4 v[124:125], v[114:117], off sc1
	s_nop 1
	v_add_f32_e32 v114, 1.0, v118
	v_add_f32_e32 v115, 1.0, v119
	v_rcp_f32_e32 v114, v114
	v_rcp_f32_e32 v115, v115
	v_or_b32_e32 v116, 16, v145
	v_mad_i64_i32 v[116:117], s[40:41], v116, s65, v[136:137]
	v_pk_mul_f32 v[108:109], v[108:109], v[114:115]
	v_mul_f32_e32 v114, 0xbfb8aa3b, v110
	v_mul_f32_e32 v115, 0xbfb8aa3b, v111
	v_exp_f32_e32 v114, v114
	v_exp_f32_e32 v115, v115
	v_pk_mul_f32 v[104:105], v[108:109], v[104:105]
	v_add_f32_e32 v108, 1.0, v114
	v_add_f32_e32 v109, 1.0, v115
	v_mul_f32_e32 v114, 0xbfb8aa3b, v96
	v_mul_f32_e32 v115, 0xbfb8aa3b, v97
	v_rcp_f32_e32 v108, v108
	v_rcp_f32_e32 v109, v109
	v_exp_f32_e32 v114, v114
	v_exp_f32_e32 v115, v115
	v_pk_mul_f32 v[108:109], v[110:111], v[108:109]
	v_add_f32_e32 v110, 1.0, v114
	v_add_f32_e32 v111, 1.0, v115
	v_mul_f32_e32 v114, 0xbfb8aa3b, v98
	v_mul_f32_e32 v115, 0xbfb8aa3b, v99
	v_exp_f32_e32 v114, v114
	v_exp_f32_e32 v115, v115
	v_rcp_f32_e32 v110, v110
	v_rcp_f32_e32 v111, v111
	v_add_f32_e32 v114, 1.0, v114
	v_add_f32_e32 v115, 1.0, v115
	v_rcp_f32_e32 v114, v114
	v_rcp_f32_e32 v115, v115
	v_pk_mul_f32 v[96:97], v[96:97], v[110:111]
	v_pk_mul_f32 v[106:107], v[108:109], v[106:107]
	v_pk_mul_f32 v[100:101], v[96:97], v[100:101]
	v_pk_mul_f32 v[96:97], v[98:99], v[114:115]
	v_cvt_pk_bf16_f32 v98, v100, v101
	v_mul_f32_e32 v100, 0xbfb8aa3b, v92
	v_mul_f32_e32 v101, 0xbfb8aa3b, v93
	v_exp_f32_e32 v100, v100
	v_exp_f32_e32 v101, v101
	v_pk_mul_f32 v[102:103], v[96:97], v[102:103]
	v_lshl_add_u64 v[108:109], v[116:117], 0, v[112:113]
	v_cvt_pk_bf16_f32 v96, v104, v105
	v_cvt_pk_bf16_f32 v97, v106, v107
	v_cvt_pk_bf16_f32 v99, v102, v103
	global_store_dwordx4 v[108:109], v[96:99], off sc1
	s_nop 1
	v_add_f32_e32 v96, 1.0, v100
	v_add_f32_e32 v97, 1.0, v101
	v_rcp_f32_e32 v96, v96
	v_rcp_f32_e32 v97, v97
	v_or_b32_e32 v98, 32, v145
	v_mad_i64_i32 v[98:99], s[40:41], v98, s65, v[136:137]
	v_pk_mul_f32 v[92:93], v[92:93], v[96:97]
	v_mul_f32_e32 v96, 0xbfb8aa3b, v94
	v_mul_f32_e32 v97, 0xbfb8aa3b, v95
	v_exp_f32_e32 v96, v96
	v_exp_f32_e32 v97, v97
	v_pk_mul_f32 v[88:89], v[92:93], v[88:89]
	v_add_f32_e32 v92, 1.0, v96
	v_add_f32_e32 v93, 1.0, v97
	v_mul_f32_e32 v96, 0xbfb8aa3b, v80
	v_mul_f32_e32 v97, 0xbfb8aa3b, v81
	v_rcp_f32_e32 v92, v92
	v_rcp_f32_e32 v93, v93
	v_exp_f32_e32 v96, v96
	v_exp_f32_e32 v97, v97
	v_pk_mul_f32 v[92:93], v[94:95], v[92:93]
	v_add_f32_e32 v94, 1.0, v96
	v_add_f32_e32 v95, 1.0, v97
	v_mul_f32_e32 v96, 0xbfb8aa3b, v82
	v_mul_f32_e32 v97, 0xbfb8aa3b, v83
	v_exp_f32_e32 v96, v96
	v_exp_f32_e32 v97, v97
	v_rcp_f32_e32 v94, v94
	v_rcp_f32_e32 v95, v95
	v_add_f32_e32 v96, 1.0, v96
	v_add_f32_e32 v97, 1.0, v97
	v_rcp_f32_e32 v96, v96
	v_rcp_f32_e32 v97, v97
	v_pk_mul_f32 v[80:81], v[80:81], v[94:95]
	v_pk_mul_f32 v[90:91], v[92:93], v[90:91]
	v_pk_mul_f32 v[84:85], v[80:81], v[84:85]
	v_pk_mul_f32 v[80:81], v[82:83], v[96:97]
	v_cvt_pk_bf16_f32 v82, v84, v85
	v_mul_f32_e32 v84, 0xbfb8aa3b, v76
	v_mul_f32_e32 v85, 0xbfb8aa3b, v77
	v_exp_f32_e32 v84, v84
	v_exp_f32_e32 v85, v85
	v_pk_mul_f32 v[86:87], v[80:81], v[86:87]
	v_lshl_add_u64 v[92:93], v[98:99], 0, v[112:113]
	v_cvt_pk_bf16_f32 v80, v88, v89
	v_cvt_pk_bf16_f32 v81, v90, v91
	v_cvt_pk_bf16_f32 v83, v86, v87
	global_store_dwordx4 v[92:93], v[80:83], off sc1
	s_nop 1
	v_add_f32_e32 v80, 1.0, v84
	v_add_f32_e32 v81, 1.0, v85
	v_rcp_f32_e32 v80, v80
	v_rcp_f32_e32 v81, v81
	v_or_b32_e32 v82, 48, v145
	v_mad_i64_i32 v[82:83], s[40:41], v82, s65, v[136:137]
	v_pk_mul_f32 v[76:77], v[76:77], v[80:81]
	v_mul_f32_e32 v80, 0xbfb8aa3b, v78
	v_mul_f32_e32 v81, 0xbfb8aa3b, v79
	v_exp_f32_e32 v80, v80
	v_exp_f32_e32 v81, v81
	v_pk_mul_f32 v[72:73], v[76:77], v[72:73]
	v_add_f32_e32 v76, 1.0, v80
	v_add_f32_e32 v77, 1.0, v81
	v_mul_f32_e32 v80, 0xbfb8aa3b, v64
	v_mul_f32_e32 v81, 0xbfb8aa3b, v65
	v_rcp_f32_e32 v76, v76
	v_rcp_f32_e32 v77, v77
	v_exp_f32_e32 v80, v80
	v_exp_f32_e32 v81, v81
	v_pk_mul_f32 v[76:77], v[78:79], v[76:77]
	v_add_f32_e32 v78, 1.0, v80
	v_add_f32_e32 v79, 1.0, v81
	v_mul_f32_e32 v80, 0xbfb8aa3b, v66
	v_mul_f32_e32 v81, 0xbfb8aa3b, v67
	v_exp_f32_e32 v80, v80
	v_exp_f32_e32 v81, v81
	v_rcp_f32_e32 v78, v78
	v_rcp_f32_e32 v79, v79
	v_add_f32_e32 v80, 1.0, v80
	v_add_f32_e32 v81, 1.0, v81
	v_rcp_f32_e32 v80, v80
	v_rcp_f32_e32 v81, v81
	v_pk_mul_f32 v[64:65], v[64:65], v[78:79]
	v_pk_mul_f32 v[74:75], v[76:77], v[74:75]
	v_pk_mul_f32 v[68:69], v[64:65], v[68:69]
	v_pk_mul_f32 v[64:65], v[66:67], v[80:81]
	v_cvt_pk_bf16_f32 v66, v68, v69
	v_mul_f32_e32 v68, 0xbfb8aa3b, v60
	v_mul_f32_e32 v69, 0xbfb8aa3b, v61
	v_exp_f32_e32 v68, v68
	v_exp_f32_e32 v69, v69
	v_pk_mul_f32 v[70:71], v[64:65], v[70:71]
	v_lshl_add_u64 v[76:77], v[82:83], 0, v[112:113]
	v_cvt_pk_bf16_f32 v64, v72, v73
	v_cvt_pk_bf16_f32 v65, v74, v75
	v_cvt_pk_bf16_f32 v67, v70, v71
	global_store_dwordx4 v[76:77], v[64:67], off sc1
	s_nop 1
	v_add_f32_e32 v64, 1.0, v68
	v_add_f32_e32 v65, 1.0, v69
	v_rcp_f32_e32 v64, v64
	v_rcp_f32_e32 v65, v65
	v_add_u32_e32 v66, 0x80, v145
	v_mad_i64_i32 v[66:67], s[40:41], v66, s65, v[136:137]
	v_pk_mul_f32 v[60:61], v[60:61], v[64:65]
	v_mul_f32_e32 v64, 0xbfb8aa3b, v62
	v_mul_f32_e32 v65, 0xbfb8aa3b, v63
	v_exp_f32_e32 v64, v64
	v_exp_f32_e32 v65, v65
	v_pk_mul_f32 v[56:57], v[60:61], v[56:57]
	v_add_f32_e32 v60, 1.0, v64
	v_add_f32_e32 v61, 1.0, v65
	v_mul_f32_e32 v64, 0xbfb8aa3b, v48
	v_mul_f32_e32 v65, 0xbfb8aa3b, v49
	v_rcp_f32_e32 v60, v60
	v_rcp_f32_e32 v61, v61
	v_exp_f32_e32 v64, v64
	v_exp_f32_e32 v65, v65
	v_pk_mul_f32 v[60:61], v[62:63], v[60:61]
	v_add_f32_e32 v62, 1.0, v64
	v_add_f32_e32 v63, 1.0, v65
	v_mul_f32_e32 v64, 0xbfb8aa3b, v50
	v_mul_f32_e32 v65, 0xbfb8aa3b, v51
	v_exp_f32_e32 v64, v64
	v_exp_f32_e32 v65, v65
	v_rcp_f32_e32 v62, v62
	v_rcp_f32_e32 v63, v63
	v_add_f32_e32 v64, 1.0, v64
	v_add_f32_e32 v65, 1.0, v65
	v_rcp_f32_e32 v64, v64
	v_rcp_f32_e32 v65, v65
	v_pk_mul_f32 v[48:49], v[48:49], v[62:63]
	v_pk_mul_f32 v[58:59], v[60:61], v[58:59]
	v_pk_mul_f32 v[52:53], v[48:49], v[52:53]
	v_pk_mul_f32 v[48:49], v[50:51], v[64:65]
	v_cvt_pk_bf16_f32 v50, v52, v53
	v_mul_f32_e32 v52, 0xbfb8aa3b, v44
	v_mul_f32_e32 v53, 0xbfb8aa3b, v45
	v_exp_f32_e32 v52, v52
	v_exp_f32_e32 v53, v53
	v_pk_mul_f32 v[54:55], v[48:49], v[54:55]
	v_lshl_add_u64 v[60:61], v[66:67], 0, v[112:113]
	v_cvt_pk_bf16_f32 v48, v56, v57
	v_cvt_pk_bf16_f32 v49, v58, v59
	v_cvt_pk_bf16_f32 v51, v54, v55
	global_store_dwordx4 v[60:61], v[48:51], off sc1
	s_nop 1
	v_add_f32_e32 v48, 1.0, v52
	v_add_f32_e32 v49, 1.0, v53
	v_rcp_f32_e32 v48, v48
	v_rcp_f32_e32 v49, v49
	v_add_u32_e32 v50, 0x90, v145
	v_mad_i64_i32 v[50:51], s[40:41], v50, s65, v[136:137]
	v_pk_mul_f32 v[44:45], v[44:45], v[48:49]
	v_mul_f32_e32 v48, 0xbfb8aa3b, v46
	v_mul_f32_e32 v49, 0xbfb8aa3b, v47
	v_exp_f32_e32 v48, v48
	v_exp_f32_e32 v49, v49
	v_pk_mul_f32 v[40:41], v[44:45], v[40:41]
	v_add_f32_e32 v44, 1.0, v48
	v_add_f32_e32 v45, 1.0, v49
	v_mul_f32_e32 v48, 0xbfb8aa3b, v32
	v_mul_f32_e32 v49, 0xbfb8aa3b, v33
	v_rcp_f32_e32 v44, v44
	v_rcp_f32_e32 v45, v45
	v_exp_f32_e32 v48, v48
	v_exp_f32_e32 v49, v49
	v_pk_mul_f32 v[44:45], v[46:47], v[44:45]
	v_add_f32_e32 v46, 1.0, v48
	v_add_f32_e32 v47, 1.0, v49
	v_mul_f32_e32 v48, 0xbfb8aa3b, v34
	v_mul_f32_e32 v49, 0xbfb8aa3b, v35
	v_exp_f32_e32 v48, v48
	v_exp_f32_e32 v49, v49
	v_rcp_f32_e32 v46, v46
	v_rcp_f32_e32 v47, v47
	v_add_f32_e32 v48, 1.0, v48
	v_add_f32_e32 v49, 1.0, v49
	v_rcp_f32_e32 v48, v48
	v_rcp_f32_e32 v49, v49
	v_pk_mul_f32 v[32:33], v[32:33], v[46:47]
	v_pk_mul_f32 v[42:43], v[44:45], v[42:43]
	v_pk_mul_f32 v[36:37], v[32:33], v[36:37]
	v_pk_mul_f32 v[32:33], v[34:35], v[48:49]
	v_cvt_pk_bf16_f32 v34, v36, v37
	v_mul_f32_e32 v36, 0xbfb8aa3b, v28
	v_mul_f32_e32 v37, 0xbfb8aa3b, v29
	v_exp_f32_e32 v36, v36
	v_exp_f32_e32 v37, v37
	v_pk_mul_f32 v[38:39], v[32:33], v[38:39]
	v_lshl_add_u64 v[44:45], v[50:51], 0, v[112:113]
	v_cvt_pk_bf16_f32 v32, v40, v41
	v_cvt_pk_bf16_f32 v33, v42, v43
	v_cvt_pk_bf16_f32 v35, v38, v39
	global_store_dwordx4 v[44:45], v[32:35], off sc1
	s_nop 1
	v_add_f32_e32 v32, 1.0, v36
	v_add_f32_e32 v33, 1.0, v37
	v_rcp_f32_e32 v32, v32
	v_rcp_f32_e32 v33, v33
	v_add_u32_e32 v34, 0xa0, v145
	v_mad_i64_i32 v[34:35], s[40:41], v34, s65, v[136:137]
	v_pk_mul_f32 v[28:29], v[28:29], v[32:33]
	v_mul_f32_e32 v32, 0xbfb8aa3b, v30
	v_mul_f32_e32 v33, 0xbfb8aa3b, v31
	v_exp_f32_e32 v32, v32
	v_exp_f32_e32 v33, v33
	v_pk_mul_f32 v[24:25], v[28:29], v[24:25]
	v_add_f32_e32 v28, 1.0, v32
	v_add_f32_e32 v29, 1.0, v33
	v_mul_f32_e32 v32, 0xbfb8aa3b, v16
	v_mul_f32_e32 v33, 0xbfb8aa3b, v17
	v_rcp_f32_e32 v28, v28
	v_rcp_f32_e32 v29, v29
	v_exp_f32_e32 v32, v32
	v_exp_f32_e32 v33, v33
	v_pk_mul_f32 v[28:29], v[30:31], v[28:29]
	v_add_f32_e32 v30, 1.0, v32
	v_add_f32_e32 v31, 1.0, v33
	v_mul_f32_e32 v32, 0xbfb8aa3b, v18
	v_mul_f32_e32 v33, 0xbfb8aa3b, v19
	v_exp_f32_e32 v32, v32
	v_exp_f32_e32 v33, v33
	v_rcp_f32_e32 v30, v30
	v_rcp_f32_e32 v31, v31
	v_add_f32_e32 v32, 1.0, v32
	v_add_f32_e32 v33, 1.0, v33
	v_rcp_f32_e32 v32, v32
	v_rcp_f32_e32 v33, v33
	v_pk_mul_f32 v[16:17], v[16:17], v[30:31]
	v_pk_mul_f32 v[26:27], v[28:29], v[26:27]
	v_pk_mul_f32 v[20:21], v[16:17], v[20:21]
	v_pk_mul_f32 v[16:17], v[18:19], v[32:33]
	v_cvt_pk_bf16_f32 v18, v20, v21
	v_mul_f32_e32 v20, 0xbfb8aa3b, v12
	v_mul_f32_e32 v21, 0xbfb8aa3b, v13
	v_exp_f32_e32 v20, v20
	v_exp_f32_e32 v21, v21
	v_pk_mul_f32 v[22:23], v[16:17], v[22:23]
	v_lshl_add_u64 v[28:29], v[34:35], 0, v[112:113]
	v_cvt_pk_bf16_f32 v16, v24, v25
	v_cvt_pk_bf16_f32 v17, v26, v27
	v_cvt_pk_bf16_f32 v19, v22, v23
	global_store_dwordx4 v[28:29], v[16:19], off sc1
	s_nop 1
	v_add_f32_e32 v16, 1.0, v20
	v_add_f32_e32 v17, 1.0, v21
	v_rcp_f32_e32 v16, v16
	v_rcp_f32_e32 v17, v17
	v_add_u32_e32 v18, 0xb0, v145
	v_mad_i64_i32 v[18:19], s[40:41], v18, s65, v[136:137]
	v_pk_mul_f32 v[12:13], v[12:13], v[16:17]
	v_mul_f32_e32 v16, 0xbfb8aa3b, v14
	v_mul_f32_e32 v17, 0xbfb8aa3b, v15
	v_exp_f32_e32 v16, v16
	v_exp_f32_e32 v17, v17
	v_pk_mul_f32 v[8:9], v[12:13], v[8:9]
	v_add_f32_e32 v12, 1.0, v16
	v_add_f32_e32 v13, 1.0, v17
	v_mul_f32_e32 v16, 0xbfb8aa3b, v0
	v_mul_f32_e32 v17, 0xbfb8aa3b, v1
	v_rcp_f32_e32 v12, v12
	v_rcp_f32_e32 v13, v13
	v_exp_f32_e32 v16, v16
	v_exp_f32_e32 v17, v17
	v_pk_mul_f32 v[12:13], v[14:15], v[12:13]
	v_add_f32_e32 v14, 1.0, v16
	v_add_f32_e32 v15, 1.0, v17
	v_mul_f32_e32 v16, 0xbfb8aa3b, v2
	v_mul_f32_e32 v17, 0xbfb8aa3b, v3
	v_exp_f32_e32 v16, v16
	v_exp_f32_e32 v17, v17
	v_rcp_f32_e32 v14, v14
	v_rcp_f32_e32 v15, v15
	v_add_f32_e32 v16, 1.0, v16
	v_add_f32_e32 v17, 1.0, v17
	v_rcp_f32_e32 v16, v16
	v_rcp_f32_e32 v17, v17
	v_pk_mul_f32 v[0:1], v[0:1], v[14:15]
	v_pk_mul_f32 v[10:11], v[12:13], v[10:11]
	v_pk_mul_f32 v[4:5], v[0:1], v[4:5]
	v_pk_mul_f32 v[0:1], v[2:3], v[16:17]
	v_lshl_add_u64 v[12:13], v[18:19], 0, v[112:113]
	v_pk_mul_f32 v[6:7], v[0:1], v[6:7]
	v_cvt_pk_bf16_f32 v0, v8, v9
	v_cvt_pk_bf16_f32 v1, v10, v11
	v_cvt_pk_bf16_f32 v2, v4, v5
	v_cvt_pk_bf16_f32 v3, v6, v7
	global_store_dwordx4 v[12:13], v[0:3], off sc1
	s_cbranch_vccnz .LBB0_171
	s_andn2_b64 vcc, exec, s[14:15]
	s_cbranch_vccnz .LBB0_170
	s_barrier
	s_branch .LBB0_170

.LBB0_258:
	v_mov_b32_e32 v137, v139
	s_lshl_b32 s38, s69, 8
	s_add_i32 s38, s38, s60
	v_and_or_b32 v136, v137, 15, s38
	s_lshl_b32 s38, s72, 8
	v_lshrrev_b32_e32 v137, 1, v137
	v_and_or_b32 v137, v137, 24, s38
	v_or_b32_e32 v144, s61, v137
	v_ashrrev_i32_e32 v137, 31, v136
	v_ashrrev_i32_e32 v145, 31, v144
	v_lshlrev_b64 v[146:147], 11, v[136:137]
	v_lshl_add_u64 v[146:147], s[18:19], 0, v[146:147]
	v_lshlrev_b64 v[144:145], 1, v[144:145]
	v_lshl_add_u64 v[146:147], v[146:147], 0, v[144:145]
	v_cvt_pk_bf16_f32 v60, v60, v61
	v_cvt_pk_bf16_f32 v61, v62, v63
	v_cvt_pk_bf16_f32 v62, v56, v57
	v_add_co_u32_e32 v56, vcc, s65, v146
	v_cvt_pk_bf16_f32 v68, v68, v69
	v_cvt_pk_bf16_f32 v69, v70, v71
	v_cvt_pk_bf16_f32 v70, v64, v65
	v_lshl_add_u64 v[64:65], v[146:147], 0, s[30:31]
	v_addc_co_u32_e32 v57, vcc, 0, v147, vcc
	v_cvt_pk_bf16_f32 v44, v44, v45
	v_cvt_pk_bf16_f32 v45, v46, v47
	v_cvt_pk_bf16_f32 v46, v40, v41
	v_cvt_pk_bf16_f32 v47, v42, v43
	v_cvt_pk_bf16_f32 v108, v108, v109
	v_cvt_pk_bf16_f32 v109, v110, v111
	v_cvt_pk_bf16_f32 v110, v104, v105
	v_or_b32_e32 v104, 16, v136
	global_store_dwordx4 v[64:65], v[44:47], off offset:256 sc1
	v_ashrrev_i32_e32 v105, 31, v104
	v_cvt_pk_bf16_f32 v92, v92, v93
	v_add_co_u32_e32 v46, vcc, s66, v146
	v_cvt_pk_bf16_f32 v93, v94, v95
	v_cvt_pk_bf16_f32 v94, v88, v89
	v_or_b32_e32 v88, 32, v136
	v_lshl_add_u64 v[44:45], v[146:147], 0, s[34:35]
	v_addc_co_u32_e32 v47, vcc, 0, v147, vcc
	v_cvt_pk_bf16_f32 v28, v28, v29
	v_cvt_pk_bf16_f32 v29, v30, v31
	v_cvt_pk_bf16_f32 v30, v24, v25
	v_cvt_pk_bf16_f32 v31, v26, v27
	v_lshlrev_b64 v[104:105], 11, v[104:105]
	v_ashrrev_i32_e32 v89, 31, v88
	v_cvt_pk_bf16_f32 v76, v76, v77
	v_cvt_pk_bf16_f32 v77, v78, v79
	v_cvt_pk_bf16_f32 v78, v72, v73
	v_or_b32_e32 v72, 48, v136
	global_store_dwordx4 v[44:45], v[28:31], off offset:256 sc1
	v_cvt_pk_bf16_f32 v111, v106, v107
	v_lshl_add_u64 v[104:105], s[18:19], 0, v[104:105]
	v_add_co_u32_e32 v30, vcc, s67, v146
	v_lshlrev_b64 v[88:89], 11, v[88:89]
	v_ashrrev_i32_e32 v73, 31, v72
	v_lshl_add_u64 v[28:29], v[146:147], 0, s[36:37]
	v_addc_co_u32_e32 v31, vcc, 0, v147, vcc
	v_cvt_pk_bf16_f32 v12, v12, v13
	v_cvt_pk_bf16_f32 v13, v14, v15
	v_cvt_pk_bf16_f32 v14, v8, v9
	v_cvt_pk_bf16_f32 v15, v10, v11
	global_store_dwordx4 v[146:147], v[108:111], off offset:256 sc1
	v_cvt_pk_bf16_f32 v95, v90, v91
	v_lshl_add_u64 v[88:89], s[18:19], 0, v[88:89]
	v_lshl_add_u64 v[108:109], v[104:105], 0, v[144:145]
	v_lshlrev_b64 v[72:73], 11, v[72:73]
	global_store_dwordx4 v[28:29], v[12:15], off offset:256 sc1
	global_store_dwordx4 v[108:109], v[92:95], off offset:256 sc1
	v_cvt_pk_bf16_f32 v79, v74, v75
	v_add_co_u32_e32 v14, vcc, s68, v146
	v_lshl_add_u64 v[92:93], v[88:89], 0, v[144:145]
	v_lshl_add_u64 v[72:73], s[18:19], 0, v[72:73]
	v_addc_co_u32_e32 v15, vcc, 0, v147, vcc
	v_cvt_pk_bf16_f32 v124, v124, v125
	v_cvt_pk_bf16_f32 v125, v126, v127
	v_cvt_pk_bf16_f32 v126, v120, v121
	v_cvt_pk_bf16_f32 v127, v122, v123
	v_cvt_pk_bf16_f32 v104, v116, v117
	v_cvt_pk_bf16_f32 v105, v118, v119
	v_cvt_pk_bf16_f32 v106, v112, v113
	v_cvt_pk_bf16_f32 v107, v114, v115
	v_cvt_pk_bf16_f32 v88, v100, v101
	v_cvt_pk_bf16_f32 v89, v102, v103
	v_cvt_pk_bf16_f32 v90, v96, v97
	v_cvt_pk_bf16_f32 v91, v98, v99
	global_store_dwordx4 v[92:93], v[76:79], off offset:256 sc1
	v_cvt_pk_bf16_f32 v74, v80, v81
	v_cvt_pk_bf16_f32 v75, v82, v83
	v_lshl_add_u64 v[76:77], v[72:73], 0, v[144:145]
	v_cvt_pk_bf16_f32 v72, v84, v85
	v_cvt_pk_bf16_f32 v73, v86, v87
	v_cvt_pk_bf16_f32 v71, v66, v67
	v_cvt_pk_bf16_f32 v63, v58, v59
	v_cvt_pk_bf16_f32 v40, v52, v53
	v_cvt_pk_bf16_f32 v41, v54, v55
	v_cvt_pk_bf16_f32 v42, v48, v49
	v_cvt_pk_bf16_f32 v43, v50, v51
	v_cvt_pk_bf16_f32 v24, v36, v37
	v_cvt_pk_bf16_f32 v25, v38, v39
	v_cvt_pk_bf16_f32 v26, v32, v33
	v_cvt_pk_bf16_f32 v27, v34, v35
	v_lshl_add_u64 v[12:13], v[146:147], 0, s[2:3]
	v_cvt_pk_bf16_f32 v8, v20, v21
	v_cvt_pk_bf16_f32 v9, v22, v23
	v_cvt_pk_bf16_f32 v10, v16, v17
	v_cvt_pk_bf16_f32 v11, v18, v19
	v_cvt_pk_bf16_f32 v4, v4, v5
	v_cvt_pk_bf16_f32 v5, v6, v7
	v_cvt_pk_bf16_f32 v6, v0, v1
	v_cvt_pk_bf16_f32 v7, v2, v3
	s_and_b64 vcc, exec, s[4:5]
	s_mov_b64 s[4:5], -1
	global_store_dwordx4 v[146:147], v[124:127], off sc1
	global_store_dwordx4 v[108:109], v[104:107], off sc1
	global_store_dwordx4 v[92:93], v[88:91], off sc1
	global_store_dwordx4 v[76:77], v[72:75], off sc1
	global_store_dwordx4 v[76:77], v[68:71], off offset:256 sc1
	global_store_dwordx4 v[56:57], v[60:63], off sc1
	global_store_dwordx4 v[46:47], v[40:43], off sc1
	global_store_dwordx4 v[30:31], v[24:27], off sc1
	global_store_dwordx4 v[14:15], v[8:11], off sc1
	global_store_dwordx4 v[12:13], v[4:7], off offset:256 sc1
	s_cbranch_vccnz .LBB0_243
	s_andn2_b64 vcc, exec, s[16:17]
	s_cbranch_vccnz .LBB0_242
	s_barrier
	s_branch .LBB0_242

.LBB0_392:
	s_lshl_b32 s0, s38, 8
	s_and_b32 s0, s0, 0x300
	s_or_b32 s0, s0, s88
	v_or_b32_e32 v223, s0, v222
	s_cmp_gt_i32 s38, 3
	s_mov_b64 s[0:1], -1
	s_cbranch_scc0 .LBB0_414
	s_cmp_gt_u32 s38, 15
	s_cbranch_scc0 .LBB0_411
	s_cmp_gt_u32 s38, 19
	s_cbranch_scc0 .LBB0_408
	s_cmp_gt_u32 s38, 23
	s_cbranch_scc0 .LBB0_405
	v_mul_f32_e32 v128, 0xbfb8aa3b, v124
	v_exp_f32_e32 v128, v128
	s_cmp_gt_u32 s38, 27
	v_add_f32_e32 v128, 1.0, v128
	v_rcp_f32_e32 v188, v128
	s_cbranch_scc0 .LBB0_402
	v_mul_f32_e32 v129, 0xbfb8aa3b, v126
	v_mul_f32_e32 v130, 0xbfb8aa3b, v127
	v_mul_f32_e32 v131, 0xbfb8aa3b, v120
	v_mul_f32_e32 v132, 0xbfb8aa3b, v121
	v_mul_f32_e32 v133, 0xbfb8aa3b, v122
	v_mul_f32_e32 v134, 0xbfb8aa3b, v123
	v_exp_f32_e32 v129, v129
	v_exp_f32_e32 v130, v130
	v_exp_f32_e32 v131, v131
	v_exp_f32_e32 v132, v132
	v_exp_f32_e32 v133, v133
	v_exp_f32_e32 v134, v134
	v_add_f32_e32 v129, 1.0, v129
	v_add_f32_e32 v130, 1.0, v130
	v_add_f32_e32 v131, 1.0, v131
	v_add_f32_e32 v132, 1.0, v132
	v_add_f32_e32 v133, 1.0, v133
	v_add_f32_e32 v134, 1.0, v134
	v_rcp_f32_e32 v129, v129
	v_rcp_f32_e32 v130, v130
	v_rcp_f32_e32 v131, v131
	v_rcp_f32_e32 v132, v132
	v_rcp_f32_e32 v133, v133
	v_rcp_f32_e32 v134, v134
	v_cvt_pk_bf16_f32 v129, v129, v130
	v_cvt_pk_bf16_f32 v130, v131, v132
	v_mul_f32_e32 v132, 0xbfb8aa3b, v112
	v_cvt_pk_bf16_f32 v131, v133, v134
	v_mul_f32_e32 v133, 0xbfb8aa3b, v113
	v_mul_f32_e32 v134, 0xbfb8aa3b, v114
	v_mul_f32_e32 v135, 0xbfb8aa3b, v115
	v_mul_f32_e32 v138, 0xbfb8aa3b, v106
	v_mul_f32_e32 v139, 0xbfb8aa3b, v107
	v_exp_f32_e32 v132, v132
	v_exp_f32_e32 v133, v133
	v_exp_f32_e32 v134, v134
	v_exp_f32_e32 v135, v135
	v_exp_f32_e32 v138, v138
	v_exp_f32_e32 v139, v139
	v_mul_f32_e32 v136, 0xbfb8aa3b, v104
	v_mul_f32_e32 v137, 0xbfb8aa3b, v105
	v_exp_f32_e32 v136, v136
	v_exp_f32_e32 v137, v137
	v_add_f32_e32 v132, 1.0, v132
	v_add_f32_e32 v133, 1.0, v133
	v_add_f32_e32 v134, 1.0, v134
	v_add_f32_e32 v135, 1.0, v135
	v_add_f32_e32 v138, 1.0, v138
	v_add_f32_e32 v139, 1.0, v139
	v_rcp_f32_e32 v132, v132
	v_rcp_f32_e32 v133, v133
	v_rcp_f32_e32 v134, v134
	v_rcp_f32_e32 v135, v135
	v_rcp_f32_e32 v138, v138
	v_rcp_f32_e32 v139, v139
	v_add_f32_e32 v136, 1.0, v136
	v_add_f32_e32 v137, 1.0, v137
	v_rcp_f32_e32 v136, v136
	v_rcp_f32_e32 v137, v137
	v_cvt_pk_bf16_f32 v132, v132, v133
	v_cvt_pk_bf16_f32 v133, v134, v135
	v_cvt_pk_bf16_f32 v135, v138, v139
	v_mul_f32_e32 v138, 0xbfb8aa3b, v96
	v_mul_f32_e32 v139, 0xbfb8aa3b, v97
	v_exp_f32_e32 v138, v138
	v_exp_f32_e32 v139, v139
	v_cvt_pk_bf16_f32 v134, v136, v137
	v_or_b32_e32 v136, 16, v186
	v_ashrrev_i32_e32 v137, 31, v136
	v_lshlrev_b64 v[192:193], 11, v[136:137]
	v_add_f32_e32 v136, 1.0, v138
	v_add_f32_e32 v137, 1.0, v139
	v_mul_f32_e32 v138, 0xbfb8aa3b, v98
	v_mul_f32_e32 v139, 0xbfb8aa3b, v99
	v_mul_f32_e32 v142, 0xbfb8aa3b, v90
	v_mul_f32_e32 v143, 0xbfb8aa3b, v91
	v_exp_f32_e32 v138, v138
	v_exp_f32_e32 v139, v139
	v_exp_f32_e32 v142, v142
	v_exp_f32_e32 v143, v143
	v_mul_f32_e32 v140, 0xbfb8aa3b, v88
	v_mul_f32_e32 v141, 0xbfb8aa3b, v89
	v_exp_f32_e32 v140, v140
	v_exp_f32_e32 v141, v141
	v_add_f32_e32 v138, 1.0, v138
	v_add_f32_e32 v139, 1.0, v139
	v_add_f32_e32 v142, 1.0, v142
	v_add_f32_e32 v143, 1.0, v143
	v_rcp_f32_e32 v136, v136
	v_rcp_f32_e32 v137, v137
	v_rcp_f32_e32 v138, v138
	v_rcp_f32_e32 v139, v139
	v_rcp_f32_e32 v142, v142
	v_rcp_f32_e32 v143, v143
	v_add_f32_e32 v140, 1.0, v140
	v_add_f32_e32 v141, 1.0, v141
	v_rcp_f32_e32 v140, v140
	v_rcp_f32_e32 v141, v141
	v_cvt_pk_bf16_f32 v136, v136, v137
	v_cvt_pk_bf16_f32 v137, v138, v139
	v_cvt_pk_bf16_f32 v139, v142, v143
	v_mul_f32_e32 v142, 0xbfb8aa3b, v80
	v_mul_f32_e32 v143, 0xbfb8aa3b, v81
	v_exp_f32_e32 v142, v142
	v_exp_f32_e32 v143, v143
	v_cvt_pk_bf16_f32 v138, v140, v141
	v_or_b32_e32 v140, 32, v186
	v_ashrrev_i32_e32 v141, 31, v140
	v_lshlrev_b64 v[194:195], 11, v[140:141]
	v_add_f32_e32 v140, 1.0, v142
	v_add_f32_e32 v141, 1.0, v143
	v_mul_f32_e32 v142, 0xbfb8aa3b, v82
	v_mul_f32_e32 v143, 0xbfb8aa3b, v83
	v_mul_f32_e32 v146, 0xbfb8aa3b, v74
	v_mul_f32_e32 v147, 0xbfb8aa3b, v75
	v_exp_f32_e32 v142, v142
	v_exp_f32_e32 v143, v143
	v_exp_f32_e32 v146, v146
	v_exp_f32_e32 v147, v147
	v_mul_f32_e32 v144, 0xbfb8aa3b, v72
	v_mul_f32_e32 v145, 0xbfb8aa3b, v73
	v_exp_f32_e32 v144, v144
	v_exp_f32_e32 v145, v145
	v_add_f32_e32 v142, 1.0, v142
	v_add_f32_e32 v143, 1.0, v143
	v_add_f32_e32 v146, 1.0, v146
	v_add_f32_e32 v147, 1.0, v147
	v_rcp_f32_e32 v140, v140
	v_rcp_f32_e32 v141, v141
	v_rcp_f32_e32 v142, v142
	v_rcp_f32_e32 v143, v143
	v_rcp_f32_e32 v146, v146
	v_rcp_f32_e32 v147, v147
	v_add_f32_e32 v144, 1.0, v144
	v_add_f32_e32 v145, 1.0, v145
	v_rcp_f32_e32 v144, v144
	v_rcp_f32_e32 v145, v145
	v_cvt_pk_bf16_f32 v140, v140, v141
	v_cvt_pk_bf16_f32 v141, v142, v143
	v_cvt_pk_bf16_f32 v143, v146, v147
	v_mul_f32_e32 v146, 0xbfb8aa3b, v60
	v_mul_f32_e32 v147, 0xbfb8aa3b, v61
	v_exp_f32_e32 v146, v146
	v_exp_f32_e32 v147, v147
	v_cvt_pk_bf16_f32 v142, v144, v145
	v_or_b32_e32 v144, 48, v186
	v_ashrrev_i32_e32 v145, 31, v144
	v_lshlrev_b64 v[196:197], 11, v[144:145]
	v_add_f32_e32 v144, 1.0, v146
	v_add_f32_e32 v145, 1.0, v147
	v_mul_f32_e32 v146, 0xbfb8aa3b, v62
	v_mul_f32_e32 v147, 0xbfb8aa3b, v63
	v_mul_f32_e32 v148, 0xbfb8aa3b, v56
	v_mul_f32_e32 v149, 0xbfb8aa3b, v57
	v_mul_f32_e32 v150, 0xbfb8aa3b, v58
	v_mul_f32_e32 v151, 0xbfb8aa3b, v59
	v_exp_f32_e32 v146, v146
	v_exp_f32_e32 v147, v147
	v_exp_f32_e32 v148, v148
	v_exp_f32_e32 v149, v149
	v_exp_f32_e32 v150, v150
	v_exp_f32_e32 v151, v151
	v_add_f32_e32 v146, 1.0, v146
	v_add_f32_e32 v147, 1.0, v147
	v_add_f32_e32 v148, 1.0, v148
	v_add_f32_e32 v149, 1.0, v149
	v_add_f32_e32 v150, 1.0, v150
	v_add_f32_e32 v151, 1.0, v151
	v_rcp_f32_e32 v144, v144
	v_rcp_f32_e32 v145, v145
	v_rcp_f32_e32 v146, v146
	v_rcp_f32_e32 v147, v147
	v_rcp_f32_e32 v148, v148
	v_rcp_f32_e32 v149, v149
	v_rcp_f32_e32 v150, v150
	v_rcp_f32_e32 v151, v151
	v_cvt_pk_bf16_f32 v144, v144, v145
	v_cvt_pk_bf16_f32 v145, v146, v147
	v_cvt_pk_bf16_f32 v146, v148, v149
	v_cvt_pk_bf16_f32 v147, v150, v151
	v_mul_f32_e32 v148, 0xbfb8aa3b, v48
	v_mul_f32_e32 v149, 0xbfb8aa3b, v49
	v_mul_f32_e32 v150, 0xbfb8aa3b, v50
	v_mul_f32_e32 v151, 0xbfb8aa3b, v51
	v_mul_f32_e32 v152, 0xbfb8aa3b, v40
	v_mul_f32_e32 v153, 0xbfb8aa3b, v41
	v_mul_f32_e32 v154, 0xbfb8aa3b, v42
	v_mul_f32_e32 v155, 0xbfb8aa3b, v43
	v_exp_f32_e32 v148, v148
	v_exp_f32_e32 v149, v149
	v_exp_f32_e32 v150, v150
	v_exp_f32_e32 v151, v151
	v_exp_f32_e32 v152, v152
	v_exp_f32_e32 v153, v153
	v_exp_f32_e32 v154, v154
	v_exp_f32_e32 v155, v155
	v_add_f32_e32 v148, 1.0, v148
	v_add_f32_e32 v149, 1.0, v149
	v_add_f32_e32 v150, 1.0, v150
	v_add_f32_e32 v151, 1.0, v151
	v_add_f32_e32 v152, 1.0, v152
	v_add_f32_e32 v153, 1.0, v153
	v_add_f32_e32 v154, 1.0, v154
	v_add_f32_e32 v155, 1.0, v155
	v_rcp_f32_e32 v148, v148
	v_rcp_f32_e32 v149, v149
	v_rcp_f32_e32 v150, v150
	v_rcp_f32_e32 v151, v151
	v_rcp_f32_e32 v152, v152
	v_rcp_f32_e32 v153, v153
	v_rcp_f32_e32 v154, v154
	v_rcp_f32_e32 v155, v155
	v_cvt_pk_bf16_f32 v148, v148, v149
	v_cvt_pk_bf16_f32 v149, v150, v151
	v_cvt_pk_bf16_f32 v150, v152, v153
	v_cvt_pk_bf16_f32 v151, v154, v155
	v_mul_f32_e32 v152, 0xbfb8aa3b, v32
	v_mul_f32_e32 v153, 0xbfb8aa3b, v33
	v_mul_f32_e32 v154, 0xbfb8aa3b, v34
	v_mul_f32_e32 v155, 0xbfb8aa3b, v35
	v_mul_f32_e32 v156, 0xbfb8aa3b, v24
	v_mul_f32_e32 v157, 0xbfb8aa3b, v25
	v_mul_f32_e32 v158, 0xbfb8aa3b, v26
	v_mul_f32_e32 v159, 0xbfb8aa3b, v27
	v_exp_f32_e32 v152, v152
	v_exp_f32_e32 v153, v153
	v_exp_f32_e32 v154, v154
	v_exp_f32_e32 v155, v155
	v_exp_f32_e32 v156, v156
	v_exp_f32_e32 v157, v157
	v_exp_f32_e32 v158, v158
	v_exp_f32_e32 v159, v159
	v_add_f32_e32 v152, 1.0, v152
	v_add_f32_e32 v153, 1.0, v153
	v_add_f32_e32 v154, 1.0, v154
	v_add_f32_e32 v155, 1.0, v155
	v_add_f32_e32 v156, 1.0, v156
	v_add_f32_e32 v157, 1.0, v157
	v_add_f32_e32 v158, 1.0, v158
	v_add_f32_e32 v159, 1.0, v159
	v_rcp_f32_e32 v152, v152
	v_rcp_f32_e32 v153, v153
	v_rcp_f32_e32 v154, v154
	v_rcp_f32_e32 v155, v155
	v_rcp_f32_e32 v156, v156
	v_rcp_f32_e32 v157, v157
	v_rcp_f32_e32 v158, v158
	v_rcp_f32_e32 v159, v159
	v_cvt_pk_bf16_f32 v152, v152, v153
	v_cvt_pk_bf16_f32 v153, v154, v155
	v_cvt_pk_bf16_f32 v154, v156, v157
	v_cvt_pk_bf16_f32 v155, v158, v159
	v_mul_f32_e32 v156, 0xbfb8aa3b, v16
	v_mul_f32_e32 v157, 0xbfb8aa3b, v17
	v_mul_f32_e32 v158, 0xbfb8aa3b, v18
	v_mul_f32_e32 v159, 0xbfb8aa3b, v19
	v_mul_f32_e32 v160, 0xbfb8aa3b, v8
	v_mul_f32_e32 v161, 0xbfb8aa3b, v9
	v_mul_f32_e32 v162, 0xbfb8aa3b, v10
	v_mul_f32_e32 v163, 0xbfb8aa3b, v11
	v_exp_f32_e32 v156, v156
	v_exp_f32_e32 v157, v157
	v_exp_f32_e32 v158, v158
	v_exp_f32_e32 v159, v159
	v_exp_f32_e32 v160, v160
	v_exp_f32_e32 v161, v161
	v_exp_f32_e32 v162, v162
	v_exp_f32_e32 v163, v163
	v_add_f32_e32 v156, 1.0, v156
	v_add_f32_e32 v157, 1.0, v157
	v_add_f32_e32 v158, 1.0, v158
	v_add_f32_e32 v159, 1.0, v159
	v_add_f32_e32 v160, 1.0, v160
	v_add_f32_e32 v161, 1.0, v161
	v_add_f32_e32 v162, 1.0, v162
	v_add_f32_e32 v163, 1.0, v163
	v_rcp_f32_e32 v156, v156
	v_rcp_f32_e32 v157, v157
	v_rcp_f32_e32 v158, v158
	v_rcp_f32_e32 v159, v159
	v_rcp_f32_e32 v160, v160
	v_rcp_f32_e32 v161, v161
	v_rcp_f32_e32 v162, v162
	v_rcp_f32_e32 v163, v163
	v_cvt_pk_bf16_f32 v156, v156, v157
	v_cvt_pk_bf16_f32 v157, v158, v159
	v_cvt_pk_bf16_f32 v158, v160, v161
	v_cvt_pk_bf16_f32 v159, v162, v163
	v_mul_f32_e32 v160, 0xbfb8aa3b, v116
	v_mul_f32_e32 v161, 0xbfb8aa3b, v117
	v_mul_f32_e32 v162, 0xbfb8aa3b, v118
	v_mul_f32_e32 v163, 0xbfb8aa3b, v119
	v_exp_f32_e32 v160, v160
	v_exp_f32_e32 v161, v161
	v_exp_f32_e32 v162, v162
	v_exp_f32_e32 v163, v163
	v_mul_f32_e32 v164, 0xbfb8aa3b, v108
	v_mul_f32_e32 v165, 0xbfb8aa3b, v109
	v_exp_f32_e32 v164, v164
	v_exp_f32_e32 v165, v165
	v_mul_f32_e32 v166, 0xbfb8aa3b, v110
	v_mul_f32_e32 v167, 0xbfb8aa3b, v111
	v_exp_f32_e32 v166, v166
	v_exp_f32_e32 v167, v167
	v_add_f32_e32 v160, 1.0, v160
	v_add_f32_e32 v161, 1.0, v161
	v_add_f32_e32 v162, 1.0, v162
	v_add_f32_e32 v163, 1.0, v163
	v_rcp_f32_e32 v160, v160
	v_rcp_f32_e32 v161, v161
	v_rcp_f32_e32 v162, v162
	v_rcp_f32_e32 v163, v163
	v_add_f32_e32 v164, 1.0, v164
	v_add_f32_e32 v165, 1.0, v165
	v_rcp_f32_e32 v164, v164
	v_rcp_f32_e32 v165, v165
	v_add_f32_e32 v166, 1.0, v166
	v_add_f32_e32 v167, 1.0, v167
	v_rcp_f32_e32 v166, v166
	v_rcp_f32_e32 v167, v167
	v_cvt_pk_bf16_f32 v160, v160, v161
	v_cvt_pk_bf16_f32 v161, v162, v163
	v_mul_f32_e32 v163, 0xbfb8aa3b, v100
	v_ashrrev_i32_e32 v187, 31, v186
	v_cvt_pk_bf16_f32 v162, v164, v165
	v_exp_f32_e32 v164, v163
	v_mul_f32_e32 v163, 0xbfb8aa3b, v101
	v_mul_f32_e32 v128, 0xbfb8aa3b, v125
	v_lshlrev_b64 v[190:191], 11, v[186:187]
	v_exp_f32_e32 v165, v163
	v_cvt_pk_bf16_f32 v163, v166, v167
	v_mul_f32_e32 v166, 0xbfb8aa3b, v102
	v_mul_f32_e32 v167, 0xbfb8aa3b, v103
	v_mul_f32_e32 v172, 0xbfb8aa3b, v92
	v_mul_f32_e32 v187, 0xbfb8aa3b, v93
	v_mul_f32_e32 v189, 0xbfb8aa3b, v94
	v_mul_f32_e32 v206, 0xbfb8aa3b, v95
	v_exp_f32_e32 v128, v128
	v_exp_f32_e32 v166, v166
	v_exp_f32_e32 v167, v167
	v_exp_f32_e32 v172, v172
	v_exp_f32_e32 v187, v187
	v_exp_f32_e32 v189, v189
	v_exp_f32_e32 v206, v206
	v_add_f32_e32 v128, 1.0, v128
	v_add_f32_e32 v164, 1.0, v164
	v_add_f32_e32 v165, 1.0, v165
	v_add_f32_e32 v166, 1.0, v166
	v_add_f32_e32 v167, 1.0, v167
	v_add_f32_e32 v172, 1.0, v172
	v_add_f32_e32 v187, 1.0, v187
	v_add_f32_e32 v189, 1.0, v189
	v_add_f32_e32 v206, 1.0, v206
	v_rcp_f32_e32 v128, v128
	v_rcp_f32_e32 v164, v164
	v_rcp_f32_e32 v165, v165
	v_rcp_f32_e32 v166, v166
	v_rcp_f32_e32 v167, v167
	v_rcp_f32_e32 v172, v172
	v_rcp_f32_e32 v187, v187
	v_rcp_f32_e32 v189, v189
	v_rcp_f32_e32 v206, v206
	s_mov_b64 s[0:1], 0x48000
	v_lshl_add_u64 v[200:201], v[190:191], 0, s[0:1]
	s_mov_b64 s[0:1], 0x50000
	v_lshl_add_u64 v[202:203], v[190:191], 0, s[0:1]
	s_mov_b64 s[0:1], 0x58000
	s_cmp_gt_u32 s38, 31
	v_cvt_pk_bf16_f32 v128, v188, v128
	v_lshl_add_u64 v[198:199], v[190:191], 0, s[4:5]
	v_lshl_add_u64 v[204:205], v[190:191], 0, s[0:1]
	v_cvt_pk_bf16_f32 v164, v164, v165
	v_cvt_pk_bf16_f32 v165, v166, v167
	v_cvt_pk_bf16_f32 v166, v172, v187
	v_cvt_pk_bf16_f32 v167, v189, v206
	s_mov_b64 s[0:1], -1
	s_cbranch_scc0 .LBB0_399
	v_readlane_b32 s0, v250, 2
	v_lshlrev_b32_e32 v172, 1, v223
	v_readlane_b32 s1, v250, 3
	v_mul_f32_e32 v187, 0xbfb8aa3b, v85
	v_mul_f32_e32 v189, 0xbfb8aa3b, v86
	v_lshl_add_u64 v[206:207], s[0:1], 0, v[172:173]
	v_lshl_add_u64 v[224:225], v[206:207], 0, v[190:191]
	v_lshl_add_u64 v[226:227], v[206:207], 0, v[192:193]
	v_lshl_add_u64 v[228:229], v[206:207], 0, v[194:195]
	v_lshl_add_u64 v[230:231], v[206:207], 0, v[196:197]
	v_lshl_add_u64 v[232:233], v[206:207], 0, v[198:199]
	v_lshl_add_u64 v[234:235], v[206:207], 0, v[200:201]
	v_lshl_add_u64 v[208:209], v[206:207], 0, v[202:203]
	v_lshl_add_u64 v[206:207], v[206:207], 0, v[204:205]
	global_store_dwordx4 v[224:225], v[128:131], off sc1
	global_store_dwordx4 v[226:227], v[132:135], off sc1
	global_store_dwordx4 v[228:229], v[136:139], off sc1
	global_store_dwordx4 v[230:231], v[140:143], off sc1
	global_store_dwordx4 v[232:233], v[144:147], off sc1
	global_store_dwordx4 v[234:235], v[148:151], off sc1
	global_store_dwordx4 v[208:209], v[152:155], off sc1
	global_store_dwordx4 v[206:207], v[156:159], off sc1
	global_store_dwordx4 v[224:225], v[160:163], off offset:256 sc1
	v_mul_f32_e32 v224, 0xbfb8aa3b, v87
	v_exp_f32_e32 v224, v224
	v_mul_f32_e32 v225, 0xbfb8aa3b, v76
	global_store_dwordx4 v[226:227], v[164:167], off offset:256 sc1
	v_exp_f32_e32 v225, v225
	v_mul_f32_e32 v226, 0xbfb8aa3b, v77
	v_exp_f32_e32 v226, v226
	v_add_f32_e32 v224, 1.0, v224
	v_rcp_f32_e32 v227, v224
	v_add_f32_e32 v224, 1.0, v225
	v_mul_f32_e32 v225, 0xbfb8aa3b, v78
	v_mul_f32_e32 v172, 0xbfb8aa3b, v84
	v_rcp_f32_e32 v236, v224
	v_add_f32_e32 v224, 1.0, v226
	v_exp_f32_e32 v225, v225
	v_mul_f32_e32 v226, 0xbfb8aa3b, v79
	v_exp_f32_e32 v172, v172
	v_exp_f32_e32 v187, v187
	v_exp_f32_e32 v189, v189
	v_exp_f32_e32 v226, v226
	v_rcp_f32_e32 v237, v224
	v_add_f32_e32 v224, 1.0, v225
	v_add_f32_e32 v172, 1.0, v172
	v_add_f32_e32 v187, 1.0, v187
	v_add_f32_e32 v189, 1.0, v189
	v_rcp_f32_e32 v238, v224
	v_add_f32_e32 v224, 1.0, v226
	v_rcp_f32_e32 v172, v172
	v_rcp_f32_e32 v187, v187
	v_rcp_f32_e32 v189, v189
	v_rcp_f32_e32 v239, v224
	v_cvt_pk_bf16_f32 v226, v236, v237
	v_cvt_pk_bf16_f32 v224, v172, v187
	v_cvt_pk_bf16_f32 v225, v189, v227
	v_cvt_pk_bf16_f32 v227, v238, v239
	global_store_dwordx4 v[228:229], v[224:227], off offset:256 sc1
	v_mul_f32_e32 v172, 0xbfb8aa3b, v68
	v_mul_f32_e32 v187, 0xbfb8aa3b, v69
	v_mul_f32_e32 v224, 0xbfb8aa3b, v71
	v_exp_f32_e32 v224, v224
	v_mul_f32_e32 v225, 0xbfb8aa3b, v64
	v_exp_f32_e32 v225, v225
	v_mul_f32_e32 v226, 0xbfb8aa3b, v65
	v_exp_f32_e32 v226, v226
	v_add_f32_e32 v224, 1.0, v224
	v_rcp_f32_e32 v227, v224
	v_add_f32_e32 v224, 1.0, v225
	v_mul_f32_e32 v225, 0xbfb8aa3b, v66
	v_mul_f32_e32 v189, 0xbfb8aa3b, v70
	v_rcp_f32_e32 v228, v224
	v_add_f32_e32 v224, 1.0, v226
	v_exp_f32_e32 v225, v225
	v_mul_f32_e32 v226, 0xbfb8aa3b, v67
	v_exp_f32_e32 v172, v172
	v_exp_f32_e32 v187, v187
	v_exp_f32_e32 v189, v189
	v_exp_f32_e32 v226, v226
	v_rcp_f32_e32 v229, v224
	v_add_f32_e32 v224, 1.0, v225
	v_add_f32_e32 v172, 1.0, v172
	v_add_f32_e32 v187, 1.0, v187
	v_add_f32_e32 v189, 1.0, v189
	v_rcp_f32_e32 v236, v224
	v_add_f32_e32 v224, 1.0, v226
	v_rcp_f32_e32 v172, v172
	v_rcp_f32_e32 v187, v187
	v_rcp_f32_e32 v189, v189
	v_rcp_f32_e32 v237, v224
	v_cvt_pk_bf16_f32 v226, v228, v229
	v_cvt_pk_bf16_f32 v224, v172, v187
	v_cvt_pk_bf16_f32 v225, v189, v227
	v_cvt_pk_bf16_f32 v227, v236, v237
	global_store_dwordx4 v[230:231], v[224:227], off offset:256 sc1
	v_mul_f32_e32 v172, 0xbfb8aa3b, v52
	v_mul_f32_e32 v187, 0xbfb8aa3b, v53
	v_mul_f32_e32 v224, 0xbfb8aa3b, v55
	v_exp_f32_e32 v224, v224
	v_mul_f32_e32 v225, 0xbfb8aa3b, v44
	v_exp_f32_e32 v225, v225
	v_mul_f32_e32 v226, 0xbfb8aa3b, v45
	v_exp_f32_e32 v226, v226
	v_add_f32_e32 v224, 1.0, v224
	v_rcp_f32_e32 v227, v224
	v_add_f32_e32 v224, 1.0, v225
	v_mul_f32_e32 v225, 0xbfb8aa3b, v46
	v_mul_f32_e32 v189, 0xbfb8aa3b, v54
	v_rcp_f32_e32 v228, v224
	v_add_f32_e32 v224, 1.0, v226
	v_exp_f32_e32 v225, v225
	v_mul_f32_e32 v226, 0xbfb8aa3b, v47
	v_exp_f32_e32 v172, v172
	v_exp_f32_e32 v187, v187
	v_exp_f32_e32 v189, v189
	v_exp_f32_e32 v226, v226
	v_rcp_f32_e32 v229, v224
	v_add_f32_e32 v224, 1.0, v225
	v_add_f32_e32 v172, 1.0, v172
	v_add_f32_e32 v187, 1.0, v187
	v_add_f32_e32 v189, 1.0, v189
	v_rcp_f32_e32 v230, v224
	v_add_f32_e32 v224, 1.0, v226
	v_rcp_f32_e32 v172, v172
	v_rcp_f32_e32 v187, v187
	v_rcp_f32_e32 v189, v189
	v_rcp_f32_e32 v231, v224
	v_cvt_pk_bf16_f32 v226, v228, v229
	v_cvt_pk_bf16_f32 v224, v172, v187
	v_cvt_pk_bf16_f32 v225, v189, v227
	v_cvt_pk_bf16_f32 v227, v230, v231
	global_store_dwordx4 v[232:233], v[224:227], off offset:256 sc1
	v_mul_f32_e32 v172, 0xbfb8aa3b, v36
	v_mul_f32_e32 v187, 0xbfb8aa3b, v37
	v_mul_f32_e32 v224, 0xbfb8aa3b, v39
	v_exp_f32_e32 v224, v224
	v_mul_f32_e32 v225, 0xbfb8aa3b, v28
	v_exp_f32_e32 v225, v225
	v_mul_f32_e32 v226, 0xbfb8aa3b, v29
	v_exp_f32_e32 v226, v226
	v_add_f32_e32 v224, 1.0, v224
	v_rcp_f32_e32 v227, v224
	v_add_f32_e32 v224, 1.0, v225
	v_mul_f32_e32 v225, 0xbfb8aa3b, v30
	v_mul_f32_e32 v189, 0xbfb8aa3b, v38
	v_rcp_f32_e32 v228, v224
	v_add_f32_e32 v224, 1.0, v226
	v_exp_f32_e32 v225, v225
	v_mul_f32_e32 v226, 0xbfb8aa3b, v31
	v_exp_f32_e32 v172, v172
	v_exp_f32_e32 v187, v187
	v_exp_f32_e32 v189, v189
	v_exp_f32_e32 v226, v226
	v_rcp_f32_e32 v229, v224
	v_add_f32_e32 v224, 1.0, v225
	v_add_f32_e32 v172, 1.0, v172
	v_add_f32_e32 v187, 1.0, v187
	v_add_f32_e32 v189, 1.0, v189
	v_rcp_f32_e32 v230, v224
	v_add_f32_e32 v224, 1.0, v226
	v_rcp_f32_e32 v172, v172
	v_rcp_f32_e32 v187, v187
	v_rcp_f32_e32 v189, v189
	v_rcp_f32_e32 v231, v224
	v_cvt_pk_bf16_f32 v226, v228, v229
	v_cvt_pk_bf16_f32 v224, v172, v187
	v_cvt_pk_bf16_f32 v225, v189, v227
	v_cvt_pk_bf16_f32 v227, v230, v231
	global_store_dwordx4 v[234:235], v[224:227], off offset:256 sc1
	v_mul_f32_e32 v172, 0xbfb8aa3b, v20
	v_mul_f32_e32 v187, 0xbfb8aa3b, v21
	v_mul_f32_e32 v224, 0xbfb8aa3b, v23
	v_exp_f32_e32 v224, v224
	v_mul_f32_e32 v225, 0xbfb8aa3b, v12
	v_exp_f32_e32 v225, v225
	v_mul_f32_e32 v226, 0xbfb8aa3b, v13
	v_exp_f32_e32 v226, v226
	v_add_f32_e32 v224, 1.0, v224
	v_rcp_f32_e32 v227, v224
	v_add_f32_e32 v224, 1.0, v225
	v_mul_f32_e32 v225, 0xbfb8aa3b, v14
	v_mul_f32_e32 v189, 0xbfb8aa3b, v22
	v_rcp_f32_e32 v228, v224
	v_add_f32_e32 v224, 1.0, v226
	v_exp_f32_e32 v225, v225
	v_mul_f32_e32 v226, 0xbfb8aa3b, v15
	v_exp_f32_e32 v172, v172
	v_exp_f32_e32 v187, v187
	v_exp_f32_e32 v189, v189
	v_exp_f32_e32 v226, v226
	v_rcp_f32_e32 v229, v224
	v_add_f32_e32 v224, 1.0, v225
	v_add_f32_e32 v172, 1.0, v172
	v_add_f32_e32 v187, 1.0, v187
	v_add_f32_e32 v189, 1.0, v189
	v_rcp_f32_e32 v230, v224
	v_add_f32_e32 v224, 1.0, v226
	v_rcp_f32_e32 v172, v172
	v_rcp_f32_e32 v187, v187
	v_rcp_f32_e32 v189, v189
	v_rcp_f32_e32 v231, v224
	v_cvt_pk_bf16_f32 v226, v228, v229
	v_cvt_pk_bf16_f32 v224, v172, v187
	v_cvt_pk_bf16_f32 v225, v189, v227
	v_cvt_pk_bf16_f32 v227, v230, v231
	global_store_dwordx4 v[208:209], v[224:227], off offset:256 sc1
	v_mul_f32_e32 v172, 0xbfb8aa3b, v4
	v_mul_f32_e32 v187, 0xbfb8aa3b, v5
	v_mul_f32_e32 v224, 0xbfb8aa3b, v1
	v_exp_f32_e32 v224, v224
	v_mul_f32_e32 v225, 0xbfb8aa3b, v2
	v_mul_f32_e32 v189, 0xbfb8aa3b, v6
	v_mul_f32_e32 v208, 0xbfb8aa3b, v7
	v_mul_f32_e32 v209, 0xbfb8aa3b, v0
	v_exp_f32_e32 v225, v225
	v_mul_f32_e32 v226, 0xbfb8aa3b, v3
	v_exp_f32_e32 v172, v172
	v_exp_f32_e32 v187, v187
	v_exp_f32_e32 v189, v189
	v_exp_f32_e32 v208, v208
	v_exp_f32_e32 v209, v209
	v_exp_f32_e32 v226, v226
	v_add_f32_e32 v224, 1.0, v224
	v_rcp_f32_e32 v227, v224
	v_add_f32_e32 v224, 1.0, v225
	v_add_f32_e32 v172, 1.0, v172
	v_add_f32_e32 v187, 1.0, v187
	v_add_f32_e32 v189, 1.0, v189
	v_add_f32_e32 v208, 1.0, v208
	v_add_f32_e32 v209, 1.0, v209
	v_rcp_f32_e32 v228, v224
	v_add_f32_e32 v224, 1.0, v226
	v_rcp_f32_e32 v172, v172
	v_rcp_f32_e32 v187, v187
	v_rcp_f32_e32 v189, v189
	v_rcp_f32_e32 v208, v208
	v_rcp_f32_e32 v209, v209
	v_rcp_f32_e32 v229, v224
	v_cvt_pk_bf16_f32 v224, v172, v187
	v_cvt_pk_bf16_f32 v225, v189, v208
	v_cvt_pk_bf16_f32 v226, v209, v227
	v_cvt_pk_bf16_f32 v227, v228, v229
	global_store_dwordx4 v[206:207], v[224:227], off offset:256 sc1
	s_mov_b64 s[0:1], 0
.LBB0_399:
	s_andn2_b64 vcc, exec, s[0:1]
	s_cbranch_vccnz .LBB0_401
	v_readlane_b32 s0, v250, 0
	v_lshlrev_b32_e32 v172, 1, v223
	v_readlane_b32 s1, v250, 1
	s_nop 1
	v_lshl_add_u64 v[206:207], s[0:1], 0, v[172:173]
	v_lshl_add_u64 v[194:195], v[206:207], 0, v[194:195]
	v_lshl_add_u64 v[192:193], v[206:207], 0, v[192:193]
	global_store_dwordx4 v[194:195], v[136:139], off sc1
	global_store_dwordx4 v[192:193], v[132:135], off sc1
	v_lshl_add_u64 v[190:191], v[206:207], 0, v[190:191]
	v_lshl_add_u64 v[136:137], v[206:207], 0, v[196:197]
	global_store_dwordx4 v[136:137], v[140:143], off sc1
	v_mul_f32_e32 v132, 0xbfb8aa3b, v84
	v_mul_f32_e32 v133, 0xbfb8aa3b, v85
	v_mul_f32_e32 v134, 0xbfb8aa3b, v86
	v_mul_f32_e32 v135, 0xbfb8aa3b, v87
	v_mul_f32_e32 v142, 0xbfb8aa3b, v76
	v_mul_f32_e32 v143, 0xbfb8aa3b, v77
	v_exp_f32_e32 v132, v132
	v_exp_f32_e32 v133, v133
	v_exp_f32_e32 v134, v134
	v_exp_f32_e32 v135, v135
	v_exp_f32_e32 v142, v142
	v_exp_f32_e32 v143, v143
	v_lshl_add_u64 v[138:139], v[206:207], 0, v[198:199]
	global_store_dwordx4 v[138:139], v[144:147], off sc1
	v_add_f32_e32 v132, 1.0, v132
	v_add_f32_e32 v133, 1.0, v133
	v_mul_f32_e32 v144, 0xbfb8aa3b, v78
	v_mul_f32_e32 v145, 0xbfb8aa3b, v79
	v_add_f32_e32 v134, 1.0, v134
	v_add_f32_e32 v135, 1.0, v135
	v_add_f32_e32 v142, 1.0, v142
	v_add_f32_e32 v143, 1.0, v143
	v_exp_f32_e32 v144, v144
	v_exp_f32_e32 v145, v145
	v_rcp_f32_e32 v132, v132
	v_rcp_f32_e32 v133, v133
	v_rcp_f32_e32 v134, v134
	v_rcp_f32_e32 v135, v135
	v_rcp_f32_e32 v142, v142
	v_rcp_f32_e32 v143, v143
	v_add_f32_e32 v144, 1.0, v144
	v_add_f32_e32 v145, 1.0, v145
	v_rcp_f32_e32 v144, v144
	v_rcp_f32_e32 v145, v145
	v_cvt_pk_bf16_f32 v132, v132, v133
	v_cvt_pk_bf16_f32 v133, v134, v135
	v_cvt_pk_bf16_f32 v134, v142, v143
	v_mul_f32_e32 v142, 0xbfb8aa3b, v68
	v_mul_f32_e32 v143, 0xbfb8aa3b, v69
	v_exp_f32_e32 v142, v142
	v_exp_f32_e32 v143, v143
	global_store_dwordx4 v[190:191], v[128:131], off sc1
	v_lshl_add_u64 v[140:141], v[206:207], 0, v[200:201]
	v_cvt_pk_bf16_f32 v135, v144, v145
	v_lshl_add_u64 v[130:131], v[206:207], 0, v[202:203]
	v_lshl_add_u64 v[128:129], v[206:207], 0, v[204:205]
	global_store_dwordx4 v[140:141], v[148:151], off sc1
	global_store_dwordx4 v[130:131], v[152:155], off sc1
	global_store_dwordx4 v[128:129], v[156:159], off sc1
	global_store_dwordx4 v[190:191], v[160:163], off offset:256 sc1
	global_store_dwordx4 v[194:195], v[132:135], off offset:256 sc1
	v_mul_f32_e32 v144, 0xbfb8aa3b, v66
	v_mul_f32_e32 v145, 0xbfb8aa3b, v67
	v_add_f32_e32 v132, 1.0, v142
	v_add_f32_e32 v133, 1.0, v143
	v_mul_f32_e32 v134, 0xbfb8aa3b, v70
	v_mul_f32_e32 v135, 0xbfb8aa3b, v71
	v_mul_f32_e32 v142, 0xbfb8aa3b, v64
	v_mul_f32_e32 v143, 0xbfb8aa3b, v65
	v_exp_f32_e32 v134, v134
	v_exp_f32_e32 v135, v135
	v_exp_f32_e32 v142, v142
	v_exp_f32_e32 v143, v143
	v_exp_f32_e32 v144, v144
	v_exp_f32_e32 v145, v145
	v_add_f32_e32 v134, 1.0, v134
	v_add_f32_e32 v135, 1.0, v135
	v_add_f32_e32 v142, 1.0, v142
	v_add_f32_e32 v143, 1.0, v143
	v_add_f32_e32 v144, 1.0, v144
	v_add_f32_e32 v145, 1.0, v145
	v_rcp_f32_e32 v132, v132
	v_rcp_f32_e32 v133, v133
	v_rcp_f32_e32 v134, v134
	v_rcp_f32_e32 v135, v135
	v_rcp_f32_e32 v142, v142
	v_rcp_f32_e32 v143, v143
	v_rcp_f32_e32 v144, v144
	v_rcp_f32_e32 v145, v145
	v_cvt_pk_bf16_f32 v132, v132, v133
	v_cvt_pk_bf16_f32 v133, v134, v135
	v_cvt_pk_bf16_f32 v134, v142, v143
	v_cvt_pk_bf16_f32 v135, v144, v145
	v_mul_f32_e32 v142, 0xbfb8aa3b, v52
	v_mul_f32_e32 v143, 0xbfb8aa3b, v53
	v_exp_f32_e32 v142, v142
	v_exp_f32_e32 v143, v143
	global_store_dwordx4 v[136:137], v[132:135], off offset:256 sc1
	v_mul_f32_e32 v136, 0xbfb8aa3b, v44
	v_mul_f32_e32 v137, 0xbfb8aa3b, v45
	v_mul_f32_e32 v134, 0xbfb8aa3b, v54
	v_mul_f32_e32 v135, 0xbfb8aa3b, v55
	v_exp_f32_e32 v134, v134
	v_exp_f32_e32 v135, v135
	v_exp_f32_e32 v136, v136
	v_exp_f32_e32 v137, v137
	v_add_f32_e32 v132, 1.0, v142
	v_add_f32_e32 v133, 1.0, v143
	v_mul_f32_e32 v142, 0xbfb8aa3b, v46
	v_mul_f32_e32 v143, 0xbfb8aa3b, v47
	v_add_f32_e32 v134, 1.0, v134
	v_add_f32_e32 v135, 1.0, v135
	v_add_f32_e32 v136, 1.0, v136
	v_add_f32_e32 v137, 1.0, v137
	v_exp_f32_e32 v142, v142
	v_exp_f32_e32 v143, v143
	v_rcp_f32_e32 v132, v132
	v_rcp_f32_e32 v133, v133
	v_rcp_f32_e32 v134, v134
	v_rcp_f32_e32 v135, v135
	v_rcp_f32_e32 v136, v136
	v_rcp_f32_e32 v137, v137
	v_add_f32_e32 v142, 1.0, v142
	v_add_f32_e32 v143, 1.0, v143
	v_rcp_f32_e32 v142, v142
	v_rcp_f32_e32 v143, v143
	v_cvt_pk_bf16_f32 v132, v132, v133
	v_cvt_pk_bf16_f32 v133, v134, v135
	v_cvt_pk_bf16_f32 v134, v136, v137
	v_mul_f32_e32 v136, 0xbfb8aa3b, v36
	v_mul_f32_e32 v137, 0xbfb8aa3b, v37
	v_exp_f32_e32 v136, v136
	v_exp_f32_e32 v137, v137
	v_cvt_pk_bf16_f32 v135, v142, v143
	global_store_dwordx4 v[138:139], v[132:135], off offset:256 sc1
	v_mul_f32_e32 v138, 0xbfb8aa3b, v30
	v_mul_f32_e32 v139, 0xbfb8aa3b, v31
	v_add_f32_e32 v132, 1.0, v136
	v_add_f32_e32 v133, 1.0, v137
	v_mul_f32_e32 v134, 0xbfb8aa3b, v38
	v_mul_f32_e32 v135, 0xbfb8aa3b, v39
	v_mul_f32_e32 v136, 0xbfb8aa3b, v28
	v_mul_f32_e32 v137, 0xbfb8aa3b, v29
	v_exp_f32_e32 v134, v134
	v_exp_f32_e32 v135, v135
	v_exp_f32_e32 v136, v136
	v_exp_f32_e32 v137, v137
	v_add_f32_e32 v134, 1.0, v134
	v_add_f32_e32 v135, 1.0, v135
	v_add_f32_e32 v136, 1.0, v136
	v_add_f32_e32 v137, 1.0, v137
	v_exp_f32_e32 v138, v138
	v_exp_f32_e32 v139, v139
	v_rcp_f32_e32 v132, v132
	v_rcp_f32_e32 v133, v133
	v_rcp_f32_e32 v134, v134
	v_rcp_f32_e32 v135, v135
	v_rcp_f32_e32 v136, v136
	v_rcp_f32_e32 v137, v137
	v_add_f32_e32 v138, 1.0, v138
	v_add_f32_e32 v139, 1.0, v139
	v_rcp_f32_e32 v138, v138
	v_rcp_f32_e32 v139, v139
	v_cvt_pk_bf16_f32 v132, v132, v133
	v_cvt_pk_bf16_f32 v133, v134, v135
	v_cvt_pk_bf16_f32 v134, v136, v137
	v_mul_f32_e32 v136, 0xbfb8aa3b, v20
	v_mul_f32_e32 v137, 0xbfb8aa3b, v21
	v_exp_f32_e32 v136, v136
	v_exp_f32_e32 v137, v137
	v_cvt_pk_bf16_f32 v135, v138, v139
	global_store_dwordx4 v[140:141], v[132:135], off offset:256 sc1
	v_mul_f32_e32 v138, 0xbfb8aa3b, v14
	v_mul_f32_e32 v139, 0xbfb8aa3b, v15
	v_add_f32_e32 v132, 1.0, v136
	v_add_f32_e32 v133, 1.0, v137
	v_mul_f32_e32 v134, 0xbfb8aa3b, v22
	v_mul_f32_e32 v135, 0xbfb8aa3b, v23
	v_mul_f32_e32 v136, 0xbfb8aa3b, v12
	v_mul_f32_e32 v137, 0xbfb8aa3b, v13
	v_exp_f32_e32 v134, v134
	v_exp_f32_e32 v135, v135
	v_exp_f32_e32 v136, v136
	v_exp_f32_e32 v137, v137
	v_add_f32_e32 v134, 1.0, v134
	v_add_f32_e32 v135, 1.0, v135
	v_add_f32_e32 v136, 1.0, v136
	v_add_f32_e32 v137, 1.0, v137
	v_exp_f32_e32 v138, v138
	v_exp_f32_e32 v139, v139
	v_rcp_f32_e32 v132, v132
	v_rcp_f32_e32 v133, v133
	v_rcp_f32_e32 v134, v134
	v_rcp_f32_e32 v135, v135
	v_rcp_f32_e32 v136, v136
	v_rcp_f32_e32 v137, v137
	v_add_f32_e32 v138, 1.0, v138
	v_add_f32_e32 v139, 1.0, v139
	v_rcp_f32_e32 v138, v138
	v_rcp_f32_e32 v139, v139
	v_cvt_pk_bf16_f32 v132, v132, v133
	v_cvt_pk_bf16_f32 v133, v134, v135
	v_cvt_pk_bf16_f32 v134, v136, v137
	v_mul_f32_e32 v136, 0xbfb8aa3b, v4
	v_mul_f32_e32 v137, 0xbfb8aa3b, v5
	v_exp_f32_e32 v136, v136
	v_exp_f32_e32 v137, v137
	v_cvt_pk_bf16_f32 v135, v138, v139
	global_store_dwordx4 v[130:131], v[132:135], off offset:256 sc1
	v_add_f32_e32 v130, 1.0, v136
	v_add_f32_e32 v131, 1.0, v137
	v_mul_f32_e32 v132, 0xbfb8aa3b, v6
	v_mul_f32_e32 v133, 0xbfb8aa3b, v7
	v_mul_f32_e32 v134, 0xbfb8aa3b, v0
	v_mul_f32_e32 v135, 0xbfb8aa3b, v1
	v_mul_f32_e32 v136, 0xbfb8aa3b, v2
	v_mul_f32_e32 v137, 0xbfb8aa3b, v3
	v_exp_f32_e32 v132, v132
	v_exp_f32_e32 v133, v133
	v_exp_f32_e32 v134, v134
	v_exp_f32_e32 v135, v135
	v_exp_f32_e32 v136, v136
	v_exp_f32_e32 v137, v137
	v_add_f32_e32 v132, 1.0, v132
	v_add_f32_e32 v133, 1.0, v133
	v_add_f32_e32 v134, 1.0, v134
	v_add_f32_e32 v135, 1.0, v135
	v_add_f32_e32 v136, 1.0, v136
	v_add_f32_e32 v137, 1.0, v137
	v_rcp_f32_e32 v130, v130
	v_rcp_f32_e32 v131, v131
	v_rcp_f32_e32 v132, v132
	v_rcp_f32_e32 v133, v133
	v_rcp_f32_e32 v134, v134
	v_rcp_f32_e32 v135, v135
	v_rcp_f32_e32 v136, v136
	v_rcp_f32_e32 v137, v137
	v_cvt_pk_bf16_f32 v130, v130, v131
	v_cvt_pk_bf16_f32 v131, v132, v133
	v_cvt_pk_bf16_f32 v132, v134, v135
	v_cvt_pk_bf16_f32 v133, v136, v137
	global_store_dwordx4 v[192:193], v[164:167], off offset:256 sc1
	global_store_dwordx4 v[128:129], v[130:133], off offset:256 sc1

.LBB0_402:
	s_andn2_b64 vcc, exec, s[0:1]
	s_cbranch_vccnz .LBB0_404
	v_mul_f32_e32 v128, 0xbfb8aa3b, v125
	v_exp_f32_e32 v128, v128
	v_mul_f32_e32 v129, 0xbfb8aa3b, v126
	v_mul_f32_e32 v130, 0xbfb8aa3b, v127
	v_exp_f32_e32 v129, v129
	v_exp_f32_e32 v130, v130
	v_add_f32_e32 v128, 1.0, v128
	v_rcp_f32_e32 v189, v128
	v_add_f32_e32 v128, 1.0, v129
	v_add_f32_e32 v129, 1.0, v130
	v_mul_f32_e32 v130, 0xbfb8aa3b, v120
	v_mul_f32_e32 v131, 0xbfb8aa3b, v121
	v_exp_f32_e32 v130, v130
	v_exp_f32_e32 v131, v131
	v_mul_f32_e32 v132, 0xbfb8aa3b, v122
	v_mul_f32_e32 v133, 0xbfb8aa3b, v123
	v_exp_f32_e32 v132, v132
	v_exp_f32_e32 v133, v133
	v_add_f32_e32 v130, 1.0, v130
	v_add_f32_e32 v131, 1.0, v131
	v_rcp_f32_e32 v130, v130
	v_rcp_f32_e32 v131, v131
	v_rcp_f32_e32 v128, v128
	v_rcp_f32_e32 v129, v129
	v_add_f32_e32 v132, 1.0, v132
	v_add_f32_e32 v133, 1.0, v133
	v_rcp_f32_e32 v132, v132
	v_rcp_f32_e32 v133, v133
	v_pk_mul_f32 v[136:137], v[124:125], v[188:189]
	v_pk_mul_f32 v[138:139], v[120:121], v[130:131]
	v_cvt_pk_bf16_f32 v130, v136, v137
	v_mul_f32_e32 v136, 0xbfb8aa3b, v112
	v_mul_f32_e32 v137, 0xbfb8aa3b, v113
	v_readlane_b32 s0, v251, 62
	v_exp_f32_e32 v136, v136
	v_exp_f32_e32 v137, v137
	v_lshlrev_b32_e32 v172, 1, v223
	v_readlane_b32 s1, v251, 63
	v_pk_mul_f32 v[128:129], v[126:127], v[128:129]
	v_ashrrev_i32_e32 v187, 31, v186
	v_lshl_add_u64 v[134:135], s[0:1], 0, v[172:173]
	v_pk_mul_f32 v[140:141], v[122:123], v[132:133]
	v_cvt_pk_bf16_f32 v131, v128, v129
	v_lshlrev_b64 v[128:129], 11, v[186:187]
	v_cvt_pk_bf16_f32 v132, v138, v139
	v_cvt_pk_bf16_f32 v133, v140, v141
	v_lshl_add_u64 v[128:129], v[134:135], 0, v[128:129]
	global_store_dwordx4 v[128:129], v[130:133], off sc1
	v_mul_f32_e32 v138, 0xbfb8aa3b, v106
	v_mul_f32_e32 v139, 0xbfb8aa3b, v107
	v_add_f32_e32 v130, 1.0, v136
	v_add_f32_e32 v131, 1.0, v137
	v_mul_f32_e32 v136, 0xbfb8aa3b, v104
	v_mul_f32_e32 v137, 0xbfb8aa3b, v105
	v_exp_f32_e32 v136, v136
	v_exp_f32_e32 v137, v137
	v_mul_f32_e32 v132, 0xbfb8aa3b, v114
	v_mul_f32_e32 v133, 0xbfb8aa3b, v115
	v_exp_f32_e32 v132, v132
	v_exp_f32_e32 v133, v133
	v_exp_f32_e32 v138, v138
	v_exp_f32_e32 v139, v139
	v_rcp_f32_e32 v130, v130
	v_rcp_f32_e32 v131, v131
	v_add_f32_e32 v136, 1.0, v136
	v_add_f32_e32 v137, 1.0, v137
	v_rcp_f32_e32 v136, v136
	v_rcp_f32_e32 v137, v137
	v_add_f32_e32 v132, 1.0, v132
	v_add_f32_e32 v133, 1.0, v133
	v_add_f32_e32 v138, 1.0, v138
	v_add_f32_e32 v139, 1.0, v139
	v_rcp_f32_e32 v132, v132
	v_rcp_f32_e32 v133, v133
	v_rcp_f32_e32 v138, v138
	v_rcp_f32_e32 v139, v139
	v_pk_mul_f32 v[130:131], v[112:113], v[130:131]
	v_pk_mul_f32 v[140:141], v[104:105], v[136:137]
	v_cvt_pk_bf16_f32 v136, v130, v131
	v_or_b32_e32 v130, 16, v186
	v_ashrrev_i32_e32 v131, 31, v130
	v_pk_mul_f32 v[132:133], v[114:115], v[132:133]
	v_pk_mul_f32 v[142:143], v[106:107], v[138:139]
	v_lshlrev_b64 v[130:131], 11, v[130:131]
	v_cvt_pk_bf16_f32 v137, v132, v133
	v_cvt_pk_bf16_f32 v138, v140, v141
	v_cvt_pk_bf16_f32 v139, v142, v143
	v_lshl_add_u64 v[130:131], v[134:135], 0, v[130:131]
	global_store_dwordx4 v[130:131], v[136:139], off sc1
	v_mul_f32_e32 v140, 0xbfb8aa3b, v90
	v_mul_f32_e32 v141, 0xbfb8aa3b, v91
	v_mul_f32_e32 v138, 0xbfb8aa3b, v88
	v_mul_f32_e32 v139, 0xbfb8aa3b, v89
	v_mul_f32_e32 v132, 0xbfb8aa3b, v96
	v_mul_f32_e32 v133, 0xbfb8aa3b, v97
	v_exp_f32_e32 v138, v138
	v_exp_f32_e32 v139, v139
	v_exp_f32_e32 v140, v140
	v_exp_f32_e32 v141, v141
	v_exp_f32_e32 v132, v132
	v_exp_f32_e32 v133, v133
	v_mul_f32_e32 v136, 0xbfb8aa3b, v98
	v_mul_f32_e32 v137, 0xbfb8aa3b, v99
	v_exp_f32_e32 v136, v136
	v_exp_f32_e32 v137, v137
	v_add_f32_e32 v138, 1.0, v138
	v_add_f32_e32 v139, 1.0, v139
	v_add_f32_e32 v140, 1.0, v140
	v_add_f32_e32 v141, 1.0, v141
	v_add_f32_e32 v132, 1.0, v132
	v_add_f32_e32 v133, 1.0, v133
	v_rcp_f32_e32 v138, v138
	v_rcp_f32_e32 v139, v139
	v_rcp_f32_e32 v140, v140
	v_rcp_f32_e32 v141, v141
	v_rcp_f32_e32 v132, v132
	v_rcp_f32_e32 v133, v133
	v_add_f32_e32 v136, 1.0, v136
	v_add_f32_e32 v137, 1.0, v137
	v_rcp_f32_e32 v136, v136
	v_rcp_f32_e32 v137, v137
	v_pk_mul_f32 v[138:139], v[88:89], v[138:139]
	v_pk_mul_f32 v[140:141], v[90:91], v[140:141]
	v_pk_mul_f32 v[132:133], v[96:97], v[132:133]
	v_cvt_pk_bf16_f32 v138, v138, v139
	v_cvt_pk_bf16_f32 v139, v140, v141
	v_mul_f32_e32 v140, 0xbfb8aa3b, v80
	v_mul_f32_e32 v141, 0xbfb8aa3b, v81
	v_pk_mul_f32 v[142:143], v[98:99], v[136:137]
	v_cvt_pk_bf16_f32 v136, v132, v133
	v_or_b32_e32 v132, 32, v186
	v_exp_f32_e32 v140, v140
	v_exp_f32_e32 v141, v141
	v_ashrrev_i32_e32 v133, 31, v132
	v_lshlrev_b64 v[132:133], 11, v[132:133]
	v_cvt_pk_bf16_f32 v137, v142, v143
	v_lshl_add_u64 v[132:133], v[134:135], 0, v[132:133]
	global_store_dwordx4 v[132:133], v[136:139], off sc1
	v_mul_f32_e32 v142, 0xbfb8aa3b, v74
	v_mul_f32_e32 v143, 0xbfb8aa3b, v75
	v_add_f32_e32 v136, 1.0, v140
	v_add_f32_e32 v137, 1.0, v141
	v_mul_f32_e32 v138, 0xbfb8aa3b, v82
	v_mul_f32_e32 v139, 0xbfb8aa3b, v83
	v_mul_f32_e32 v140, 0xbfb8aa3b, v72
	v_mul_f32_e32 v141, 0xbfb8aa3b, v73
	v_exp_f32_e32 v138, v138
	v_exp_f32_e32 v139, v139
	v_exp_f32_e32 v140, v140
	v_exp_f32_e32 v141, v141
	v_add_f32_e32 v138, 1.0, v138
	v_add_f32_e32 v139, 1.0, v139
	v_add_f32_e32 v140, 1.0, v140
	v_add_f32_e32 v141, 1.0, v141
	v_exp_f32_e32 v142, v142
	v_exp_f32_e32 v143, v143
	v_rcp_f32_e32 v136, v136
	v_rcp_f32_e32 v137, v137
	v_rcp_f32_e32 v138, v138
	v_rcp_f32_e32 v139, v139
	v_rcp_f32_e32 v140, v140
	v_rcp_f32_e32 v141, v141
	v_add_f32_e32 v142, 1.0, v142
	v_add_f32_e32 v143, 1.0, v143
	v_rcp_f32_e32 v142, v142
	v_rcp_f32_e32 v143, v143
	v_pk_mul_f32 v[136:137], v[80:81], v[136:137]
	v_pk_mul_f32 v[138:139], v[82:83], v[138:139]
	v_pk_mul_f32 v[140:141], v[72:73], v[140:141]
	v_cvt_pk_bf16_f32 v136, v136, v137
	v_cvt_pk_bf16_f32 v137, v138, v139
	v_cvt_pk_bf16_f32 v138, v140, v141
	v_or_b32_e32 v140, 48, v186
	v_ashrrev_i32_e32 v141, 31, v140
	v_lshlrev_b64 v[140:141], 11, v[140:141]
	v_pk_mul_f32 v[142:143], v[74:75], v[142:143]
	v_lshl_add_u64 v[134:135], v[134:135], 0, v[140:141]
	v_mul_f32_e32 v140, 0xbfb8aa3b, v60
	v_mul_f32_e32 v141, 0xbfb8aa3b, v61
	v_cvt_pk_bf16_f32 v139, v142, v143
	v_exp_f32_e32 v140, v140
	v_exp_f32_e32 v141, v141
	global_store_dwordx4 v[134:135], v[136:139], off sc1
	v_mul_f32_e32 v142, 0xbfb8aa3b, v58
	v_mul_f32_e32 v143, 0xbfb8aa3b, v59
	v_mul_f32_e32 v138, 0xbfb8aa3b, v62
	v_mul_f32_e32 v139, 0xbfb8aa3b, v63
	v_exp_f32_e32 v138, v138
	v_exp_f32_e32 v139, v139
	v_add_f32_e32 v136, 1.0, v140
	v_add_f32_e32 v137, 1.0, v141
	v_mul_f32_e32 v140, 0xbfb8aa3b, v56
	v_mul_f32_e32 v141, 0xbfb8aa3b, v57
	v_exp_f32_e32 v140, v140
	v_exp_f32_e32 v141, v141
	v_exp_f32_e32 v142, v142
	v_exp_f32_e32 v143, v143
	v_add_f32_e32 v138, 1.0, v138
	v_add_f32_e32 v139, 1.0, v139
	v_rcp_f32_e32 v138, v138
	v_rcp_f32_e32 v139, v139
	v_add_f32_e32 v140, 1.0, v140
	v_add_f32_e32 v141, 1.0, v141
	v_add_f32_e32 v142, 1.0, v142
	v_add_f32_e32 v143, 1.0, v143
	v_rcp_f32_e32 v140, v140
	v_rcp_f32_e32 v141, v141
	v_rcp_f32_e32 v142, v142
	v_rcp_f32_e32 v143, v143
	v_rcp_f32_e32 v136, v136
	v_rcp_f32_e32 v137, v137
	v_pk_mul_f32 v[144:145], v[62:63], v[138:139]
	v_pk_mul_f32 v[140:141], v[56:57], v[140:141]
	v_cvt_pk_bf16_f32 v139, v144, v145
	v_mul_f32_e32 v144, 0xbfb8aa3b, v48
	v_mul_f32_e32 v145, 0xbfb8aa3b, v49
	v_exp_f32_e32 v144, v144
	v_exp_f32_e32 v145, v145
	v_pk_mul_f32 v[142:143], v[58:59], v[142:143]
	v_pk_mul_f32 v[136:137], v[60:61], v[136:137]
	v_cvt_pk_bf16_f32 v140, v140, v141
	v_cvt_pk_bf16_f32 v141, v142, v143
	v_add_co_u32_e32 v142, vcc, s93, v128
	v_cvt_pk_bf16_f32 v138, v136, v137
	s_nop 0
	v_addc_co_u32_e32 v143, vcc, 0, v129, vcc
	global_store_dwordx4 v[142:143], v[138:141], off sc1
	v_mul_f32_e32 v142, 0xbfb8aa3b, v40
	v_mul_f32_e32 v143, 0xbfb8aa3b, v41
	v_add_f32_e32 v138, 1.0, v144
	v_add_f32_e32 v139, 1.0, v145
	v_mul_f32_e32 v140, 0xbfb8aa3b, v50
	v_mul_f32_e32 v141, 0xbfb8aa3b, v51
	v_mul_f32_e32 v144, 0xbfb8aa3b, v42
	v_mul_f32_e32 v145, 0xbfb8aa3b, v43
	v_exp_f32_e32 v140, v140
	v_exp_f32_e32 v141, v141
	v_exp_f32_e32 v142, v142
	v_exp_f32_e32 v143, v143
	v_exp_f32_e32 v144, v144
	v_exp_f32_e32 v145, v145
	v_add_f32_e32 v140, 1.0, v140
	v_add_f32_e32 v141, 1.0, v141
	v_add_f32_e32 v142, 1.0, v142
	v_add_f32_e32 v143, 1.0, v143
	v_add_f32_e32 v144, 1.0, v144
	v_add_f32_e32 v145, 1.0, v145
	v_rcp_f32_e32 v140, v140
	v_rcp_f32_e32 v141, v141
	v_rcp_f32_e32 v142, v142
	v_rcp_f32_e32 v143, v143
	v_rcp_f32_e32 v144, v144
	v_rcp_f32_e32 v145, v145
	v_rcp_f32_e32 v138, v138
	v_rcp_f32_e32 v139, v139
	v_pk_mul_f32 v[146:147], v[50:51], v[140:141]
	v_pk_mul_f32 v[142:143], v[40:41], v[142:143]
	v_pk_mul_f32 v[144:145], v[42:43], v[144:145]
	v_pk_mul_f32 v[138:139], v[48:49], v[138:139]
	v_cvt_pk_bf16_f32 v141, v146, v147
	v_cvt_pk_bf16_f32 v142, v142, v143
	v_cvt_pk_bf16_f32 v143, v144, v145
	v_add_co_u32_e32 v144, vcc, s96, v128
	v_mul_f32_e32 v146, 0xbfb8aa3b, v32
	v_mul_f32_e32 v147, 0xbfb8aa3b, v33
	v_cvt_pk_bf16_f32 v140, v138, v139
	v_addc_co_u32_e32 v145, vcc, 0, v129, vcc
	v_exp_f32_e32 v146, v146
	v_exp_f32_e32 v147, v147
	global_store_dwordx4 v[144:145], v[140:143], off sc1
	v_mul_f32_e32 v144, 0xbfb8aa3b, v24
	v_mul_f32_e32 v145, 0xbfb8aa3b, v25
	v_mul_f32_e32 v142, 0xbfb8aa3b, v34
	v_mul_f32_e32 v143, 0xbfb8aa3b, v35
	v_exp_f32_e32 v142, v142
	v_exp_f32_e32 v143, v143
	v_add_f32_e32 v140, 1.0, v146
	v_add_f32_e32 v141, 1.0, v147
	v_mul_f32_e32 v146, 0xbfb8aa3b, v26
	v_mul_f32_e32 v147, 0xbfb8aa3b, v27
	v_exp_f32_e32 v144, v144
	v_exp_f32_e32 v145, v145
	v_exp_f32_e32 v146, v146
	v_exp_f32_e32 v147, v147
	v_add_f32_e32 v142, 1.0, v142
	v_add_f32_e32 v143, 1.0, v143
	v_rcp_f32_e32 v142, v142
	v_rcp_f32_e32 v143, v143
	v_rcp_f32_e32 v140, v140
	v_rcp_f32_e32 v141, v141
	v_add_f32_e32 v144, 1.0, v144
	v_add_f32_e32 v145, 1.0, v145
	v_add_f32_e32 v146, 1.0, v146
	v_add_f32_e32 v147, 1.0, v147
	v_rcp_f32_e32 v144, v144
	v_rcp_f32_e32 v145, v145
	v_rcp_f32_e32 v146, v146
	v_rcp_f32_e32 v147, v147
	v_pk_mul_f32 v[148:149], v[34:35], v[142:143]
	s_mov_b64 s[0:1], 0x48000
	v_cvt_pk_bf16_f32 v143, v148, v149
	v_mul_f32_e32 v148, 0xbfb8aa3b, v16
	v_mul_f32_e32 v149, 0xbfb8aa3b, v17
	v_lshl_add_u64 v[138:139], v[128:129], 0, s[0:1]
	v_pk_mul_f32 v[140:141], v[32:33], v[140:141]
	s_mov_b64 s[0:1], 0x50000
	v_exp_f32_e32 v148, v148
	v_exp_f32_e32 v149, v149
	v_pk_mul_f32 v[144:145], v[24:25], v[144:145]
	v_pk_mul_f32 v[146:147], v[26:27], v[146:147]
	v_cvt_pk_bf16_f32 v142, v140, v141
	v_lshl_add_u64 v[140:141], v[128:129], 0, s[0:1]
	s_mov_b32 s0, 0x50000
	v_cvt_pk_bf16_f32 v144, v144, v145
	v_cvt_pk_bf16_f32 v145, v146, v147
	v_add_co_u32_e32 v146, vcc, s0, v128
	s_mov_b64 s[0:1], 0x58000
	s_nop 0
	v_addc_co_u32_e32 v147, vcc, 0, v129, vcc
	global_store_dwordx4 v[146:147], v[142:145], off sc1
	v_mul_f32_e32 v146, 0xbfb8aa3b, v8
	v_mul_f32_e32 v147, 0xbfb8aa3b, v9
	v_add_f32_e32 v142, 1.0, v148
	v_add_f32_e32 v143, 1.0, v149
	v_mul_f32_e32 v144, 0xbfb8aa3b, v18
	v_mul_f32_e32 v145, 0xbfb8aa3b, v19
	v_mul_f32_e32 v148, 0xbfb8aa3b, v10
	v_mul_f32_e32 v149, 0xbfb8aa3b, v11
	v_exp_f32_e32 v144, v144
	v_exp_f32_e32 v145, v145
	v_exp_f32_e32 v146, v146
	v_exp_f32_e32 v147, v147
	v_exp_f32_e32 v148, v148
	v_exp_f32_e32 v149, v149
	v_rcp_f32_e32 v142, v142
	v_rcp_f32_e32 v143, v143
	v_add_f32_e32 v144, 1.0, v144
	v_add_f32_e32 v145, 1.0, v145
	v_add_f32_e32 v146, 1.0, v146
	v_add_f32_e32 v147, 1.0, v147
	v_add_f32_e32 v148, 1.0, v148
	v_add_f32_e32 v149, 1.0, v149
	v_rcp_f32_e32 v144, v144
	v_rcp_f32_e32 v145, v145
	v_rcp_f32_e32 v146, v146
	v_rcp_f32_e32 v147, v147
	v_rcp_f32_e32 v148, v148
	v_rcp_f32_e32 v149, v149
	v_pk_mul_f32 v[142:143], v[16:17], v[142:143]
	v_pk_mul_f32 v[150:151], v[18:19], v[144:145]
	v_pk_mul_f32 v[146:147], v[8:9], v[146:147]
	v_pk_mul_f32 v[148:149], v[10:11], v[148:149]
	v_cvt_pk_bf16_f32 v144, v142, v143
	v_lshl_add_u64 v[142:143], v[128:129], 0, s[0:1]
	s_mov_b32 s0, 0x58000
	v_cvt_pk_bf16_f32 v146, v146, v147
	v_cvt_pk_bf16_f32 v147, v148, v149
	v_add_co_u32_e32 v148, vcc, s0, v128
	v_cvt_pk_bf16_f32 v145, v150, v151
	s_nop 0
	v_addc_co_u32_e32 v149, vcc, 0, v129, vcc
	v_mul_f32_e32 v150, 0xbfb8aa3b, v116
	v_mul_f32_e32 v151, 0xbfb8aa3b, v117
	v_exp_f32_e32 v150, v150
	v_exp_f32_e32 v151, v151
	global_store_dwordx4 v[148:149], v[144:147], off sc1
	v_mul_f32_e32 v148, 0xbfb8aa3b, v108
	v_mul_f32_e32 v149, 0xbfb8aa3b, v109
	v_mul_f32_e32 v146, 0xbfb8aa3b, v118
	v_mul_f32_e32 v147, 0xbfb8aa3b, v119
	v_exp_f32_e32 v146, v146
	v_exp_f32_e32 v147, v147
	v_exp_f32_e32 v148, v148
	v_exp_f32_e32 v149, v149
	v_add_f32_e32 v144, 1.0, v150
	v_add_f32_e32 v145, 1.0, v151
	v_mul_f32_e32 v150, 0xbfb8aa3b, v110
	v_mul_f32_e32 v151, 0xbfb8aa3b, v111
	v_add_f32_e32 v146, 1.0, v146
	v_add_f32_e32 v147, 1.0, v147
	v_add_f32_e32 v148, 1.0, v148
	v_add_f32_e32 v149, 1.0, v149
	v_exp_f32_e32 v150, v150
	v_exp_f32_e32 v151, v151
	v_rcp_f32_e32 v144, v144
	v_rcp_f32_e32 v145, v145
	v_rcp_f32_e32 v146, v146
	v_rcp_f32_e32 v147, v147
	v_rcp_f32_e32 v148, v148
	v_rcp_f32_e32 v149, v149
	v_add_f32_e32 v150, 1.0, v150
	v_add_f32_e32 v151, 1.0, v151
	v_rcp_f32_e32 v150, v150
	v_rcp_f32_e32 v151, v151
	v_pk_mul_f32 v[144:145], v[116:117], v[144:145]
	v_pk_mul_f32 v[146:147], v[118:119], v[146:147]
	v_pk_mul_f32 v[148:149], v[108:109], v[148:149]
	v_cvt_pk_bf16_f32 v144, v144, v145
	v_cvt_pk_bf16_f32 v145, v146, v147
	v_cvt_pk_bf16_f32 v146, v148, v149
	v_mul_f32_e32 v148, 0xbfb8aa3b, v100
	v_mul_f32_e32 v149, 0xbfb8aa3b, v101
	v_exp_f32_e32 v148, v148
	v_exp_f32_e32 v149, v149
	v_pk_mul_f32 v[150:151], v[110:111], v[150:151]
	v_lshl_add_u64 v[136:137], v[128:129], 0, s[4:5]
	v_cvt_pk_bf16_f32 v147, v150, v151
	global_store_dwordx4 v[128:129], v[144:147], off offset:256 sc1
	v_add_f32_e32 v128, 1.0, v148
	v_add_f32_e32 v129, 1.0, v149
	v_mul_f32_e32 v144, 0xbfb8aa3b, v102
	v_mul_f32_e32 v145, 0xbfb8aa3b, v103
	v_mul_f32_e32 v146, 0xbfb8aa3b, v92
	v_mul_f32_e32 v147, 0xbfb8aa3b, v93
	v_mul_f32_e32 v148, 0xbfb8aa3b, v94
	v_mul_f32_e32 v149, 0xbfb8aa3b, v95
	v_exp_f32_e32 v144, v144
	v_exp_f32_e32 v145, v145
	v_exp_f32_e32 v146, v146
	v_exp_f32_e32 v147, v147
	v_exp_f32_e32 v148, v148
	v_exp_f32_e32 v149, v149
	v_add_f32_e32 v144, 1.0, v144
	v_add_f32_e32 v145, 1.0, v145
	v_add_f32_e32 v146, 1.0, v146
	v_add_f32_e32 v147, 1.0, v147
	v_add_f32_e32 v148, 1.0, v148
	v_add_f32_e32 v149, 1.0, v149
	v_rcp_f32_e32 v128, v128
	v_rcp_f32_e32 v129, v129
	v_rcp_f32_e32 v144, v144
	v_rcp_f32_e32 v145, v145
	v_rcp_f32_e32 v146, v146
	v_rcp_f32_e32 v147, v147
	v_rcp_f32_e32 v148, v148
	v_rcp_f32_e32 v149, v149
	v_pk_mul_f32 v[128:129], v[100:101], v[128:129]
	v_pk_mul_f32 v[150:151], v[102:103], v[144:145]
	v_pk_mul_f32 v[146:147], v[92:93], v[146:147]
	v_pk_mul_f32 v[148:149], v[94:95], v[148:149]
	v_cvt_pk_bf16_f32 v144, v128, v129
	v_cvt_pk_bf16_f32 v145, v150, v151
	v_cvt_pk_bf16_f32 v146, v146, v147
	v_cvt_pk_bf16_f32 v147, v148, v149
	v_mul_f32_e32 v128, 0xbfb8aa3b, v84
	v_mul_f32_e32 v129, 0xbfb8aa3b, v85
	global_store_dwordx4 v[130:131], v[144:147], off offset:256 sc1
	v_mul_f32_e32 v130, 0xbfb8aa3b, v86
	v_mul_f32_e32 v131, 0xbfb8aa3b, v87
	v_mul_f32_e32 v144, 0xbfb8aa3b, v76
	v_mul_f32_e32 v145, 0xbfb8aa3b, v77
	v_mul_f32_e32 v146, 0xbfb8aa3b, v78
	v_mul_f32_e32 v147, 0xbfb8aa3b, v79
	v_exp_f32_e32 v128, v128
	v_exp_f32_e32 v129, v129
	v_exp_f32_e32 v130, v130
	v_exp_f32_e32 v131, v131
	v_exp_f32_e32 v144, v144
	v_exp_f32_e32 v145, v145
	v_exp_f32_e32 v146, v146
	v_exp_f32_e32 v147, v147
	v_add_f32_e32 v128, 1.0, v128
	v_add_f32_e32 v129, 1.0, v129
	v_add_f32_e32 v130, 1.0, v130
	v_add_f32_e32 v131, 1.0, v131
	v_add_f32_e32 v144, 1.0, v144
	v_add_f32_e32 v145, 1.0, v145
	v_add_f32_e32 v146, 1.0, v146
	v_add_f32_e32 v147, 1.0, v147
	v_rcp_f32_e32 v128, v128
	v_rcp_f32_e32 v129, v129
	v_rcp_f32_e32 v130, v130
	v_rcp_f32_e32 v131, v131
	v_rcp_f32_e32 v144, v144
	v_rcp_f32_e32 v145, v145
	v_rcp_f32_e32 v146, v146
	v_rcp_f32_e32 v147, v147
	v_pk_mul_f32 v[128:129], v[84:85], v[128:129]
	v_pk_mul_f32 v[130:131], v[86:87], v[130:131]
	v_pk_mul_f32 v[144:145], v[76:77], v[144:145]
	v_pk_mul_f32 v[146:147], v[78:79], v[146:147]
	v_cvt_pk_bf16_f32 v128, v128, v129
	v_cvt_pk_bf16_f32 v129, v130, v131
	v_cvt_pk_bf16_f32 v130, v144, v145
	v_cvt_pk_bf16_f32 v131, v146, v147
	v_mul_f32_e32 v144, 0xbfb8aa3b, v68
	v_mul_f32_e32 v145, 0xbfb8aa3b, v69
	v_exp_f32_e32 v144, v144
	v_exp_f32_e32 v145, v145
	global_store_dwordx4 v[132:133], v[128:131], off offset:256 sc1
	v_mul_f32_e32 v132, 0xbfb8aa3b, v64
	v_mul_f32_e32 v133, 0xbfb8aa3b, v65
	v_mul_f32_e32 v130, 0xbfb8aa3b, v70
	v_mul_f32_e32 v131, 0xbfb8aa3b, v71
	v_exp_f32_e32 v130, v130
	v_exp_f32_e32 v131, v131
	v_exp_f32_e32 v132, v132
	v_exp_f32_e32 v133, v133
	v_add_f32_e32 v128, 1.0, v144
	v_add_f32_e32 v129, 1.0, v145
	v_mul_f32_e32 v144, 0xbfb8aa3b, v66
	v_mul_f32_e32 v145, 0xbfb8aa3b, v67
	v_add_f32_e32 v130, 1.0, v130
	v_add_f32_e32 v131, 1.0, v131
	v_add_f32_e32 v132, 1.0, v132
	v_add_f32_e32 v133, 1.0, v133
	v_exp_f32_e32 v144, v144
	v_exp_f32_e32 v145, v145
	v_rcp_f32_e32 v128, v128
	v_rcp_f32_e32 v129, v129
	v_rcp_f32_e32 v130, v130
	v_rcp_f32_e32 v131, v131
	v_rcp_f32_e32 v132, v132
	v_rcp_f32_e32 v133, v133
	v_add_f32_e32 v144, 1.0, v144
	v_add_f32_e32 v145, 1.0, v145
	v_rcp_f32_e32 v144, v144
	v_rcp_f32_e32 v145, v145
	v_pk_mul_f32 v[128:129], v[68:69], v[128:129]
	v_pk_mul_f32 v[130:131], v[70:71], v[130:131]
	v_pk_mul_f32 v[132:133], v[64:65], v[132:133]
	v_cvt_pk_bf16_f32 v128, v128, v129
	v_cvt_pk_bf16_f32 v129, v130, v131
	v_cvt_pk_bf16_f32 v130, v132, v133
	v_mul_f32_e32 v132, 0xbfb8aa3b, v52
	v_mul_f32_e32 v133, 0xbfb8aa3b, v53
	v_exp_f32_e32 v132, v132
	v_exp_f32_e32 v133, v133
	v_pk_mul_f32 v[144:145], v[66:67], v[144:145]
	s_nop 0
	v_cvt_pk_bf16_f32 v131, v144, v145
	global_store_dwordx4 v[134:135], v[128:131], off offset:256 sc1
	v_mul_f32_e32 v134, 0xbfb8aa3b, v46
	v_mul_f32_e32 v135, 0xbfb8aa3b, v47
	v_add_f32_e32 v128, 1.0, v132
	v_add_f32_e32 v129, 1.0, v133
	v_mul_f32_e32 v130, 0xbfb8aa3b, v54
	v_mul_f32_e32 v131, 0xbfb8aa3b, v55
	v_mul_f32_e32 v132, 0xbfb8aa3b, v44
	v_mul_f32_e32 v133, 0xbfb8aa3b, v45
	v_exp_f32_e32 v130, v130
	v_exp_f32_e32 v131, v131
	v_exp_f32_e32 v132, v132
	v_exp_f32_e32 v133, v133
	v_add_f32_e32 v130, 1.0, v130
	v_add_f32_e32 v131, 1.0, v131
	v_add_f32_e32 v132, 1.0, v132
	v_add_f32_e32 v133, 1.0, v133
	v_exp_f32_e32 v134, v134
	v_exp_f32_e32 v135, v135
	v_rcp_f32_e32 v128, v128
	v_rcp_f32_e32 v129, v129
	v_rcp_f32_e32 v130, v130
	v_rcp_f32_e32 v131, v131
	v_rcp_f32_e32 v132, v132
	v_rcp_f32_e32 v133, v133
	v_add_f32_e32 v134, 1.0, v134
	v_add_f32_e32 v135, 1.0, v135
	v_rcp_f32_e32 v134, v134
	v_rcp_f32_e32 v135, v135
	v_pk_mul_f32 v[128:129], v[52:53], v[128:129]
	v_pk_mul_f32 v[130:131], v[54:55], v[130:131]
	v_pk_mul_f32 v[132:133], v[44:45], v[132:133]
	v_cvt_pk_bf16_f32 v128, v128, v129
	v_cvt_pk_bf16_f32 v129, v130, v131
	v_cvt_pk_bf16_f32 v130, v132, v133
	v_mul_f32_e32 v132, 0xbfb8aa3b, v36
	v_mul_f32_e32 v133, 0xbfb8aa3b, v37
	v_exp_f32_e32 v132, v132
	v_exp_f32_e32 v133, v133
	v_pk_mul_f32 v[134:135], v[46:47], v[134:135]
	s_nop 0
	v_cvt_pk_bf16_f32 v131, v134, v135
	global_store_dwordx4 v[136:137], v[128:131], off offset:256 sc1
	v_mul_f32_e32 v134, 0xbfb8aa3b, v30
	v_mul_f32_e32 v135, 0xbfb8aa3b, v31
	v_add_f32_e32 v128, 1.0, v132
	v_add_f32_e32 v129, 1.0, v133
	v_mul_f32_e32 v130, 0xbfb8aa3b, v38
	v_mul_f32_e32 v131, 0xbfb8aa3b, v39
	v_mul_f32_e32 v132, 0xbfb8aa3b, v28
	v_mul_f32_e32 v133, 0xbfb8aa3b, v29
	v_exp_f32_e32 v130, v130
	v_exp_f32_e32 v131, v131
	v_exp_f32_e32 v132, v132
	v_exp_f32_e32 v133, v133
	v_add_f32_e32 v130, 1.0, v130
	v_add_f32_e32 v131, 1.0, v131
	v_add_f32_e32 v132, 1.0, v132
	v_add_f32_e32 v133, 1.0, v133
	v_exp_f32_e32 v134, v134
	v_exp_f32_e32 v135, v135
	v_rcp_f32_e32 v128, v128
	v_rcp_f32_e32 v129, v129
	v_rcp_f32_e32 v130, v130
	v_rcp_f32_e32 v131, v131
	v_rcp_f32_e32 v132, v132
	v_rcp_f32_e32 v133, v133
	v_add_f32_e32 v134, 1.0, v134
	v_add_f32_e32 v135, 1.0, v135
	v_rcp_f32_e32 v134, v134
	v_rcp_f32_e32 v135, v135
	v_pk_mul_f32 v[128:129], v[36:37], v[128:129]
	v_pk_mul_f32 v[130:131], v[38:39], v[130:131]
	v_pk_mul_f32 v[132:133], v[28:29], v[132:133]
	v_cvt_pk_bf16_f32 v128, v128, v129
	v_cvt_pk_bf16_f32 v129, v130, v131
	v_cvt_pk_bf16_f32 v130, v132, v133
	v_mul_f32_e32 v132, 0xbfb8aa3b, v20
	v_mul_f32_e32 v133, 0xbfb8aa3b, v21
	v_exp_f32_e32 v132, v132
	v_exp_f32_e32 v133, v133
	v_pk_mul_f32 v[134:135], v[30:31], v[134:135]
	s_nop 0
	v_cvt_pk_bf16_f32 v131, v134, v135
	global_store_dwordx4 v[138:139], v[128:131], off offset:256 sc1
	v_mul_f32_e32 v134, 0xbfb8aa3b, v14
	v_mul_f32_e32 v135, 0xbfb8aa3b, v15
	v_add_f32_e32 v128, 1.0, v132
	v_add_f32_e32 v129, 1.0, v133
	v_mul_f32_e32 v130, 0xbfb8aa3b, v22
	v_mul_f32_e32 v131, 0xbfb8aa3b, v23
	v_mul_f32_e32 v132, 0xbfb8aa3b, v12
	v_mul_f32_e32 v133, 0xbfb8aa3b, v13
	v_exp_f32_e32 v130, v130
	v_exp_f32_e32 v131, v131
	v_exp_f32_e32 v132, v132
	v_exp_f32_e32 v133, v133
	v_add_f32_e32 v130, 1.0, v130
	v_add_f32_e32 v131, 1.0, v131
	v_add_f32_e32 v132, 1.0, v132
	v_add_f32_e32 v133, 1.0, v133
	v_exp_f32_e32 v134, v134
	v_exp_f32_e32 v135, v135
	v_rcp_f32_e32 v128, v128
	v_rcp_f32_e32 v129, v129
	v_rcp_f32_e32 v130, v130
	v_rcp_f32_e32 v131, v131
	v_rcp_f32_e32 v132, v132
	v_rcp_f32_e32 v133, v133
	v_add_f32_e32 v134, 1.0, v134
	v_add_f32_e32 v135, 1.0, v135
	v_rcp_f32_e32 v134, v134
	v_rcp_f32_e32 v135, v135
	v_pk_mul_f32 v[128:129], v[20:21], v[128:129]
	v_pk_mul_f32 v[130:131], v[22:23], v[130:131]
	v_pk_mul_f32 v[132:133], v[12:13], v[132:133]
	v_cvt_pk_bf16_f32 v128, v128, v129
	v_cvt_pk_bf16_f32 v129, v130, v131
	v_cvt_pk_bf16_f32 v130, v132, v133
	v_mul_f32_e32 v132, 0xbfb8aa3b, v4
	v_mul_f32_e32 v133, 0xbfb8aa3b, v5
	v_exp_f32_e32 v132, v132
	v_exp_f32_e32 v133, v133
	v_pk_mul_f32 v[134:135], v[14:15], v[134:135]
	s_nop 0
	v_cvt_pk_bf16_f32 v131, v134, v135
	global_store_dwordx4 v[140:141], v[128:131], off offset:256 sc1
	v_mul_f32_e32 v134, 0xbfb8aa3b, v2
	v_mul_f32_e32 v135, 0xbfb8aa3b, v3
	v_add_f32_e32 v128, 1.0, v132
	v_add_f32_e32 v129, 1.0, v133
	v_mul_f32_e32 v130, 0xbfb8aa3b, v6
	v_mul_f32_e32 v131, 0xbfb8aa3b, v7
	v_mul_f32_e32 v132, 0xbfb8aa3b, v0
	v_mul_f32_e32 v133, 0xbfb8aa3b, v1
	v_exp_f32_e32 v130, v130
	v_exp_f32_e32 v131, v131
	v_exp_f32_e32 v132, v132
	v_exp_f32_e32 v133, v133
	v_exp_f32_e32 v134, v134
	v_exp_f32_e32 v135, v135
	v_add_f32_e32 v130, 1.0, v130
	v_add_f32_e32 v131, 1.0, v131
	v_add_f32_e32 v132, 1.0, v132
	v_add_f32_e32 v133, 1.0, v133
	v_add_f32_e32 v134, 1.0, v134
	v_add_f32_e32 v135, 1.0, v135
	v_rcp_f32_e32 v128, v128
	v_rcp_f32_e32 v129, v129
	v_rcp_f32_e32 v130, v130
	v_rcp_f32_e32 v131, v131
	v_rcp_f32_e32 v132, v132
	v_rcp_f32_e32 v133, v133
	v_rcp_f32_e32 v134, v134
	v_rcp_f32_e32 v135, v135
	v_pk_mul_f32 v[128:129], v[4:5], v[128:129]
	v_pk_mul_f32 v[130:131], v[6:7], v[130:131]
	v_pk_mul_f32 v[132:133], v[0:1], v[132:133]
	v_pk_mul_f32 v[134:135], v[2:3], v[134:135]
	v_cvt_pk_bf16_f32 v128, v128, v129
	v_cvt_pk_bf16_f32 v129, v130, v131
	v_cvt_pk_bf16_f32 v130, v132, v133
	v_cvt_pk_bf16_f32 v131, v134, v135
	global_store_dwordx4 v[142:143], v[128:131], off offset:256 sc1

.LBB0_405:
	s_andn2_b64 vcc, exec, s[0:1]
	s_cbranch_vccnz .LBB0_407
	v_readlane_b32 s0, v251, 60
	v_lshlrev_b32_e32 v172, 1, v223
	v_readlane_b32 s1, v251, 61
	v_ashrrev_i32_e32 v187, 31, v186
	v_or_b32_e32 v136, 16, v186
	v_lshl_add_u64 v[132:133], s[0:1], 0, v[172:173]
	v_lshlrev_b64 v[134:135], 11, v[186:187]
	v_ashrrev_i32_e32 v137, 31, v136
	v_or_b32_e32 v138, 32, v186
	v_cvt_pk_bf16_f32 v128, v124, v125
	v_cvt_pk_bf16_f32 v129, v126, v127
	v_cvt_pk_bf16_f32 v130, v120, v121
	v_cvt_pk_bf16_f32 v131, v122, v123
	v_lshl_add_u64 v[134:135], v[132:133], 0, v[134:135]
	v_lshlrev_b64 v[136:137], 11, v[136:137]
	v_ashrrev_i32_e32 v139, 31, v138
	v_or_b32_e32 v140, 48, v186
	global_store_dwordx4 v[134:135], v[128:131], off sc1
	v_lshl_add_u64 v[136:137], v[132:133], 0, v[136:137]
	v_lshlrev_b64 v[138:139], 11, v[138:139]
	v_cvt_pk_bf16_f32 v128, v112, v113
	v_cvt_pk_bf16_f32 v129, v114, v115
	v_cvt_pk_bf16_f32 v130, v104, v105
	v_cvt_pk_bf16_f32 v131, v106, v107
	v_ashrrev_i32_e32 v141, 31, v140
	global_store_dwordx4 v[136:137], v[128:131], off sc1
	v_lshl_add_u64 v[138:139], v[132:133], 0, v[138:139]
	v_lshlrev_b64 v[140:141], 11, v[140:141]
	v_cvt_pk_bf16_f32 v128, v96, v97
	v_cvt_pk_bf16_f32 v129, v98, v99
	v_cvt_pk_bf16_f32 v130, v88, v89
	v_cvt_pk_bf16_f32 v131, v90, v91
	v_add_co_u32_e32 v142, vcc, s93, v134
	global_store_dwordx4 v[138:139], v[128:131], off sc1
	v_lshl_add_u64 v[132:133], v[132:133], 0, v[140:141]
	v_addc_co_u32_e32 v143, vcc, 0, v135, vcc
	v_cvt_pk_bf16_f32 v128, v80, v81
	v_cvt_pk_bf16_f32 v129, v82, v83
	v_cvt_pk_bf16_f32 v130, v72, v73
	v_cvt_pk_bf16_f32 v131, v74, v75
	global_store_dwordx4 v[132:133], v[128:131], off sc1
	s_mov_b64 s[0:1], 0x48000
	v_add_co_u32_e32 v144, vcc, s96, v134
	v_cvt_pk_bf16_f32 v128, v60, v61
	v_cvt_pk_bf16_f32 v129, v62, v63
	v_cvt_pk_bf16_f32 v130, v56, v57
	v_cvt_pk_bf16_f32 v131, v58, v59
	global_store_dwordx4 v[142:143], v[128:131], off sc1
	v_lshl_add_u64 v[142:143], v[134:135], 0, s[0:1]
	v_addc_co_u32_e32 v145, vcc, 0, v135, vcc
	v_cvt_pk_bf16_f32 v128, v48, v49
	v_cvt_pk_bf16_f32 v129, v50, v51
	v_cvt_pk_bf16_f32 v130, v40, v41
	v_cvt_pk_bf16_f32 v131, v42, v43
	s_mov_b64 s[0:1], 0x50000
	global_store_dwordx4 v[144:145], v[128:131], off sc1
	v_lshl_add_u64 v[144:145], v[134:135], 0, s[0:1]
	s_mov_b32 s0, 0x50000
	v_add_co_u32_e32 v146, vcc, s0, v134
	v_cvt_pk_bf16_f32 v128, v32, v33
	v_cvt_pk_bf16_f32 v129, v34, v35
	v_cvt_pk_bf16_f32 v130, v24, v25
	v_cvt_pk_bf16_f32 v131, v26, v27
	v_addc_co_u32_e32 v147, vcc, 0, v135, vcc
	s_mov_b64 s[0:1], 0x58000
	global_store_dwordx4 v[146:147], v[128:131], off sc1
	v_lshl_add_u64 v[146:147], v[134:135], 0, s[0:1]
	s_mov_b32 s0, 0x58000
	v_add_co_u32_e32 v148, vcc, s0, v134
	v_cvt_pk_bf16_f32 v128, v16, v17
	v_cvt_pk_bf16_f32 v129, v18, v19
	v_cvt_pk_bf16_f32 v130, v8, v9
	v_cvt_pk_bf16_f32 v131, v10, v11
	v_addc_co_u32_e32 v149, vcc, 0, v135, vcc
	global_store_dwordx4 v[148:149], v[128:131], off sc1
	v_lshl_add_u64 v[140:141], v[134:135], 0, s[4:5]
	s_nop 0
	v_cvt_pk_bf16_f32 v128, v116, v117
	v_cvt_pk_bf16_f32 v129, v118, v119
	v_cvt_pk_bf16_f32 v130, v108, v109
	v_cvt_pk_bf16_f32 v131, v110, v111
	global_store_dwordx4 v[134:135], v[128:131], off offset:256 sc1
	s_nop 1
	v_cvt_pk_bf16_f32 v128, v100, v101
	v_cvt_pk_bf16_f32 v129, v102, v103
	v_cvt_pk_bf16_f32 v130, v92, v93
	v_cvt_pk_bf16_f32 v131, v94, v95
	global_store_dwordx4 v[136:137], v[128:131], off offset:256 sc1
	s_nop 1
	v_cvt_pk_bf16_f32 v128, v84, v85
	v_cvt_pk_bf16_f32 v129, v86, v87
	v_cvt_pk_bf16_f32 v130, v76, v77
	v_cvt_pk_bf16_f32 v131, v78, v79
	global_store_dwordx4 v[138:139], v[128:131], off offset:256 sc1
	s_nop 1
	v_cvt_pk_bf16_f32 v128, v68, v69
	v_cvt_pk_bf16_f32 v129, v70, v71
	v_cvt_pk_bf16_f32 v130, v64, v65
	v_cvt_pk_bf16_f32 v131, v66, v67
	global_store_dwordx4 v[132:133], v[128:131], off offset:256 sc1
	s_nop 1
	v_cvt_pk_bf16_f32 v128, v52, v53
	v_cvt_pk_bf16_f32 v129, v54, v55
	v_cvt_pk_bf16_f32 v130, v44, v45
	v_cvt_pk_bf16_f32 v131, v46, v47
	global_store_dwordx4 v[140:141], v[128:131], off offset:256 sc1
	s_nop 1
	v_cvt_pk_bf16_f32 v128, v36, v37
	v_cvt_pk_bf16_f32 v129, v38, v39
	v_cvt_pk_bf16_f32 v130, v28, v29
	v_cvt_pk_bf16_f32 v131, v30, v31
	global_store_dwordx4 v[142:143], v[128:131], off offset:256 sc1
	s_nop 1
	v_cvt_pk_bf16_f32 v128, v20, v21
	v_cvt_pk_bf16_f32 v129, v22, v23
	v_cvt_pk_bf16_f32 v130, v12, v13
	v_cvt_pk_bf16_f32 v131, v14, v15
	global_store_dwordx4 v[144:145], v[128:131], off offset:256 sc1
	s_nop 1
	v_cvt_pk_bf16_f32 v128, v4, v5
	v_cvt_pk_bf16_f32 v129, v6, v7
	v_cvt_pk_bf16_f32 v130, v0, v1
	v_cvt_pk_bf16_f32 v131, v2, v3
	global_store_dwordx4 v[146:147], v[128:131], off offset:256 sc1

.LBB0_408:
	s_andn2_b64 vcc, exec, s[0:1]
	s_cbranch_vccnz .LBB0_410
	v_readlane_b32 s42, v250, 4
	v_lshlrev_b32_e32 v132, 2, v223
	v_readlane_b32 s43, v250, 5
	s_nop 4
	global_load_dwordx4 v[128:131], v132, s[42:43] offset:16
	s_nop 0
	global_load_dwordx4 v[132:135], v132, s[42:43]
	v_mul_f32_e32 v138, 0xbfb8aa3b, v124
	v_exp_f32_e32 v138, v138
	s_mov_b32 s2, 0x7f800000
	v_readlane_b32 s8, v251, 58
	v_lshlrev_b32_e32 v172, 1, v223
	v_add_f32_e32 v138, 1.0, v138
	v_rcp_f32_e32 v138, v138
	v_readlane_b32 s9, v251, 59
	v_ashrrev_i32_e32 v187, 31, v186
	s_waitcnt vmcnt(0)
	v_sub_f32_e32 v156, 1.0, v128
	v_sub_f32_e32 v150, 1.0, v132
	v_fma_f32 v138, v138, v150, v132
	v_cmp_gt_f32_e32 vcc, s33, v138
	v_sub_f32_e32 v151, 1.0, v133
	v_sub_f32_e32 v154, 1.0, v134
	v_cndmask_b32_e64 v139, 0, 32, vcc
	v_ldexp_f32 v138, v138, v139
	v_log_f32_e32 v138, v138
	v_sub_f32_e32 v155, 1.0, v135
	v_sub_f32_e32 v157, 1.0, v129
	v_sub_f32_e32 v159, 1.0, v130
	v_mul_f32_e32 v139, 0x3f317217, v138
	v_fma_f32 v139, v138, s97, -v139
	v_fmac_f32_e32 v139, 0x3377d1cf, v138
	v_fmac_f32_e32 v139, 0x3f317217, v138
	v_cmp_lt_f32_e64 s[0:1], |v138|, s2
	v_sub_f32_e32 v158, 1.0, v131
	v_lshl_add_u64 v[136:137], s[8:9], 0, v[172:173]
	v_cndmask_b32_e64 v138, v138, v139, s[0:1]
	v_cndmask_b32_e32 v139, 0, v213, vcc
	v_sub_f32_e32 v138, v138, v139
	v_mul_f32_e32 v139, 0xbfb8aa3b, v125
	v_exp_f32_e32 v139, v139
	s_nop 0
	v_add_f32_e32 v139, 1.0, v139
	v_rcp_f32_e32 v139, v139
	s_nop 0
	v_fma_f32 v139, v139, v151, v133
	v_cmp_gt_f32_e32 vcc, s33, v139
	s_nop 1
	v_cndmask_b32_e64 v140, 0, 32, vcc
	v_ldexp_f32 v139, v139, v140
	v_log_f32_e32 v139, v139
	s_nop 0
	v_mul_f32_e32 v140, 0x3f317217, v139
	v_fma_f32 v140, v139, s97, -v140
	v_fmac_f32_e32 v140, 0x3377d1cf, v139
	v_fmac_f32_e32 v140, 0x3f317217, v139
	v_cmp_lt_f32_e64 s[0:1], |v139|, s2
	s_nop 1
	v_cndmask_b32_e64 v139, v139, v140, s[0:1]
	v_cndmask_b32_e32 v140, 0, v213, vcc
	v_sub_f32_e32 v139, v139, v140
	v_mul_f32_e32 v140, 0xbfb8aa3b, v126
	v_exp_f32_e32 v140, v140
	s_nop 0
	v_add_f32_e32 v140, 1.0, v140
	v_rcp_f32_e32 v140, v140
	s_nop 0
	v_fma_f32 v140, v140, v154, v134
	v_cmp_gt_f32_e32 vcc, s33, v140
	s_nop 1
	v_cndmask_b32_e64 v141, 0, 32, vcc
	v_ldexp_f32 v140, v140, v141
	v_log_f32_e32 v140, v140
	s_nop 0
	v_mul_f32_e32 v141, 0x3f317217, v140
	v_fma_f32 v141, v140, s97, -v141
	v_fmac_f32_e32 v141, 0x3377d1cf, v140
	v_fmac_f32_e32 v141, 0x3f317217, v140
	v_cmp_lt_f32_e64 s[0:1], |v140|, s2
	s_nop 1
	v_cndmask_b32_e64 v140, v140, v141, s[0:1]
	v_cndmask_b32_e32 v141, 0, v213, vcc
	v_sub_f32_e32 v140, v140, v141
	v_mul_f32_e32 v141, 0xbfb8aa3b, v127
	v_exp_f32_e32 v141, v141
	s_nop 0
	v_add_f32_e32 v141, 1.0, v141
	v_rcp_f32_e32 v141, v141
	s_nop 0
	v_fma_f32 v141, v141, v155, v135
	v_cmp_gt_f32_e32 vcc, s33, v141
	s_nop 1
	v_cndmask_b32_e64 v142, 0, 32, vcc
	v_ldexp_f32 v141, v141, v142
	v_log_f32_e32 v141, v141
	s_nop 0
	v_mul_f32_e32 v142, 0x3f317217, v141
	v_fma_f32 v142, v141, s97, -v142
	v_fmac_f32_e32 v142, 0x3377d1cf, v141
	v_fmac_f32_e32 v142, 0x3f317217, v141
	v_cmp_lt_f32_e64 s[0:1], |v141|, s2
	s_nop 1
	v_cndmask_b32_e64 v141, v141, v142, s[0:1]
	v_cndmask_b32_e32 v142, 0, v213, vcc
	v_sub_f32_e32 v141, v141, v142
	v_mul_f32_e32 v142, 0xbfb8aa3b, v120
	v_exp_f32_e32 v142, v142
	s_nop 0
	v_add_f32_e32 v142, 1.0, v142
	v_rcp_f32_e32 v142, v142
	s_nop 0
	v_fma_f32 v142, v142, v156, v128
	v_cmp_gt_f32_e32 vcc, s33, v142
	s_nop 1
	v_cndmask_b32_e64 v143, 0, 32, vcc
	v_ldexp_f32 v142, v142, v143
	v_log_f32_e32 v142, v142
	s_nop 0
	v_mul_f32_e32 v143, 0x3f317217, v142
	v_fma_f32 v143, v142, s97, -v143
	v_fmac_f32_e32 v143, 0x3377d1cf, v142
	v_fmac_f32_e32 v143, 0x3f317217, v142
	v_cmp_lt_f32_e64 s[0:1], |v142|, s2
	s_nop 1
	v_cndmask_b32_e64 v142, v142, v143, s[0:1]
	v_cndmask_b32_e32 v143, 0, v213, vcc
	v_sub_f32_e32 v142, v142, v143
	v_mul_f32_e32 v143, 0xbfb8aa3b, v121
	v_exp_f32_e32 v143, v143
	s_nop 0
	v_add_f32_e32 v143, 1.0, v143
	v_rcp_f32_e32 v143, v143
	s_nop 0
	v_fma_f32 v143, v143, v157, v129
	v_cmp_gt_f32_e32 vcc, s33, v143
	s_nop 1
	v_cndmask_b32_e64 v144, 0, 32, vcc
	v_ldexp_f32 v143, v143, v144
	v_log_f32_e32 v143, v143
	s_nop 0
	v_mul_f32_e32 v144, 0x3f317217, v143
	v_fma_f32 v144, v143, s97, -v144
	v_fmac_f32_e32 v144, 0x3377d1cf, v143
	v_fmac_f32_e32 v144, 0x3f317217, v143
	v_cmp_lt_f32_e64 s[0:1], |v143|, s2
	s_nop 1
	v_cndmask_b32_e64 v143, v143, v144, s[0:1]
	v_cndmask_b32_e32 v144, 0, v213, vcc
	v_sub_f32_e32 v143, v143, v144
	v_mul_f32_e32 v144, 0xbfb8aa3b, v122
	v_exp_f32_e32 v144, v144
	v_cvt_pk_bf16_f32 v146, v142, v143
	v_add_f32_e32 v144, 1.0, v144
	v_rcp_f32_e32 v144, v144
	s_nop 0
	v_fma_f32 v144, v144, v159, v130
	v_cmp_gt_f32_e32 vcc, s33, v144
	s_nop 1
	v_cndmask_b32_e64 v145, 0, 32, vcc
	v_ldexp_f32 v144, v144, v145
	v_log_f32_e32 v144, v144
	s_nop 0
	v_mul_f32_e32 v145, 0x3f317217, v144
	v_fma_f32 v145, v144, s97, -v145
	v_fmac_f32_e32 v145, 0x3377d1cf, v144
	v_fmac_f32_e32 v145, 0x3f317217, v144
	v_cmp_lt_f32_e64 s[0:1], |v144|, s2
	s_nop 1
	v_cndmask_b32_e64 v144, v144, v145, s[0:1]
	v_cndmask_b32_e32 v145, 0, v213, vcc
	v_sub_f32_e32 v147, v144, v145
	v_mul_f32_e32 v144, 0xbfb8aa3b, v123
	v_exp_f32_e32 v144, v144
	s_nop 0
	v_add_f32_e32 v144, 1.0, v144
	v_rcp_f32_e32 v144, v144
	s_nop 0
	v_fma_f32 v144, v144, v158, v131
	v_cmp_gt_f32_e32 vcc, s33, v144
	s_nop 1
	v_cndmask_b32_e64 v145, 0, 32, vcc
	v_ldexp_f32 v144, v144, v145
	v_log_f32_e32 v144, v144
	s_nop 0
	v_mul_f32_e32 v145, 0x3f317217, v144
	v_fma_f32 v145, v144, s97, -v145
	v_fmac_f32_e32 v145, 0x3377d1cf, v144
	v_fmac_f32_e32 v145, 0x3f317217, v144
	v_cmp_lt_f32_e64 s[0:1], |v144|, s2
	s_nop 1
	v_cndmask_b32_e64 v144, v144, v145, s[0:1]
	v_cndmask_b32_e32 v145, 0, v213, vcc
	v_sub_f32_e32 v148, v144, v145
	v_cvt_pk_bf16_f32 v144, v138, v139
	v_lshlrev_b64 v[138:139], 11, v[186:187]
	v_cvt_pk_bf16_f32 v145, v140, v141
	v_cvt_pk_bf16_f32 v147, v147, v148
	v_lshl_add_u64 v[140:141], v[136:137], 0, v[138:139]
	global_store_dwordx4 v[140:141], v[144:147], off sc1
	v_mul_f32_e32 v140, 0xbfb8aa3b, v112
	v_exp_f32_e32 v140, v140
	s_nop 0
	v_add_f32_e32 v140, 1.0, v140
	v_rcp_f32_e32 v140, v140
	s_nop 0
	v_fma_f32 v140, v140, v150, v132
	v_cmp_gt_f32_e32 vcc, s33, v140
	s_nop 1
	v_cndmask_b32_e64 v141, 0, 32, vcc
	v_ldexp_f32 v140, v140, v141
	v_log_f32_e32 v140, v140
	s_nop 0
	v_mul_f32_e32 v141, 0x3f317217, v140
	v_fma_f32 v141, v140, s97, -v141
	v_fmac_f32_e32 v141, 0x3377d1cf, v140
	v_fmac_f32_e32 v141, 0x3f317217, v140
	v_cmp_lt_f32_e64 s[0:1], |v140|, s2
	s_nop 1
	v_cndmask_b32_e64 v140, v140, v141, s[0:1]
	v_cndmask_b32_e32 v141, 0, v213, vcc
	v_sub_f32_e32 v140, v140, v141
	v_mul_f32_e32 v141, 0xbfb8aa3b, v113
	v_exp_f32_e32 v141, v141
	s_nop 0
	v_add_f32_e32 v141, 1.0, v141
	v_rcp_f32_e32 v141, v141
	s_nop 0
	v_fma_f32 v141, v141, v151, v133
	v_cmp_gt_f32_e32 vcc, s33, v141
	s_nop 1
	v_cndmask_b32_e64 v142, 0, 32, vcc
	v_ldexp_f32 v141, v141, v142
	v_log_f32_e32 v141, v141
	s_nop 0
	v_mul_f32_e32 v142, 0x3f317217, v141
	v_fma_f32 v142, v141, s97, -v142
	v_fmac_f32_e32 v142, 0x3377d1cf, v141
	v_fmac_f32_e32 v142, 0x3f317217, v141
	v_cmp_lt_f32_e64 s[0:1], |v141|, s2
	s_nop 1
	v_cndmask_b32_e64 v141, v141, v142, s[0:1]
	v_cndmask_b32_e32 v142, 0, v213, vcc
	v_sub_f32_e32 v141, v141, v142
	v_mul_f32_e32 v142, 0xbfb8aa3b, v114
	v_exp_f32_e32 v142, v142
	s_nop 0
	v_add_f32_e32 v142, 1.0, v142
	v_rcp_f32_e32 v142, v142
	s_nop 0
	v_fma_f32 v142, v142, v154, v134
	v_cmp_gt_f32_e32 vcc, s33, v142
	s_nop 1
	v_cndmask_b32_e64 v143, 0, 32, vcc
	v_ldexp_f32 v142, v142, v143
	v_log_f32_e32 v142, v142
	s_nop 0
	v_mul_f32_e32 v143, 0x3f317217, v142
	v_fma_f32 v143, v142, s97, -v143
	v_fmac_f32_e32 v143, 0x3377d1cf, v142
	v_fmac_f32_e32 v143, 0x3f317217, v142
	v_cmp_lt_f32_e64 s[0:1], |v142|, s2
	s_nop 1
	v_cndmask_b32_e64 v142, v142, v143, s[0:1]
	v_cndmask_b32_e32 v143, 0, v213, vcc
	v_sub_f32_e32 v143, v142, v143
	v_mul_f32_e32 v142, 0xbfb8aa3b, v115
	v_exp_f32_e32 v142, v142
	s_nop 0
	v_add_f32_e32 v142, 1.0, v142
	v_rcp_f32_e32 v142, v142
	s_nop 0
	v_fma_f32 v142, v142, v155, v135
	v_cmp_gt_f32_e32 vcc, s33, v142
	s_nop 1
	v_cndmask_b32_e64 v144, 0, 32, vcc
	v_ldexp_f32 v142, v142, v144
	v_log_f32_e32 v142, v142
	s_nop 0
	v_mul_f32_e32 v144, 0x3f317217, v142
	v_fma_f32 v144, v142, s97, -v144
	v_fmac_f32_e32 v144, 0x3377d1cf, v142
	v_fmac_f32_e32 v144, 0x3f317217, v142
	v_cmp_lt_f32_e64 s[0:1], |v142|, s2
	s_nop 1
	v_cndmask_b32_e64 v142, v142, v144, s[0:1]
	v_cndmask_b32_e32 v144, 0, v213, vcc
	v_sub_f32_e32 v144, v142, v144
	v_mul_f32_e32 v142, 0xbfb8aa3b, v104
	v_exp_f32_e32 v142, v142
	v_cvt_pk_bf16_f32 v143, v143, v144
	v_add_f32_e32 v142, 1.0, v142
	v_rcp_f32_e32 v142, v142
	s_nop 0
	v_fma_f32 v142, v142, v156, v128
	v_cmp_gt_f32_e32 vcc, s33, v142
	s_nop 1
	v_cndmask_b32_e64 v145, 0, 32, vcc
	v_ldexp_f32 v142, v142, v145
	v_log_f32_e32 v142, v142
	s_nop 0
	v_mul_f32_e32 v145, 0x3f317217, v142
	v_fma_f32 v145, v142, s97, -v145
	v_fmac_f32_e32 v145, 0x3377d1cf, v142
	v_fmac_f32_e32 v145, 0x3f317217, v142
	v_cmp_lt_f32_e64 s[0:1], |v142|, s2
	s_nop 1
	v_cndmask_b32_e64 v142, v142, v145, s[0:1]
	v_cndmask_b32_e32 v145, 0, v213, vcc
	v_sub_f32_e32 v145, v142, v145
	v_mul_f32_e32 v142, 0xbfb8aa3b, v105
	v_exp_f32_e32 v142, v142
	s_nop 0
	v_add_f32_e32 v142, 1.0, v142
	v_rcp_f32_e32 v142, v142
	s_nop 0
	v_fma_f32 v142, v142, v157, v129
	v_cmp_gt_f32_e32 vcc, s33, v142
	s_nop 1
	v_cndmask_b32_e64 v146, 0, 32, vcc
	v_ldexp_f32 v142, v142, v146
	v_log_f32_e32 v142, v142
	s_nop 0
	v_mul_f32_e32 v146, 0x3f317217, v142
	v_fma_f32 v146, v142, s97, -v146
	v_fmac_f32_e32 v146, 0x3377d1cf, v142
	v_fmac_f32_e32 v146, 0x3f317217, v142
	v_cmp_lt_f32_e64 s[0:1], |v142|, s2
	s_nop 1
	v_cndmask_b32_e64 v142, v142, v146, s[0:1]
	v_cndmask_b32_e32 v146, 0, v213, vcc
	v_sub_f32_e32 v146, v142, v146
	v_mul_f32_e32 v142, 0xbfb8aa3b, v106
	v_exp_f32_e32 v142, v142
	v_cvt_pk_bf16_f32 v144, v145, v146
	v_add_f32_e32 v142, 1.0, v142
	v_rcp_f32_e32 v142, v142
	s_nop 0
	v_fma_f32 v142, v142, v159, v130
	v_cmp_gt_f32_e32 vcc, s33, v142
	s_nop 1
	v_cndmask_b32_e64 v147, 0, 32, vcc
	v_ldexp_f32 v142, v142, v147
	v_log_f32_e32 v142, v142
	s_nop 0
	v_mul_f32_e32 v147, 0x3f317217, v142
	v_fma_f32 v147, v142, s97, -v147
	v_fmac_f32_e32 v147, 0x3377d1cf, v142
	v_fmac_f32_e32 v147, 0x3f317217, v142
	v_cmp_lt_f32_e64 s[0:1], |v142|, s2
	s_nop 1
	v_cndmask_b32_e64 v142, v142, v147, s[0:1]
	v_cndmask_b32_e32 v147, 0, v213, vcc
	v_sub_f32_e32 v147, v142, v147
	v_mul_f32_e32 v142, 0xbfb8aa3b, v107
	v_exp_f32_e32 v142, v142
	s_nop 0
	v_add_f32_e32 v142, 1.0, v142
	v_rcp_f32_e32 v142, v142
	s_nop 0
	v_fma_f32 v142, v142, v158, v131
	v_cmp_gt_f32_e32 vcc, s33, v142
	s_nop 1
	v_cndmask_b32_e64 v148, 0, 32, vcc
	v_ldexp_f32 v142, v142, v148
	v_log_f32_e32 v142, v142
	s_nop 0
	v_mul_f32_e32 v148, 0x3f317217, v142
	v_fma_f32 v148, v142, s97, -v148
	v_fmac_f32_e32 v148, 0x3377d1cf, v142
	v_fmac_f32_e32 v148, 0x3f317217, v142
	v_cmp_lt_f32_e64 s[0:1], |v142|, s2
	s_nop 1
	v_cndmask_b32_e64 v142, v142, v148, s[0:1]
	v_cndmask_b32_e32 v148, 0, v213, vcc
	v_sub_f32_e32 v148, v142, v148
	v_cvt_pk_bf16_f32 v142, v140, v141
	v_or_b32_e32 v140, 16, v186
	v_ashrrev_i32_e32 v141, 31, v140
	v_lshlrev_b64 v[140:141], 11, v[140:141]
	v_cvt_pk_bf16_f32 v145, v147, v148
	v_lshl_add_u64 v[146:147], v[136:137], 0, v[140:141]
	global_store_dwordx4 v[146:147], v[142:145], off sc1
	s_nop 1
	v_mul_f32_e32 v142, 0xbfb8aa3b, v96
	v_exp_f32_e32 v142, v142
	s_nop 0
	v_add_f32_e32 v142, 1.0, v142
	v_rcp_f32_e32 v142, v142
	s_nop 0
	v_fma_f32 v142, v142, v150, v132
	v_cmp_gt_f32_e32 vcc, s33, v142
	s_nop 1
	v_cndmask_b32_e64 v143, 0, 32, vcc
	v_ldexp_f32 v142, v142, v143
	v_log_f32_e32 v142, v142
	s_nop 0
	v_mul_f32_e32 v143, 0x3f317217, v142
	v_fma_f32 v143, v142, s97, -v143
	v_fmac_f32_e32 v143, 0x3377d1cf, v142
	v_fmac_f32_e32 v143, 0x3f317217, v142
	v_cmp_lt_f32_e64 s[0:1], |v142|, s2
	s_nop 1
	v_cndmask_b32_e64 v142, v142, v143, s[0:1]
	v_cndmask_b32_e32 v143, 0, v213, vcc
	v_sub_f32_e32 v142, v142, v143
	v_mul_f32_e32 v143, 0xbfb8aa3b, v97
	v_exp_f32_e32 v143, v143
	s_nop 0
	v_add_f32_e32 v143, 1.0, v143
	v_rcp_f32_e32 v143, v143
	s_nop 0
	v_fma_f32 v143, v143, v151, v133
	v_cmp_gt_f32_e32 vcc, s33, v143
	s_nop 1
	v_cndmask_b32_e64 v144, 0, 32, vcc
	v_ldexp_f32 v143, v143, v144
	v_log_f32_e32 v143, v143
	s_nop 0
	v_mul_f32_e32 v144, 0x3f317217, v143
	v_fma_f32 v144, v143, s97, -v144
	v_fmac_f32_e32 v144, 0x3377d1cf, v143
	v_fmac_f32_e32 v144, 0x3f317217, v143
	v_cmp_lt_f32_e64 s[0:1], |v143|, s2
	s_nop 1
	v_cndmask_b32_e64 v143, v143, v144, s[0:1]
	v_cndmask_b32_e32 v144, 0, v213, vcc
	v_sub_f32_e32 v143, v143, v144
	v_mul_f32_e32 v144, 0xbfb8aa3b, v98
	v_exp_f32_e32 v144, v144
	s_nop 0
	v_add_f32_e32 v144, 1.0, v144
	v_rcp_f32_e32 v144, v144
	s_nop 0
	v_fma_f32 v144, v144, v154, v134
	v_cmp_gt_f32_e32 vcc, s33, v144
	s_nop 1
	v_cndmask_b32_e64 v145, 0, 32, vcc
	v_ldexp_f32 v144, v144, v145
	v_log_f32_e32 v144, v144
	s_nop 0
	v_mul_f32_e32 v145, 0x3f317217, v144
	v_fma_f32 v145, v144, s97, -v145
	v_fmac_f32_e32 v145, 0x3377d1cf, v144
	v_fmac_f32_e32 v145, 0x3f317217, v144
	v_cmp_lt_f32_e64 s[0:1], |v144|, s2
	s_nop 1
	v_cndmask_b32_e64 v144, v144, v145, s[0:1]
	v_cndmask_b32_e32 v145, 0, v213, vcc
	v_sub_f32_e32 v145, v144, v145
	v_mul_f32_e32 v144, 0xbfb8aa3b, v99
	v_exp_f32_e32 v144, v144
	s_nop 0
	v_add_f32_e32 v144, 1.0, v144
	v_rcp_f32_e32 v144, v144
	s_nop 0
	v_fma_f32 v144, v144, v155, v135
	v_cmp_gt_f32_e32 vcc, s33, v144
	s_nop 1
	v_cndmask_b32_e64 v146, 0, 32, vcc
	v_ldexp_f32 v144, v144, v146
	v_log_f32_e32 v144, v144
	s_nop 0
	v_mul_f32_e32 v146, 0x3f317217, v144
	v_fma_f32 v146, v144, s97, -v146
	v_fmac_f32_e32 v146, 0x3377d1cf, v144
	v_fmac_f32_e32 v146, 0x3f317217, v144
	v_cmp_lt_f32_e64 s[0:1], |v144|, s2
	s_nop 1
	v_cndmask_b32_e64 v144, v144, v146, s[0:1]
	v_cndmask_b32_e32 v146, 0, v213, vcc
	v_sub_f32_e32 v146, v144, v146
	v_mul_f32_e32 v144, 0xbfb8aa3b, v88
	v_exp_f32_e32 v144, v144
	v_cvt_pk_bf16_f32 v145, v145, v146
	v_add_f32_e32 v144, 1.0, v144
	v_rcp_f32_e32 v144, v144
	s_nop 0
	v_fma_f32 v144, v144, v156, v128
	v_cmp_gt_f32_e32 vcc, s33, v144
	s_nop 1
	v_cndmask_b32_e64 v147, 0, 32, vcc
	v_ldexp_f32 v144, v144, v147
	v_log_f32_e32 v144, v144
	s_nop 0
	v_mul_f32_e32 v147, 0x3f317217, v144
	v_fma_f32 v147, v144, s97, -v147
	v_fmac_f32_e32 v147, 0x3377d1cf, v144
	v_fmac_f32_e32 v147, 0x3f317217, v144
	v_cmp_lt_f32_e64 s[0:1], |v144|, s2
	s_nop 1
	v_cndmask_b32_e64 v144, v144, v147, s[0:1]
	v_cndmask_b32_e32 v147, 0, v213, vcc
	v_sub_f32_e32 v147, v144, v147
	v_mul_f32_e32 v144, 0xbfb8aa3b, v89
	v_exp_f32_e32 v144, v144
	s_nop 0
	v_add_f32_e32 v144, 1.0, v144
	v_rcp_f32_e32 v144, v144
	s_nop 0
	v_fma_f32 v144, v144, v157, v129
	v_cmp_gt_f32_e32 vcc, s33, v144
	s_nop 1
	v_cndmask_b32_e64 v148, 0, 32, vcc
	v_ldexp_f32 v144, v144, v148
	v_log_f32_e32 v144, v144
	s_nop 0
	v_mul_f32_e32 v148, 0x3f317217, v144
	v_fma_f32 v148, v144, s97, -v148
	v_fmac_f32_e32 v148, 0x3377d1cf, v144
	v_fmac_f32_e32 v148, 0x3f317217, v144
	v_cmp_lt_f32_e64 s[0:1], |v144|, s2
	s_nop 1
	v_cndmask_b32_e64 v144, v144, v148, s[0:1]
	v_cndmask_b32_e32 v148, 0, v213, vcc
	v_sub_f32_e32 v148, v144, v148
	v_mul_f32_e32 v144, 0xbfb8aa3b, v90
	v_exp_f32_e32 v144, v144
	v_cvt_pk_bf16_f32 v146, v147, v148
	v_add_f32_e32 v144, 1.0, v144
	v_rcp_f32_e32 v144, v144
	s_nop 0
	v_fma_f32 v144, v144, v159, v130
	v_cmp_gt_f32_e32 vcc, s33, v144
	s_nop 1
	v_cndmask_b32_e64 v149, 0, 32, vcc
	v_ldexp_f32 v144, v144, v149
	v_log_f32_e32 v144, v144
	s_nop 0
	v_mul_f32_e32 v149, 0x3f317217, v144
	v_fma_f32 v149, v144, s97, -v149
	v_fmac_f32_e32 v149, 0x3377d1cf, v144
	v_fmac_f32_e32 v149, 0x3f317217, v144
	v_cmp_lt_f32_e64 s[0:1], |v144|, s2
	s_nop 1
	v_cndmask_b32_e64 v144, v144, v149, s[0:1]
	v_cndmask_b32_e32 v149, 0, v213, vcc
	v_sub_f32_e32 v149, v144, v149
	v_mul_f32_e32 v144, 0xbfb8aa3b, v91
	v_exp_f32_e32 v144, v144
	s_nop 0
	v_add_f32_e32 v144, 1.0, v144
	v_rcp_f32_e32 v144, v144
	s_nop 0
	v_fma_f32 v144, v144, v158, v131
	v_cmp_gt_f32_e32 vcc, s33, v144
	s_nop 1
	v_cndmask_b32_e64 v152, 0, 32, vcc
	v_ldexp_f32 v144, v144, v152
	v_log_f32_e32 v144, v144
	s_nop 0
	v_mul_f32_e32 v152, 0x3f317217, v144
	v_fma_f32 v152, v144, s97, -v152
	v_fmac_f32_e32 v152, 0x3377d1cf, v144
	v_fmac_f32_e32 v152, 0x3f317217, v144
	v_cmp_lt_f32_e64 s[0:1], |v144|, s2
	s_nop 1
	v_cndmask_b32_e64 v144, v144, v152, s[0:1]
	v_cndmask_b32_e32 v152, 0, v213, vcc
	v_sub_f32_e32 v152, v144, v152
	v_cvt_pk_bf16_f32 v144, v142, v143
	v_or_b32_e32 v142, 32, v186
	v_ashrrev_i32_e32 v143, 31, v142
	v_lshlrev_b64 v[142:143], 11, v[142:143]
	v_cvt_pk_bf16_f32 v147, v149, v152
	v_lshl_add_u64 v[148:149], v[136:137], 0, v[142:143]
	global_store_dwordx4 v[148:149], v[144:147], off sc1
	v_lshl_add_u64 v[142:143], s[8:9], 0, v[142:143]
	s_nop 0
	v_mul_f32_e32 v144, 0xbfb8aa3b, v80
	v_exp_f32_e32 v144, v144
	s_nop 0
	v_add_f32_e32 v144, 1.0, v144
	v_rcp_f32_e32 v144, v144
	s_nop 0
	v_fma_f32 v144, v144, v150, v132
	v_cmp_gt_f32_e32 vcc, s33, v144
	s_nop 1
	v_cndmask_b32_e64 v145, 0, 32, vcc
	v_ldexp_f32 v144, v144, v145
	v_log_f32_e32 v144, v144
	s_nop 0
	v_mul_f32_e32 v145, 0x3f317217, v144
	v_fma_f32 v145, v144, s97, -v145
	v_fmac_f32_e32 v145, 0x3377d1cf, v144
	v_fmac_f32_e32 v145, 0x3f317217, v144
	v_cmp_lt_f32_e64 s[0:1], |v144|, s2
	s_nop 1
	v_cndmask_b32_e64 v144, v144, v145, s[0:1]
	v_cndmask_b32_e32 v145, 0, v213, vcc
	v_sub_f32_e32 v144, v144, v145
	v_mul_f32_e32 v145, 0xbfb8aa3b, v81
	v_exp_f32_e32 v145, v145
	s_nop 0
	v_add_f32_e32 v145, 1.0, v145
	v_rcp_f32_e32 v145, v145
	s_nop 0
	v_fma_f32 v145, v145, v151, v133
	v_cmp_gt_f32_e32 vcc, s33, v145
	s_nop 1
	v_cndmask_b32_e64 v146, 0, 32, vcc
	v_ldexp_f32 v145, v145, v146
	v_log_f32_e32 v145, v145
	s_nop 0
	v_mul_f32_e32 v146, 0x3f317217, v145
	v_fma_f32 v146, v145, s97, -v146
	v_fmac_f32_e32 v146, 0x3377d1cf, v145
	v_fmac_f32_e32 v146, 0x3f317217, v145
	v_cmp_lt_f32_e64 s[0:1], |v145|, s2
	s_nop 1
	v_cndmask_b32_e64 v145, v145, v146, s[0:1]
	v_cndmask_b32_e32 v146, 0, v213, vcc
	v_sub_f32_e32 v145, v145, v146
	v_mul_f32_e32 v146, 0xbfb8aa3b, v82
	v_exp_f32_e32 v146, v146
	s_nop 0
	v_add_f32_e32 v146, 1.0, v146
	v_rcp_f32_e32 v146, v146
	s_nop 0
	v_fma_f32 v146, v146, v154, v134
	v_cmp_gt_f32_e32 vcc, s33, v146
	s_nop 1
	v_cndmask_b32_e64 v147, 0, 32, vcc
	v_ldexp_f32 v146, v146, v147
	v_log_f32_e32 v146, v146
	s_nop 0
	v_mul_f32_e32 v147, 0x3f317217, v146
	v_fma_f32 v147, v146, s97, -v147
	v_fmac_f32_e32 v147, 0x3377d1cf, v146
	v_fmac_f32_e32 v147, 0x3f317217, v146
	v_cmp_lt_f32_e64 s[0:1], |v146|, s2
	s_nop 1
	v_cndmask_b32_e64 v146, v146, v147, s[0:1]
	v_cndmask_b32_e32 v147, 0, v213, vcc
	v_sub_f32_e32 v147, v146, v147
	v_mul_f32_e32 v146, 0xbfb8aa3b, v83
	v_exp_f32_e32 v146, v146
	s_nop 0
	v_add_f32_e32 v146, 1.0, v146
	v_rcp_f32_e32 v146, v146
	s_nop 0
	v_fma_f32 v146, v146, v155, v135
	v_cmp_gt_f32_e32 vcc, s33, v146
	s_nop 1
	v_cndmask_b32_e64 v148, 0, 32, vcc
	v_ldexp_f32 v146, v146, v148
	v_log_f32_e32 v146, v146
	s_nop 0
	v_mul_f32_e32 v148, 0x3f317217, v146
	v_fma_f32 v148, v146, s97, -v148
	v_fmac_f32_e32 v148, 0x3377d1cf, v146
	v_fmac_f32_e32 v148, 0x3f317217, v146
	v_cmp_lt_f32_e64 s[0:1], |v146|, s2
	s_nop 1
	v_cndmask_b32_e64 v146, v146, v148, s[0:1]
	v_cndmask_b32_e32 v148, 0, v213, vcc
	v_sub_f32_e32 v148, v146, v148
	v_mul_f32_e32 v146, 0xbfb8aa3b, v72
	v_exp_f32_e32 v146, v146
	v_cvt_pk_bf16_f32 v147, v147, v148
	v_add_f32_e32 v146, 1.0, v146
	v_rcp_f32_e32 v146, v146
	s_nop 0
	v_fma_f32 v146, v146, v156, v128
	v_cmp_gt_f32_e32 vcc, s33, v146
	s_nop 1
	v_cndmask_b32_e64 v149, 0, 32, vcc
	v_ldexp_f32 v146, v146, v149
	v_log_f32_e32 v146, v146
	s_nop 0
	v_mul_f32_e32 v149, 0x3f317217, v146
	v_fma_f32 v149, v146, s97, -v149
	v_fmac_f32_e32 v149, 0x3377d1cf, v146
	v_fmac_f32_e32 v149, 0x3f317217, v146
	v_cmp_lt_f32_e64 s[0:1], |v146|, s2
	s_nop 1
	v_cndmask_b32_e64 v146, v146, v149, s[0:1]
	v_cndmask_b32_e32 v149, 0, v213, vcc
	v_sub_f32_e32 v149, v146, v149
	v_mul_f32_e32 v146, 0xbfb8aa3b, v73
	v_exp_f32_e32 v146, v146
	s_nop 0
	v_add_f32_e32 v146, 1.0, v146
	v_rcp_f32_e32 v146, v146
	s_nop 0
	v_fma_f32 v146, v146, v157, v129
	v_cmp_gt_f32_e32 vcc, s33, v146
	s_nop 1
	v_cndmask_b32_e64 v152, 0, 32, vcc
	v_ldexp_f32 v146, v146, v152
	v_log_f32_e32 v146, v146
	s_nop 0
	v_mul_f32_e32 v152, 0x3f317217, v146
	v_fma_f32 v152, v146, s97, -v152
	v_fmac_f32_e32 v152, 0x3377d1cf, v146
	v_fmac_f32_e32 v152, 0x3f317217, v146
	v_cmp_lt_f32_e64 s[0:1], |v146|, s2
	s_nop 1
	v_cndmask_b32_e64 v146, v146, v152, s[0:1]
	v_cndmask_b32_e32 v152, 0, v213, vcc
	v_sub_f32_e32 v152, v146, v152
	v_mul_f32_e32 v146, 0xbfb8aa3b, v74
	v_exp_f32_e32 v146, v146
	v_cvt_pk_bf16_f32 v148, v149, v152
	v_add_f32_e32 v146, 1.0, v146
	v_rcp_f32_e32 v146, v146
	s_nop 0
	v_fma_f32 v146, v146, v159, v130
	v_cmp_gt_f32_e32 vcc, s33, v146
	s_nop 1
	v_cndmask_b32_e64 v153, 0, 32, vcc
	v_ldexp_f32 v146, v146, v153
	v_log_f32_e32 v146, v146
	s_nop 0
	v_mul_f32_e32 v153, 0x3f317217, v146
	v_fma_f32 v153, v146, s97, -v153
	v_fmac_f32_e32 v153, 0x3377d1cf, v146
	v_fmac_f32_e32 v153, 0x3f317217, v146
	v_cmp_lt_f32_e64 s[0:1], |v146|, s2
	s_nop 1
	v_cndmask_b32_e64 v146, v146, v153, s[0:1]
	v_cndmask_b32_e32 v153, 0, v213, vcc
	v_sub_f32_e32 v153, v146, v153
	v_mul_f32_e32 v146, 0xbfb8aa3b, v75
	v_exp_f32_e32 v146, v146
	s_nop 0
	v_add_f32_e32 v146, 1.0, v146
	v_rcp_f32_e32 v146, v146
	s_nop 0
	v_fma_f32 v146, v146, v158, v131
	v_cmp_gt_f32_e32 vcc, s33, v146
	s_nop 1
	v_cndmask_b32_e64 v160, 0, 32, vcc
	v_ldexp_f32 v146, v146, v160
	v_log_f32_e32 v146, v146
	s_nop 0
	v_mul_f32_e32 v160, 0x3f317217, v146
	v_fma_f32 v160, v146, s97, -v160
	v_fmac_f32_e32 v160, 0x3377d1cf, v146
	v_fmac_f32_e32 v160, 0x3f317217, v146
	v_cmp_lt_f32_e64 s[0:1], |v146|, s2
	s_nop 1
	v_cndmask_b32_e64 v146, v146, v160, s[0:1]
	v_cndmask_b32_e32 v160, 0, v213, vcc
	v_sub_f32_e32 v160, v146, v160
	v_cvt_pk_bf16_f32 v146, v144, v145
	v_or_b32_e32 v144, 48, v186
	v_ashrrev_i32_e32 v145, 31, v144
	v_lshlrev_b64 v[144:145], 11, v[144:145]
	v_cvt_pk_bf16_f32 v149, v153, v160
	v_lshl_add_u64 v[152:153], v[136:137], 0, v[144:145]
	global_store_dwordx4 v[152:153], v[146:149], off sc1
	s_nop 1
	v_mul_f32_e32 v146, 0xbfb8aa3b, v60
	v_exp_f32_e32 v146, v146
	s_nop 0
	v_add_f32_e32 v146, 1.0, v146
	v_rcp_f32_e32 v146, v146
	s_nop 0
	v_fma_f32 v146, v146, v150, v132
	v_cmp_gt_f32_e32 vcc, s33, v146
	s_nop 1
	v_cndmask_b32_e64 v147, 0, 32, vcc
	v_ldexp_f32 v146, v146, v147
	v_log_f32_e32 v146, v146
	s_nop 0
	v_mul_f32_e32 v147, 0x3f317217, v146
	v_fma_f32 v147, v146, s97, -v147
	v_fmac_f32_e32 v147, 0x3377d1cf, v146
	v_fmac_f32_e32 v147, 0x3f317217, v146
	v_cmp_lt_f32_e64 s[0:1], |v146|, s2
	s_nop 1
	v_cndmask_b32_e64 v146, v146, v147, s[0:1]
	v_cndmask_b32_e32 v147, 0, v213, vcc
	v_sub_f32_e32 v146, v146, v147
	v_mul_f32_e32 v147, 0xbfb8aa3b, v61
	v_exp_f32_e32 v147, v147
	s_nop 0
	v_add_f32_e32 v147, 1.0, v147
	v_rcp_f32_e32 v147, v147
	s_nop 0
	v_fma_f32 v147, v147, v151, v133
	v_cmp_gt_f32_e32 vcc, s33, v147
	s_nop 1
	v_cndmask_b32_e64 v148, 0, 32, vcc
	v_ldexp_f32 v147, v147, v148
	v_log_f32_e32 v147, v147
	s_nop 0
	v_mul_f32_e32 v148, 0x3f317217, v147
	v_fma_f32 v148, v147, s97, -v148
	v_fmac_f32_e32 v148, 0x3377d1cf, v147
	v_fmac_f32_e32 v148, 0x3f317217, v147
	v_cmp_lt_f32_e64 s[0:1], |v147|, s2
	s_nop 1
	v_cndmask_b32_e64 v147, v147, v148, s[0:1]
	v_cndmask_b32_e32 v148, 0, v213, vcc
	v_sub_f32_e32 v147, v147, v148
	v_mul_f32_e32 v148, 0xbfb8aa3b, v62
	v_exp_f32_e32 v148, v148
	s_nop 0
	v_add_f32_e32 v148, 1.0, v148
	v_rcp_f32_e32 v148, v148
	s_nop 0
	v_fma_f32 v148, v148, v154, v134
	v_cmp_gt_f32_e32 vcc, s33, v148
	s_nop 1
	v_cndmask_b32_e64 v149, 0, 32, vcc
	v_ldexp_f32 v148, v148, v149
	v_log_f32_e32 v148, v148
	s_nop 0
	v_mul_f32_e32 v149, 0x3f317217, v148
	v_fma_f32 v149, v148, s97, -v149
	v_fmac_f32_e32 v149, 0x3377d1cf, v148
	v_fmac_f32_e32 v149, 0x3f317217, v148
	v_cmp_lt_f32_e64 s[0:1], |v148|, s2
	s_nop 1
	v_cndmask_b32_e64 v148, v148, v149, s[0:1]
	v_cndmask_b32_e32 v149, 0, v213, vcc
	v_sub_f32_e32 v148, v148, v149
	v_mul_f32_e32 v149, 0xbfb8aa3b, v63
	v_exp_f32_e32 v149, v149
	s_nop 0
	v_add_f32_e32 v149, 1.0, v149
	v_rcp_f32_e32 v149, v149
	s_nop 0
	v_fma_f32 v149, v149, v155, v135
	v_cmp_gt_f32_e32 vcc, s33, v149
	s_nop 1
	v_cndmask_b32_e64 v152, 0, 32, vcc
	v_ldexp_f32 v149, v149, v152
	v_log_f32_e32 v149, v149
	s_nop 0
	v_mul_f32_e32 v152, 0x3f317217, v149
	v_fma_f32 v152, v149, s97, -v152
	v_fmac_f32_e32 v152, 0x3377d1cf, v149
	v_fmac_f32_e32 v152, 0x3f317217, v149
	v_cmp_lt_f32_e64 s[0:1], |v149|, s2
	s_nop 1
	v_cndmask_b32_e64 v149, v149, v152, s[0:1]
	v_cndmask_b32_e32 v152, 0, v213, vcc
	v_sub_f32_e32 v149, v149, v152
	v_mul_f32_e32 v152, 0xbfb8aa3b, v56
	v_exp_f32_e32 v152, v152
	s_nop 0
	v_add_f32_e32 v152, 1.0, v152
	v_rcp_f32_e32 v152, v152
	s_nop 0
	v_fma_f32 v152, v152, v156, v128
	v_cmp_gt_f32_e32 vcc, s33, v152
	s_nop 1
	v_cndmask_b32_e64 v153, 0, 32, vcc
	v_ldexp_f32 v152, v152, v153
	v_log_f32_e32 v152, v152
	s_nop 0
	v_mul_f32_e32 v153, 0x3f317217, v152
	v_fma_f32 v153, v152, s97, -v153
	v_fmac_f32_e32 v153, 0x3377d1cf, v152
	v_fmac_f32_e32 v153, 0x3f317217, v152
	v_cmp_lt_f32_e64 s[0:1], |v152|, s2
	s_nop 1
	v_cndmask_b32_e64 v152, v152, v153, s[0:1]
	v_cndmask_b32_e32 v153, 0, v213, vcc
	v_sub_f32_e32 v152, v152, v153
	v_mul_f32_e32 v153, 0xbfb8aa3b, v57
	v_exp_f32_e32 v153, v153
	s_nop 0
	v_add_f32_e32 v153, 1.0, v153
	v_rcp_f32_e32 v153, v153
	s_nop 0
	v_fma_f32 v153, v153, v157, v129
	v_cmp_gt_f32_e32 vcc, s33, v153
	s_nop 1
	v_cndmask_b32_e64 v160, 0, 32, vcc
	v_ldexp_f32 v153, v153, v160
	v_log_f32_e32 v153, v153
	s_nop 0
	v_mul_f32_e32 v160, 0x3f317217, v153
	v_fma_f32 v160, v153, s97, -v160
	v_fmac_f32_e32 v160, 0x3377d1cf, v153
	v_fmac_f32_e32 v160, 0x3f317217, v153
	v_cmp_lt_f32_e64 s[0:1], |v153|, s2
	s_nop 1
	v_cndmask_b32_e64 v153, v153, v160, s[0:1]
	v_cndmask_b32_e32 v160, 0, v213, vcc
	v_sub_f32_e32 v153, v153, v160
	v_mul_f32_e32 v160, 0xbfb8aa3b, v58
	v_exp_f32_e32 v160, v160
	v_cvt_pk_bf16_f32 v162, v152, v153
	v_add_f32_e32 v160, 1.0, v160
	v_rcp_f32_e32 v160, v160
	s_nop 0
	v_fma_f32 v160, v160, v159, v130
	v_cmp_gt_f32_e32 vcc, s33, v160
	s_nop 1
	v_cndmask_b32_e64 v161, 0, 32, vcc
	v_ldexp_f32 v160, v160, v161
	v_log_f32_e32 v160, v160
	s_nop 0
	v_mul_f32_e32 v161, 0x3f317217, v160
	v_fma_f32 v161, v160, s97, -v161
	v_fmac_f32_e32 v161, 0x3377d1cf, v160
	v_fmac_f32_e32 v161, 0x3f317217, v160
	v_cmp_lt_f32_e64 s[0:1], |v160|, s2
	s_nop 1
	v_cndmask_b32_e64 v160, v160, v161, s[0:1]
	v_cndmask_b32_e32 v161, 0, v213, vcc
	v_sub_f32_e32 v163, v160, v161
	v_mul_f32_e32 v160, 0xbfb8aa3b, v59
	v_exp_f32_e32 v160, v160
	s_nop 0
	v_add_f32_e32 v160, 1.0, v160
	v_rcp_f32_e32 v160, v160
	s_nop 0
	v_fma_f32 v160, v160, v158, v131
	v_cmp_gt_f32_e32 vcc, s33, v160
	s_nop 1
	v_cndmask_b32_e64 v161, 0, 32, vcc
	v_ldexp_f32 v160, v160, v161
	v_log_f32_e32 v160, v160
	s_nop 0
	v_mul_f32_e32 v161, 0x3f317217, v160
	v_fma_f32 v161, v160, s97, -v161
	v_fmac_f32_e32 v161, 0x3377d1cf, v160
	v_fmac_f32_e32 v161, 0x3f317217, v160
	v_cmp_lt_f32_e64 s[0:1], |v160|, s2
	s_nop 1
	v_cndmask_b32_e64 v160, v160, v161, s[0:1]
	v_cndmask_b32_e32 v161, 0, v213, vcc
	v_sub_f32_e32 v164, v160, v161
	v_cvt_pk_bf16_f32 v160, v146, v147
	v_lshl_add_u64 v[146:147], v[138:139], 0, s[4:5]
	v_cvt_pk_bf16_f32 v161, v148, v149
	v_cvt_pk_bf16_f32 v163, v163, v164
	v_lshl_add_u64 v[148:149], v[136:137], 0, v[146:147]
	global_store_dwordx4 v[148:149], v[160:163], off sc1
	v_mul_f32_e32 v148, 0xbfb8aa3b, v48
	v_exp_f32_e32 v148, v148
	s_nop 0
	v_add_f32_e32 v148, 1.0, v148
	v_rcp_f32_e32 v148, v148
	s_nop 0
	v_fma_f32 v148, v148, v150, v132
	v_cmp_gt_f32_e32 vcc, s33, v148
	s_nop 1
	v_cndmask_b32_e64 v149, 0, 32, vcc
	v_ldexp_f32 v148, v148, v149
	v_log_f32_e32 v148, v148
	s_nop 0
	v_mul_f32_e32 v149, 0x3f317217, v148
	v_fma_f32 v149, v148, s97, -v149
	v_fmac_f32_e32 v149, 0x3377d1cf, v148
	v_fmac_f32_e32 v149, 0x3f317217, v148
	v_cmp_lt_f32_e64 s[0:1], |v148|, s2
	s_nop 1
	v_cndmask_b32_e64 v148, v148, v149, s[0:1]
	v_cndmask_b32_e32 v149, 0, v213, vcc
	v_sub_f32_e32 v148, v148, v149
	v_mul_f32_e32 v149, 0xbfb8aa3b, v49
	v_exp_f32_e32 v149, v149
	s_nop 0
	v_add_f32_e32 v149, 1.0, v149
	v_rcp_f32_e32 v149, v149
	s_nop 0
	v_fma_f32 v149, v149, v151, v133
	v_cmp_gt_f32_e32 vcc, s33, v149
	s_nop 1
	v_cndmask_b32_e64 v152, 0, 32, vcc
	v_ldexp_f32 v149, v149, v152
	v_log_f32_e32 v149, v149
	s_nop 0
	v_mul_f32_e32 v152, 0x3f317217, v149
	v_fma_f32 v152, v149, s97, -v152
	v_fmac_f32_e32 v152, 0x3377d1cf, v149
	v_fmac_f32_e32 v152, 0x3f317217, v149
	v_cmp_lt_f32_e64 s[0:1], |v149|, s2
	s_nop 1
	v_cndmask_b32_e64 v149, v149, v152, s[0:1]
	v_cndmask_b32_e32 v152, 0, v213, vcc
	v_sub_f32_e32 v149, v149, v152
	v_mul_f32_e32 v152, 0xbfb8aa3b, v50
	v_exp_f32_e32 v152, v152
	s_nop 0
	v_add_f32_e32 v152, 1.0, v152
	v_rcp_f32_e32 v152, v152
	s_nop 0
	v_fma_f32 v152, v152, v154, v134
	v_cmp_gt_f32_e32 vcc, s33, v152
	s_nop 1
	v_cndmask_b32_e64 v153, 0, 32, vcc
	v_ldexp_f32 v152, v152, v153
	v_log_f32_e32 v152, v152
	s_nop 0
	v_mul_f32_e32 v153, 0x3f317217, v152
	v_fma_f32 v153, v152, s97, -v153
	v_fmac_f32_e32 v153, 0x3377d1cf, v152
	v_fmac_f32_e32 v153, 0x3f317217, v152
	v_cmp_lt_f32_e64 s[0:1], |v152|, s2
	s_nop 1
	v_cndmask_b32_e64 v152, v152, v153, s[0:1]
	v_cndmask_b32_e32 v153, 0, v213, vcc
	v_sub_f32_e32 v152, v152, v153
	v_mul_f32_e32 v153, 0xbfb8aa3b, v51
	v_exp_f32_e32 v153, v153
	s_nop 0
	v_add_f32_e32 v153, 1.0, v153
	v_rcp_f32_e32 v153, v153
	s_nop 0
	v_fma_f32 v153, v153, v155, v135
	v_cmp_gt_f32_e32 vcc, s33, v153
	s_nop 1
	v_cndmask_b32_e64 v160, 0, 32, vcc
	v_ldexp_f32 v153, v153, v160
	v_log_f32_e32 v153, v153
	s_nop 0
	v_mul_f32_e32 v160, 0x3f317217, v153
	v_fma_f32 v160, v153, s97, -v160
	v_fmac_f32_e32 v160, 0x3377d1cf, v153
	v_fmac_f32_e32 v160, 0x3f317217, v153
	v_cmp_lt_f32_e64 s[0:1], |v153|, s2
	s_nop 1
	v_cndmask_b32_e64 v153, v153, v160, s[0:1]
	v_cndmask_b32_e32 v160, 0, v213, vcc
	v_sub_f32_e32 v153, v153, v160
	v_mul_f32_e32 v160, 0xbfb8aa3b, v40
	v_exp_f32_e32 v160, v160
	s_nop 0
	v_add_f32_e32 v160, 1.0, v160
	v_rcp_f32_e32 v160, v160
	s_nop 0
	v_fma_f32 v160, v160, v156, v128
	v_cmp_gt_f32_e32 vcc, s33, v160
	s_nop 1
	v_cndmask_b32_e64 v161, 0, 32, vcc
	v_ldexp_f32 v160, v160, v161
	v_log_f32_e32 v160, v160
	s_nop 0
	v_mul_f32_e32 v161, 0x3f317217, v160
	v_fma_f32 v161, v160, s97, -v161
	v_fmac_f32_e32 v161, 0x3377d1cf, v160
	v_fmac_f32_e32 v161, 0x3f317217, v160
	v_cmp_lt_f32_e64 s[0:1], |v160|, s2
	s_nop 1
	v_cndmask_b32_e64 v160, v160, v161, s[0:1]
	v_cndmask_b32_e32 v161, 0, v213, vcc
	v_sub_f32_e32 v162, v160, v161
	v_mul_f32_e32 v160, 0xbfb8aa3b, v41
	v_exp_f32_e32 v160, v160
	s_nop 0
	v_add_f32_e32 v160, 1.0, v160
	v_rcp_f32_e32 v160, v160
	s_nop 0
	v_fma_f32 v160, v160, v157, v129
	v_cmp_gt_f32_e32 vcc, s33, v160
	s_nop 1
	v_cndmask_b32_e64 v161, 0, 32, vcc
	v_ldexp_f32 v160, v160, v161
	v_log_f32_e32 v160, v160
	s_nop 0
	v_mul_f32_e32 v161, 0x3f317217, v160
	v_fma_f32 v161, v160, s97, -v161
	v_fmac_f32_e32 v161, 0x3377d1cf, v160
	v_fmac_f32_e32 v161, 0x3f317217, v160
	v_cmp_lt_f32_e64 s[0:1], |v160|, s2
	s_nop 1
	v_cndmask_b32_e64 v160, v160, v161, s[0:1]
	v_cndmask_b32_e32 v161, 0, v213, vcc
	v_sub_f32_e32 v163, v160, v161
	v_mul_f32_e32 v160, 0xbfb8aa3b, v42
	v_exp_f32_e32 v160, v160
	v_cvt_pk_bf16_f32 v162, v162, v163
	v_add_f32_e32 v160, 1.0, v160
	v_rcp_f32_e32 v160, v160
	s_nop 0
	v_fma_f32 v160, v160, v159, v130
	v_cmp_gt_f32_e32 vcc, s33, v160
	s_nop 1
	v_cndmask_b32_e64 v161, 0, 32, vcc
	v_ldexp_f32 v160, v160, v161
	v_log_f32_e32 v160, v160
	s_nop 0
	v_mul_f32_e32 v161, 0x3f317217, v160
	v_fma_f32 v161, v160, s97, -v161
	v_fmac_f32_e32 v161, 0x3377d1cf, v160
	v_fmac_f32_e32 v161, 0x3f317217, v160
	v_cmp_lt_f32_e64 s[0:1], |v160|, s2
	s_nop 1
	v_cndmask_b32_e64 v160, v160, v161, s[0:1]
	v_cndmask_b32_e32 v161, 0, v213, vcc
	v_sub_f32_e32 v164, v160, v161
	v_mul_f32_e32 v160, 0xbfb8aa3b, v43
	v_exp_f32_e32 v160, v160
	s_nop 0
	v_add_f32_e32 v160, 1.0, v160
	v_rcp_f32_e32 v160, v160
	s_nop 0
	v_fma_f32 v160, v160, v158, v131
	v_cmp_gt_f32_e32 vcc, s33, v160
	s_nop 1
	v_cndmask_b32_e64 v161, 0, 32, vcc
	v_ldexp_f32 v160, v160, v161
	v_log_f32_e32 v160, v160
	s_nop 0
	v_mul_f32_e32 v161, 0x3f317217, v160
	v_fma_f32 v161, v160, s97, -v161
	v_fmac_f32_e32 v161, 0x3377d1cf, v160
	v_fmac_f32_e32 v161, 0x3f317217, v160
	v_cmp_lt_f32_e64 s[0:1], |v160|, s2
	s_nop 1
	v_cndmask_b32_e64 v160, v160, v161, s[0:1]
	v_cndmask_b32_e32 v161, 0, v213, vcc
	s_mov_b64 s[0:1], 0x48000
	v_sub_f32_e32 v165, v160, v161
	v_cvt_pk_bf16_f32 v160, v148, v149
	v_lshl_add_u64 v[148:149], v[138:139], 0, s[0:1]
	v_cvt_pk_bf16_f32 v161, v152, v153
	v_cvt_pk_bf16_f32 v163, v164, v165
	v_lshl_add_u64 v[152:153], v[136:137], 0, v[148:149]
	global_store_dwordx4 v[152:153], v[160:163], off sc1
	v_mul_f32_e32 v152, 0xbfb8aa3b, v32
	v_exp_f32_e32 v152, v152
	s_nop 0
	v_add_f32_e32 v152, 1.0, v152
	v_rcp_f32_e32 v152, v152
	s_nop 0
	v_fma_f32 v152, v152, v150, v132
	v_cmp_gt_f32_e32 vcc, s33, v152
	s_nop 1
	v_cndmask_b32_e64 v153, 0, 32, vcc
	v_ldexp_f32 v152, v152, v153
	v_log_f32_e32 v152, v152
	s_nop 0
	v_mul_f32_e32 v153, 0x3f317217, v152
	v_fma_f32 v153, v152, s97, -v153
	v_fmac_f32_e32 v153, 0x3377d1cf, v152
	v_fmac_f32_e32 v153, 0x3f317217, v152
	v_cmp_lt_f32_e64 s[0:1], |v152|, s2
	s_nop 1
	v_cndmask_b32_e64 v152, v152, v153, s[0:1]
	v_cndmask_b32_e32 v153, 0, v213, vcc
	v_sub_f32_e32 v152, v152, v153
	v_mul_f32_e32 v153, 0xbfb8aa3b, v33
	v_exp_f32_e32 v153, v153
	s_nop 0
	v_add_f32_e32 v153, 1.0, v153
	v_rcp_f32_e32 v153, v153
	s_nop 0
	v_fma_f32 v153, v153, v151, v133
	v_cmp_gt_f32_e32 vcc, s33, v153
	s_nop 1
	v_cndmask_b32_e64 v160, 0, 32, vcc
	v_ldexp_f32 v153, v153, v160
	v_log_f32_e32 v153, v153
	s_nop 0
	v_mul_f32_e32 v160, 0x3f317217, v153
	v_fma_f32 v160, v153, s97, -v160
	v_fmac_f32_e32 v160, 0x3377d1cf, v153
	v_fmac_f32_e32 v160, 0x3f317217, v153
	v_cmp_lt_f32_e64 s[0:1], |v153|, s2
	s_nop 1
	v_cndmask_b32_e64 v153, v153, v160, s[0:1]
	v_cndmask_b32_e32 v160, 0, v213, vcc
	v_sub_f32_e32 v153, v153, v160
	v_mul_f32_e32 v160, 0xbfb8aa3b, v34
	v_exp_f32_e32 v160, v160
	s_nop 0
	v_add_f32_e32 v160, 1.0, v160
	v_rcp_f32_e32 v160, v160
	s_nop 0
	v_fma_f32 v160, v160, v154, v134
	v_cmp_gt_f32_e32 vcc, s33, v160
	s_nop 1
	v_cndmask_b32_e64 v161, 0, 32, vcc
	v_ldexp_f32 v160, v160, v161
	v_log_f32_e32 v160, v160
	s_nop 0
	v_mul_f32_e32 v161, 0x3f317217, v160
	v_fma_f32 v161, v160, s97, -v161
	v_fmac_f32_e32 v161, 0x3377d1cf, v160
	v_fmac_f32_e32 v161, 0x3f317217, v160
	v_cmp_lt_f32_e64 s[0:1], |v160|, s2
	s_nop 1
	v_cndmask_b32_e64 v160, v160, v161, s[0:1]
	v_cndmask_b32_e32 v161, 0, v213, vcc
	v_sub_f32_e32 v161, v160, v161
	v_mul_f32_e32 v160, 0xbfb8aa3b, v35
	v_exp_f32_e32 v160, v160
	s_nop 0
	v_add_f32_e32 v160, 1.0, v160
	v_rcp_f32_e32 v160, v160
	s_nop 0
	v_fma_f32 v160, v160, v155, v135
	v_cmp_gt_f32_e32 vcc, s33, v160
	s_nop 1
	v_cndmask_b32_e64 v162, 0, 32, vcc
	v_ldexp_f32 v160, v160, v162
	v_log_f32_e32 v160, v160
	s_nop 0
	v_mul_f32_e32 v162, 0x3f317217, v160
	v_fma_f32 v162, v160, s97, -v162
	v_fmac_f32_e32 v162, 0x3377d1cf, v160
	v_fmac_f32_e32 v162, 0x3f317217, v160
	v_cmp_lt_f32_e64 s[0:1], |v160|, s2
	s_nop 1
	v_cndmask_b32_e64 v160, v160, v162, s[0:1]
	v_cndmask_b32_e32 v162, 0, v213, vcc
	v_sub_f32_e32 v162, v160, v162
	v_mul_f32_e32 v160, 0xbfb8aa3b, v24
	v_exp_f32_e32 v160, v160
	v_cvt_pk_bf16_f32 v161, v161, v162
	v_add_f32_e32 v160, 1.0, v160
	v_rcp_f32_e32 v160, v160
	s_nop 0
	v_fma_f32 v160, v160, v156, v128
	v_cmp_gt_f32_e32 vcc, s33, v160
	s_nop 1
	v_cndmask_b32_e64 v163, 0, 32, vcc
	v_ldexp_f32 v160, v160, v163
	v_log_f32_e32 v160, v160
	s_nop 0
	v_mul_f32_e32 v163, 0x3f317217, v160
	v_fma_f32 v163, v160, s97, -v163
	v_fmac_f32_e32 v163, 0x3377d1cf, v160
	v_fmac_f32_e32 v163, 0x3f317217, v160
	v_cmp_lt_f32_e64 s[0:1], |v160|, s2
	s_nop 1
	v_cndmask_b32_e64 v160, v160, v163, s[0:1]
	v_cndmask_b32_e32 v163, 0, v213, vcc
	v_sub_f32_e32 v163, v160, v163
	v_mul_f32_e32 v160, 0xbfb8aa3b, v25
	v_exp_f32_e32 v160, v160
	s_nop 0
	v_add_f32_e32 v160, 1.0, v160
	v_rcp_f32_e32 v160, v160
	s_nop 0
	v_fma_f32 v160, v160, v157, v129
	v_cmp_gt_f32_e32 vcc, s33, v160
	s_nop 1
	v_cndmask_b32_e64 v164, 0, 32, vcc
	v_ldexp_f32 v160, v160, v164
	v_log_f32_e32 v160, v160
	s_nop 0
	v_mul_f32_e32 v164, 0x3f317217, v160
	v_fma_f32 v164, v160, s97, -v164
	v_fmac_f32_e32 v164, 0x3377d1cf, v160
	v_fmac_f32_e32 v164, 0x3f317217, v160
	v_cmp_lt_f32_e64 s[0:1], |v160|, s2
	s_nop 1
	v_cndmask_b32_e64 v160, v160, v164, s[0:1]
	v_cndmask_b32_e32 v164, 0, v213, vcc
	v_sub_f32_e32 v164, v160, v164
	v_mul_f32_e32 v160, 0xbfb8aa3b, v26
	v_exp_f32_e32 v160, v160
	v_cvt_pk_bf16_f32 v162, v163, v164
	v_add_f32_e32 v160, 1.0, v160
	v_rcp_f32_e32 v160, v160
	s_nop 0
	v_fma_f32 v160, v160, v159, v130
	v_cmp_gt_f32_e32 vcc, s33, v160
	s_nop 1
	v_cndmask_b32_e64 v165, 0, 32, vcc
	v_ldexp_f32 v160, v160, v165
	v_log_f32_e32 v160, v160
	s_nop 0
	v_mul_f32_e32 v165, 0x3f317217, v160
	v_fma_f32 v165, v160, s97, -v165
	v_fmac_f32_e32 v165, 0x3377d1cf, v160
	v_fmac_f32_e32 v165, 0x3f317217, v160
	v_cmp_lt_f32_e64 s[0:1], |v160|, s2
	s_nop 1
	v_cndmask_b32_e64 v160, v160, v165, s[0:1]
	v_cndmask_b32_e32 v165, 0, v213, vcc
	v_sub_f32_e32 v165, v160, v165
	v_mul_f32_e32 v160, 0xbfb8aa3b, v27
	v_exp_f32_e32 v160, v160
	s_nop 0
	v_add_f32_e32 v160, 1.0, v160
	v_rcp_f32_e32 v160, v160
	s_nop 0
	v_fma_f32 v160, v160, v158, v131
	v_cmp_gt_f32_e32 vcc, s33, v160
	s_nop 1
	v_cndmask_b32_e64 v166, 0, 32, vcc
	v_ldexp_f32 v160, v160, v166
	v_log_f32_e32 v160, v160
	s_nop 0
	v_mul_f32_e32 v166, 0x3f317217, v160
	v_fma_f32 v166, v160, s97, -v166
	v_fmac_f32_e32 v166, 0x3377d1cf, v160
	v_fmac_f32_e32 v166, 0x3f317217, v160
	v_cmp_lt_f32_e64 s[0:1], |v160|, s2
	s_nop 1
	v_cndmask_b32_e64 v160, v160, v166, s[0:1]
	v_cndmask_b32_e32 v166, 0, v213, vcc
	s_mov_b64 s[0:1], 0x50000
	v_sub_f32_e32 v166, v160, v166
	v_cvt_pk_bf16_f32 v160, v152, v153
	v_lshl_add_u64 v[152:153], v[138:139], 0, s[0:1]
	v_cvt_pk_bf16_f32 v163, v165, v166
	v_lshl_add_u64 v[164:165], v[136:137], 0, v[152:153]
	global_store_dwordx4 v[164:165], v[160:163], off sc1
	s_nop 1
	v_mul_f32_e32 v160, 0xbfb8aa3b, v16
	v_exp_f32_e32 v160, v160
	s_nop 0
	v_add_f32_e32 v160, 1.0, v160
	v_rcp_f32_e32 v160, v160
	s_nop 0
	v_fma_f32 v132, v160, v150, v132
	v_cmp_gt_f32_e32 vcc, s33, v132
	v_or_b32_e32 v160, 0x80, v223
	s_nop 0
	v_cndmask_b32_e64 v150, 0, 32, vcc
	v_ldexp_f32 v132, v132, v150
	v_log_f32_e32 v132, v132
	s_nop 0
	v_mul_f32_e32 v150, 0x3f317217, v132
	v_fma_f32 v150, v132, s97, -v150
	v_fmac_f32_e32 v150, 0x3377d1cf, v132
	v_fmac_f32_e32 v150, 0x3f317217, v132
	v_cmp_lt_f32_e64 s[0:1], |v132|, s2
	s_nop 1
	v_cndmask_b32_e64 v132, v132, v150, s[0:1]
	v_cndmask_b32_e32 v150, 0, v213, vcc
	v_sub_f32_e32 v132, v132, v150
	v_mul_f32_e32 v150, 0xbfb8aa3b, v17
	v_exp_f32_e32 v150, v150
	s_nop 0
	v_add_f32_e32 v150, 1.0, v150
	v_rcp_f32_e32 v150, v150
	s_nop 0
	v_fma_f32 v133, v150, v151, v133
	v_cmp_gt_f32_e32 vcc, s33, v133
	s_nop 1
	v_cndmask_b32_e64 v150, 0, 32, vcc
	v_ldexp_f32 v133, v133, v150
	v_log_f32_e32 v133, v133
	s_nop 0
	v_mul_f32_e32 v150, 0x3f317217, v133
	v_fma_f32 v150, v133, s97, -v150
	v_fmac_f32_e32 v150, 0x3377d1cf, v133
	v_fmac_f32_e32 v150, 0x3f317217, v133
	v_cmp_lt_f32_e64 s[0:1], |v133|, s2
	s_nop 1
	v_cndmask_b32_e64 v133, v133, v150, s[0:1]
	v_cndmask_b32_e32 v150, 0, v213, vcc
	v_sub_f32_e32 v133, v133, v150
	v_mul_f32_e32 v150, 0xbfb8aa3b, v18
	v_exp_f32_e32 v150, v150
	s_nop 0
	v_add_f32_e32 v150, 1.0, v150
	v_rcp_f32_e32 v150, v150
	s_nop 0
	v_fma_f32 v134, v150, v154, v134
	v_cmp_gt_f32_e32 vcc, s33, v134
	s_nop 1
	v_cndmask_b32_e64 v150, 0, 32, vcc
	v_ldexp_f32 v134, v134, v150
	v_log_f32_e32 v134, v134
	s_nop 0
	v_mul_f32_e32 v150, 0x3f317217, v134
	v_fma_f32 v150, v134, s97, -v150
	v_fmac_f32_e32 v150, 0x3377d1cf, v134
	v_fmac_f32_e32 v150, 0x3f317217, v134
	v_cmp_lt_f32_e64 s[0:1], |v134|, s2
	s_nop 1
	v_cndmask_b32_e64 v134, v134, v150, s[0:1]
	v_cndmask_b32_e32 v150, 0, v213, vcc
	v_sub_f32_e32 v134, v134, v150
	v_mul_f32_e32 v150, 0xbfb8aa3b, v19
	v_exp_f32_e32 v150, v150
	s_nop 0
	v_add_f32_e32 v150, 1.0, v150
	v_rcp_f32_e32 v150, v150
	s_nop 0
	v_fmac_f32_e32 v135, v150, v155
	v_cmp_gt_f32_e32 vcc, s33, v135
	s_nop 1
	v_cndmask_b32_e64 v150, 0, 32, vcc
	v_ldexp_f32 v135, v135, v150
	v_log_f32_e32 v135, v135
	s_nop 0
	v_mul_f32_e32 v150, 0x3f317217, v135
	v_fma_f32 v150, v135, s97, -v150
	v_fmac_f32_e32 v150, 0x3377d1cf, v135
	v_fmac_f32_e32 v150, 0x3f317217, v135
	v_cmp_lt_f32_e64 s[0:1], |v135|, s2
	s_nop 1
	v_cndmask_b32_e64 v135, v135, v150, s[0:1]
	v_cndmask_b32_e32 v150, 0, v213, vcc
	v_sub_f32_e32 v135, v135, v150
	v_mul_f32_e32 v150, 0xbfb8aa3b, v8
	v_exp_f32_e32 v150, v150
	s_nop 0
	v_add_f32_e32 v150, 1.0, v150
	v_rcp_f32_e32 v150, v150
	s_nop 0
	v_fma_f32 v128, v150, v156, v128
	v_cmp_gt_f32_e32 vcc, s33, v128
	s_nop 1
	v_cndmask_b32_e64 v150, 0, 32, vcc
	v_ldexp_f32 v128, v128, v150
	v_log_f32_e32 v128, v128
	s_nop 0
	v_mul_f32_e32 v150, 0x3f317217, v128
	v_fma_f32 v150, v128, s97, -v150
	v_fmac_f32_e32 v150, 0x3377d1cf, v128
	v_fmac_f32_e32 v150, 0x3f317217, v128
	v_cmp_lt_f32_e64 s[0:1], |v128|, s2
	s_nop 1
	v_cndmask_b32_e64 v128, v128, v150, s[0:1]
	v_cndmask_b32_e32 v150, 0, v213, vcc
	v_sub_f32_e32 v150, v128, v150
	v_mul_f32_e32 v128, 0xbfb8aa3b, v9
	v_exp_f32_e32 v128, v128
	s_nop 0
	v_add_f32_e32 v128, 1.0, v128
	v_rcp_f32_e32 v128, v128
	s_nop 0
	v_fma_f32 v128, v128, v157, v129
	v_cmp_gt_f32_e32 vcc, s33, v128
	s_nop 1
	v_cndmask_b32_e64 v129, 0, 32, vcc
	v_ldexp_f32 v128, v128, v129
	v_log_f32_e32 v128, v128
	s_nop 0
	v_mul_f32_e32 v129, 0x3f317217, v128
	v_fma_f32 v129, v128, s97, -v129
	v_fmac_f32_e32 v129, 0x3377d1cf, v128
	v_fmac_f32_e32 v129, 0x3f317217, v128
	v_cmp_lt_f32_e64 s[0:1], |v128|, s2
	s_nop 1
	v_cndmask_b32_e64 v128, v128, v129, s[0:1]
	v_cndmask_b32_e32 v129, 0, v213, vcc
	v_sub_f32_e32 v151, v128, v129
	v_mul_f32_e32 v128, 0xbfb8aa3b, v10
	v_exp_f32_e32 v128, v128
	s_nop 0
	v_add_f32_e32 v128, 1.0, v128
	v_rcp_f32_e32 v128, v128
	s_nop 0
	v_fma_f32 v128, v128, v159, v130
	v_cmp_gt_f32_e32 vcc, s33, v128
	v_cvt_pk_bf16_f32 v130, v150, v151
	s_nop 0
	v_cndmask_b32_e64 v129, 0, 32, vcc
	v_ldexp_f32 v128, v128, v129
	v_log_f32_e32 v128, v128
	s_nop 0
	v_mul_f32_e32 v129, 0x3f317217, v128
	v_fma_f32 v129, v128, s97, -v129
	v_fmac_f32_e32 v129, 0x3377d1cf, v128
	v_fmac_f32_e32 v129, 0x3f317217, v128
	v_cmp_lt_f32_e64 s[0:1], |v128|, s2
	s_nop 1
	v_cndmask_b32_e64 v128, v128, v129, s[0:1]
	v_cndmask_b32_e32 v129, 0, v213, vcc
	v_sub_f32_e32 v154, v128, v129
	v_mul_f32_e32 v128, 0xbfb8aa3b, v11
	v_exp_f32_e32 v128, v128
	s_nop 0
	v_add_f32_e32 v128, 1.0, v128
	v_rcp_f32_e32 v128, v128
	s_nop 0
	v_fmac_f32_e32 v131, v128, v158
	v_cmp_gt_f32_e32 vcc, s33, v131
	s_nop 1
	v_cndmask_b32_e64 v128, 0, 32, vcc
	v_ldexp_f32 v128, v131, v128
	v_log_f32_e32 v128, v128
	s_nop 0
	v_mul_f32_e32 v129, 0x3f317217, v128
	v_fma_f32 v129, v128, s97, -v129
	v_fmac_f32_e32 v129, 0x3377d1cf, v128
	v_fmac_f32_e32 v129, 0x3f317217, v128
	v_cmp_lt_f32_e64 s[0:1], |v128|, s2
	s_nop 1
	v_cndmask_b32_e64 v128, v128, v129, s[0:1]
	v_cndmask_b32_e32 v129, 0, v213, vcc
	s_mov_b64 s[0:1], 0x58000
	v_sub_f32_e32 v131, v128, v129
	v_lshl_add_u64 v[150:151], v[138:139], 0, s[0:1]
	v_cvt_pk_bf16_f32 v128, v132, v133
	v_cvt_pk_bf16_f32 v129, v134, v135
	v_cvt_pk_bf16_f32 v131, v154, v131
	v_lshl_add_u64 v[132:133], v[136:137], 0, v[150:151]
	global_store_dwordx4 v[132:133], v[128:131], off sc1
	v_lshlrev_b32_e32 v132, 2, v160
	global_load_dwordx4 v[128:131], v132, s[42:43] offset:16
	s_nop 0
	global_load_dwordx4 v[132:135], v132, s[42:43]
	v_mul_f32_e32 v136, 0xbfb8aa3b, v116
	v_exp_f32_e32 v136, v136
	v_lshl_add_u64 v[138:139], s[8:9], 0, v[138:139]
	v_add_f32_e32 v136, 1.0, v136
	v_rcp_f32_e32 v136, v136
	s_waitcnt vmcnt(1)
	v_sub_f32_e32 v158, 1.0, v128
	s_waitcnt vmcnt(0)
	v_sub_f32_e32 v159, 1.0, v132
	v_fma_f32 v136, v136, v159, v132
	v_cmp_gt_f32_e32 vcc, s33, v136
	v_sub_f32_e32 v157, 1.0, v133
	v_sub_f32_e32 v156, 1.0, v134
	v_cndmask_b32_e64 v137, 0, 32, vcc
	v_ldexp_f32 v136, v136, v137
	v_log_f32_e32 v136, v136
	v_sub_f32_e32 v154, 1.0, v135
	v_mul_f32_e32 v137, 0x3f317217, v136
	v_fma_f32 v137, v136, s97, -v137
	v_fmac_f32_e32 v137, 0x3377d1cf, v136
	v_fmac_f32_e32 v137, 0x3f317217, v136
	v_cmp_lt_f32_e64 s[0:1], |v136|, s2
	s_nop 1
	v_cndmask_b32_e64 v136, v136, v137, s[0:1]
	v_cndmask_b32_e32 v137, 0, v213, vcc
	v_sub_f32_e32 v161, v136, v137
	v_mul_f32_e32 v136, 0xbfb8aa3b, v117
	v_exp_f32_e32 v136, v136
	s_nop 0
	v_add_f32_e32 v136, 1.0, v136
	v_rcp_f32_e32 v136, v136
	s_nop 0
	v_fma_f32 v136, v136, v157, v133
	v_cmp_gt_f32_e32 vcc, s33, v136
	s_nop 1
	v_cndmask_b32_e64 v137, 0, 32, vcc
	v_ldexp_f32 v136, v136, v137
	v_log_f32_e32 v136, v136
	s_nop 0
	v_mul_f32_e32 v137, 0x3f317217, v136
	v_fma_f32 v137, v136, s97, -v137
	v_fmac_f32_e32 v137, 0x3377d1cf, v136
	v_fmac_f32_e32 v137, 0x3f317217, v136
	v_cmp_lt_f32_e64 s[0:1], |v136|, s2
	s_nop 1
	v_cndmask_b32_e64 v136, v136, v137, s[0:1]
	v_cndmask_b32_e32 v137, 0, v213, vcc
	v_sub_f32_e32 v162, v136, v137
	v_mul_f32_e32 v136, 0xbfb8aa3b, v118
	v_exp_f32_e32 v136, v136
	v_cvt_pk_bf16_f32 v162, v161, v162
	v_add_f32_e32 v136, 1.0, v136
	v_rcp_f32_e32 v136, v136
	s_nop 0
	v_fma_f32 v136, v136, v156, v134
	v_cmp_gt_f32_e32 vcc, s33, v136
	s_nop 1
	v_cndmask_b32_e64 v137, 0, 32, vcc
	v_ldexp_f32 v136, v136, v137
	v_log_f32_e32 v136, v136
	s_nop 0
	v_mul_f32_e32 v137, 0x3f317217, v136
	v_fma_f32 v137, v136, s97, -v137
	v_fmac_f32_e32 v137, 0x3377d1cf, v136
	v_fmac_f32_e32 v137, 0x3f317217, v136
	v_cmp_lt_f32_e64 s[0:1], |v136|, s2
	s_nop 1
	v_cndmask_b32_e64 v136, v136, v137, s[0:1]
	v_cndmask_b32_e32 v137, 0, v213, vcc
	v_sub_f32_e32 v163, v136, v137
	v_mul_f32_e32 v136, 0xbfb8aa3b, v119
	v_exp_f32_e32 v136, v136
	s_nop 0
	v_add_f32_e32 v136, 1.0, v136
	v_rcp_f32_e32 v136, v136
	s_nop 0
	v_fma_f32 v136, v136, v154, v135
	v_cmp_gt_f32_e32 vcc, s33, v136
	s_nop 1
	v_cndmask_b32_e64 v137, 0, 32, vcc
	v_ldexp_f32 v136, v136, v137
	v_log_f32_e32 v136, v136
	s_nop 0
	v_mul_f32_e32 v137, 0x3f317217, v136
	v_fma_f32 v137, v136, s97, -v137
	v_fmac_f32_e32 v137, 0x3377d1cf, v136
	v_fmac_f32_e32 v137, 0x3f317217, v136
	v_cmp_lt_f32_e64 s[0:1], |v136|, s2
	s_nop 1
	v_cndmask_b32_e64 v136, v136, v137, s[0:1]
	v_cndmask_b32_e32 v137, 0, v213, vcc
	v_sub_f32_e32 v164, v136, v137
	v_mul_f32_e32 v136, 0xbfb8aa3b, v108
	v_exp_f32_e32 v136, v136
	v_cvt_pk_bf16_f32 v163, v163, v164
	v_add_f32_e32 v136, 1.0, v136
	v_rcp_f32_e32 v136, v136
	s_nop 0
	v_fma_f32 v136, v136, v158, v128
	v_cmp_gt_f32_e32 vcc, s33, v136
	s_nop 1
	v_cndmask_b32_e64 v137, 0, 32, vcc
	v_ldexp_f32 v136, v136, v137
	v_log_f32_e32 v136, v136
	s_nop 0
	v_mul_f32_e32 v137, 0x3f317217, v136
	v_fma_f32 v137, v136, s97, -v137
	v_fmac_f32_e32 v137, 0x3377d1cf, v136
	v_fmac_f32_e32 v137, 0x3f317217, v136
	v_cmp_lt_f32_e64 s[0:1], |v136|, s2
	s_nop 1
	v_cndmask_b32_e64 v136, v136, v137, s[0:1]
	v_cndmask_b32_e32 v137, 0, v213, vcc
	v_sub_f32_e32 v165, v136, v137
	v_mul_f32_e32 v136, 0xbfb8aa3b, v109
	v_exp_f32_e32 v136, v136
	s_nop 0
	v_add_f32_e32 v136, 1.0, v136
	v_rcp_f32_e32 v137, v136
	v_sub_f32_e32 v136, 1.0, v129
	v_fma_f32 v137, v137, v136, v129
	v_cmp_gt_f32_e32 vcc, s33, v137
	s_nop 1
	v_cndmask_b32_e64 v155, 0, 32, vcc
	v_ldexp_f32 v137, v137, v155
	v_log_f32_e32 v137, v137
	s_nop 0
	v_mul_f32_e32 v155, 0x3f317217, v137
	v_fma_f32 v155, v137, s97, -v155
	v_fmac_f32_e32 v155, 0x3377d1cf, v137
	v_fmac_f32_e32 v155, 0x3f317217, v137
	v_cmp_lt_f32_e64 s[0:1], |v137|, s2
	s_nop 1
	v_cndmask_b32_e64 v137, v137, v155, s[0:1]
	v_cndmask_b32_e32 v155, 0, v213, vcc
	v_sub_f32_e32 v166, v137, v155
	v_mul_f32_e32 v137, 0xbfb8aa3b, v110
	v_exp_f32_e32 v137, v137
	v_sub_f32_e32 v155, 1.0, v130
	v_cvt_pk_bf16_f32 v164, v165, v166
	v_add_f32_e32 v137, 1.0, v137
	v_rcp_f32_e32 v137, v137
	s_nop 0
	v_fma_f32 v137, v137, v155, v130
	v_cmp_gt_f32_e32 vcc, s33, v137
	s_nop 1
	v_cndmask_b32_e64 v167, 0, 32, vcc
	v_ldexp_f32 v137, v137, v167
	v_log_f32_e32 v137, v137
	s_nop 0
	v_mul_f32_e32 v167, 0x3f317217, v137
	v_fma_f32 v167, v137, s97, -v167
	v_fmac_f32_e32 v167, 0x3377d1cf, v137
	v_fmac_f32_e32 v167, 0x3f317217, v137
	v_cmp_lt_f32_e64 s[0:1], |v137|, s2
	s_nop 1
	v_cndmask_b32_e64 v137, v137, v167, s[0:1]
	v_cndmask_b32_e32 v167, 0, v213, vcc
	v_sub_f32_e32 v167, v137, v167
	v_mul_f32_e32 v137, 0xbfb8aa3b, v111
	v_exp_f32_e32 v137, v137
	s_nop 0
	v_add_f32_e32 v137, 1.0, v137
	v_rcp_f32_e32 v172, v137
	v_sub_f32_e32 v137, 1.0, v131
	v_fma_f32 v172, v172, v137, v131
	v_cmp_gt_f32_e32 vcc, s33, v172
	s_nop 1
	v_cndmask_b32_e64 v187, 0, 32, vcc
	v_ldexp_f32 v172, v172, v187
	v_log_f32_e32 v172, v172
	s_nop 0
	v_mul_f32_e32 v187, 0x3f317217, v172
	v_fma_f32 v187, v172, s97, -v187
	v_fmac_f32_e32 v187, 0x3377d1cf, v172
	v_fmac_f32_e32 v187, 0x3f317217, v172
	v_cmp_lt_f32_e64 s[0:1], |v172|, s2
	s_nop 1
	v_cndmask_b32_e64 v172, v172, v187, s[0:1]
	v_cndmask_b32_e32 v187, 0, v213, vcc
	v_sub_f32_e32 v172, v172, v187
	v_cvt_pk_bf16_f32 v165, v167, v172
	v_lshlrev_b32_e32 v172, 1, v160
	v_lshl_add_u64 v[138:139], v[138:139], 0, v[172:173]
	global_store_dwordx4 v[138:139], v[162:165], off sc1
	v_mul_f32_e32 v138, 0xbfb8aa3b, v100
	v_exp_f32_e32 v138, v138
	v_lshl_add_u64 v[142:143], v[142:143], 0, v[172:173]
	v_add_f32_e32 v138, 1.0, v138
	v_rcp_f32_e32 v138, v138
	s_nop 0
	v_fma_f32 v138, v138, v159, v132
	v_cmp_gt_f32_e32 vcc, s33, v138
	s_nop 1
	v_cndmask_b32_e64 v139, 0, 32, vcc
	v_ldexp_f32 v138, v138, v139
	v_log_f32_e32 v138, v138
	s_nop 0
	v_mul_f32_e32 v139, 0x3f317217, v138
	v_fma_f32 v139, v138, s97, -v139
	v_fmac_f32_e32 v139, 0x3377d1cf, v138
	v_fmac_f32_e32 v139, 0x3f317217, v138
	v_cmp_lt_f32_e64 s[0:1], |v138|, s2
	s_nop 1
	v_cndmask_b32_e64 v138, v138, v139, s[0:1]
	v_cndmask_b32_e32 v139, 0, v213, vcc
	v_sub_f32_e32 v138, v138, v139
	v_mul_f32_e32 v139, 0xbfb8aa3b, v101
	v_exp_f32_e32 v139, v139
	s_nop 0
	v_add_f32_e32 v139, 1.0, v139
	v_rcp_f32_e32 v139, v139
	s_nop 0
	v_fma_f32 v139, v139, v157, v133
	v_cmp_gt_f32_e32 vcc, s33, v139
	s_nop 1
	v_cndmask_b32_e64 v160, 0, 32, vcc
	v_ldexp_f32 v139, v139, v160
	v_log_f32_e32 v139, v139
	s_nop 0
	v_mul_f32_e32 v160, 0x3f317217, v139
	v_fma_f32 v160, v139, s97, -v160
	v_fmac_f32_e32 v160, 0x3377d1cf, v139
	v_fmac_f32_e32 v160, 0x3f317217, v139
	v_cmp_lt_f32_e64 s[0:1], |v139|, s2
	s_nop 1
	v_cndmask_b32_e64 v139, v139, v160, s[0:1]
	v_cndmask_b32_e32 v160, 0, v213, vcc
	v_sub_f32_e32 v139, v139, v160
	v_mul_f32_e32 v160, 0xbfb8aa3b, v102
	v_exp_f32_e32 v160, v160
	s_nop 0
	v_add_f32_e32 v160, 1.0, v160
	v_rcp_f32_e32 v160, v160
	s_nop 0
	v_fma_f32 v160, v160, v156, v134
	v_cmp_gt_f32_e32 vcc, s33, v160
	s_nop 1
	v_cndmask_b32_e64 v161, 0, 32, vcc
	v_ldexp_f32 v160, v160, v161
	v_log_f32_e32 v160, v160
	s_nop 0
	v_mul_f32_e32 v161, 0x3f317217, v160
	v_fma_f32 v161, v160, s97, -v161
	v_fmac_f32_e32 v161, 0x3377d1cf, v160
	v_fmac_f32_e32 v161, 0x3f317217, v160
	v_cmp_lt_f32_e64 s[0:1], |v160|, s2
	s_nop 1
	v_cndmask_b32_e64 v160, v160, v161, s[0:1]
	v_cndmask_b32_e32 v161, 0, v213, vcc
	v_sub_f32_e32 v161, v160, v161
	v_mul_f32_e32 v160, 0xbfb8aa3b, v103
	v_exp_f32_e32 v160, v160
	s_nop 0
	v_add_f32_e32 v160, 1.0, v160
	v_rcp_f32_e32 v160, v160
	s_nop 0
	v_fma_f32 v160, v160, v154, v135
	v_cmp_gt_f32_e32 vcc, s33, v160
	s_nop 1
	v_cndmask_b32_e64 v162, 0, 32, vcc
	v_ldexp_f32 v160, v160, v162
	v_log_f32_e32 v160, v160
	s_nop 0
	v_mul_f32_e32 v162, 0x3f317217, v160
	v_fma_f32 v162, v160, s97, -v162
	v_fmac_f32_e32 v162, 0x3377d1cf, v160
	v_fmac_f32_e32 v162, 0x3f317217, v160
	v_cmp_lt_f32_e64 s[0:1], |v160|, s2
	s_nop 1
	v_cndmask_b32_e64 v160, v160, v162, s[0:1]
	v_cndmask_b32_e32 v162, 0, v213, vcc
	v_sub_f32_e32 v162, v160, v162
	v_mul_f32_e32 v160, 0xbfb8aa3b, v92
	v_exp_f32_e32 v160, v160
	v_cvt_pk_bf16_f32 v161, v161, v162
	v_add_f32_e32 v160, 1.0, v160
	v_rcp_f32_e32 v160, v160
	s_nop 0
	v_fma_f32 v160, v160, v158, v128
	v_cmp_gt_f32_e32 vcc, s33, v160
	s_nop 1
	v_cndmask_b32_e64 v163, 0, 32, vcc
	v_ldexp_f32 v160, v160, v163
	v_log_f32_e32 v160, v160
	s_nop 0
	v_mul_f32_e32 v163, 0x3f317217, v160
	v_fma_f32 v163, v160, s97, -v163
	v_fmac_f32_e32 v163, 0x3377d1cf, v160
	v_fmac_f32_e32 v163, 0x3f317217, v160
	v_cmp_lt_f32_e64 s[0:1], |v160|, s2
	s_nop 1
	v_cndmask_b32_e64 v160, v160, v163, s[0:1]
	v_cndmask_b32_e32 v163, 0, v213, vcc
	v_sub_f32_e32 v163, v160, v163
	v_mul_f32_e32 v160, 0xbfb8aa3b, v93
	v_exp_f32_e32 v160, v160
	s_nop 0
	v_add_f32_e32 v160, 1.0, v160
	v_rcp_f32_e32 v160, v160
	s_nop 0
	v_fma_f32 v160, v160, v136, v129
	v_cmp_gt_f32_e32 vcc, s33, v160
	s_nop 1
	v_cndmask_b32_e64 v164, 0, 32, vcc
	v_ldexp_f32 v160, v160, v164
	v_log_f32_e32 v160, v160
	s_nop 0
	v_mul_f32_e32 v164, 0x3f317217, v160
	v_fma_f32 v164, v160, s97, -v164
	v_fmac_f32_e32 v164, 0x3377d1cf, v160
	v_fmac_f32_e32 v164, 0x3f317217, v160
	v_cmp_lt_f32_e64 s[0:1], |v160|, s2
	s_nop 1
	v_cndmask_b32_e64 v160, v160, v164, s[0:1]
	v_cndmask_b32_e32 v164, 0, v213, vcc
	v_sub_f32_e32 v164, v160, v164
	v_mul_f32_e32 v160, 0xbfb8aa3b, v94
	v_exp_f32_e32 v160, v160
	v_cvt_pk_bf16_f32 v162, v163, v164
	v_add_f32_e32 v160, 1.0, v160
	v_rcp_f32_e32 v160, v160
	s_nop 0
	v_fma_f32 v160, v160, v155, v130
	v_cmp_gt_f32_e32 vcc, s33, v160
	s_nop 1
	v_cndmask_b32_e64 v165, 0, 32, vcc
	v_ldexp_f32 v160, v160, v165
	v_log_f32_e32 v160, v160
	s_nop 0
	v_mul_f32_e32 v165, 0x3f317217, v160
	v_fma_f32 v165, v160, s97, -v165
	v_fmac_f32_e32 v165, 0x3377d1cf, v160
	v_fmac_f32_e32 v165, 0x3f317217, v160
	v_cmp_lt_f32_e64 s[0:1], |v160|, s2
	s_nop 1
	v_cndmask_b32_e64 v160, v160, v165, s[0:1]
	v_cndmask_b32_e32 v165, 0, v213, vcc
	v_sub_f32_e32 v165, v160, v165
	v_mul_f32_e32 v160, 0xbfb8aa3b, v95
	v_exp_f32_e32 v160, v160
	s_nop 0
	v_add_f32_e32 v160, 1.0, v160
	v_rcp_f32_e32 v160, v160
	s_nop 0
	v_fma_f32 v160, v160, v137, v131
	v_cmp_gt_f32_e32 vcc, s33, v160
	s_nop 1
	v_cndmask_b32_e64 v166, 0, 32, vcc
	v_ldexp_f32 v160, v160, v166
	v_log_f32_e32 v160, v160
	s_nop 0
	v_mul_f32_e32 v166, 0x3f317217, v160
	v_fma_f32 v166, v160, s97, -v166
	v_fmac_f32_e32 v166, 0x3377d1cf, v160
	v_fmac_f32_e32 v166, 0x3f317217, v160
	v_cmp_lt_f32_e64 s[0:1], |v160|, s2
	s_nop 1
	v_cndmask_b32_e64 v160, v160, v166, s[0:1]
	v_cndmask_b32_e32 v166, 0, v213, vcc
	v_sub_f32_e32 v166, v160, v166
	v_cvt_pk_bf16_f32 v160, v138, v139
	v_lshl_add_u64 v[138:139], s[8:9], 0, v[140:141]
	v_cvt_pk_bf16_f32 v163, v165, v166
	v_lshl_add_u64 v[138:139], v[138:139], 0, v[172:173]
	global_store_dwordx4 v[138:139], v[160:163], off sc1
	v_mul_f32_e32 v138, 0xbfb8aa3b, v84
	v_exp_f32_e32 v138, v138
	s_nop 0
	v_add_f32_e32 v138, 1.0, v138
	v_rcp_f32_e32 v138, v138
	s_nop 0
	v_fma_f32 v138, v138, v159, v132
	v_cmp_gt_f32_e32 vcc, s33, v138
	s_nop 1
	v_cndmask_b32_e64 v139, 0, 32, vcc
	v_ldexp_f32 v138, v138, v139
	v_log_f32_e32 v138, v138
	s_nop 0
	v_mul_f32_e32 v139, 0x3f317217, v138
	v_fma_f32 v139, v138, s97, -v139
	v_fmac_f32_e32 v139, 0x3377d1cf, v138
	v_fmac_f32_e32 v139, 0x3f317217, v138
	v_cmp_lt_f32_e64 s[0:1], |v138|, s2
	s_nop 1
	v_cndmask_b32_e64 v138, v138, v139, s[0:1]
	v_cndmask_b32_e32 v139, 0, v213, vcc
	v_sub_f32_e32 v138, v138, v139
	v_mul_f32_e32 v139, 0xbfb8aa3b, v85
	v_exp_f32_e32 v139, v139
	s_nop 0
	v_add_f32_e32 v139, 1.0, v139
	v_rcp_f32_e32 v139, v139
	s_nop 0
	v_fma_f32 v139, v139, v157, v133
	v_cmp_gt_f32_e32 vcc, s33, v139
	s_nop 1
	v_cndmask_b32_e64 v140, 0, 32, vcc
	v_ldexp_f32 v139, v139, v140
	v_log_f32_e32 v139, v139
	s_nop 0
	v_mul_f32_e32 v140, 0x3f317217, v139
	v_fma_f32 v140, v139, s97, -v140
	v_fmac_f32_e32 v140, 0x3377d1cf, v139
	v_fmac_f32_e32 v140, 0x3f317217, v139
	v_cmp_lt_f32_e64 s[0:1], |v139|, s2
	s_nop 1
	v_cndmask_b32_e64 v139, v139, v140, s[0:1]
	v_cndmask_b32_e32 v140, 0, v213, vcc
	v_sub_f32_e32 v139, v139, v140
	v_mul_f32_e32 v140, 0xbfb8aa3b, v86
	v_exp_f32_e32 v140, v140
	v_cvt_pk_bf16_f32 v138, v138, v139
	v_add_f32_e32 v140, 1.0, v140
	v_rcp_f32_e32 v140, v140
	s_nop 0
	v_fma_f32 v140, v140, v156, v134
	v_cmp_gt_f32_e32 vcc, s33, v140
	s_nop 1
	v_cndmask_b32_e64 v141, 0, 32, vcc
	v_ldexp_f32 v140, v140, v141
	v_log_f32_e32 v140, v140
	s_nop 0
	v_mul_f32_e32 v141, 0x3f317217, v140
	v_fma_f32 v141, v140, s97, -v141
	v_fmac_f32_e32 v141, 0x3377d1cf, v140
	v_fmac_f32_e32 v141, 0x3f317217, v140
	v_cmp_lt_f32_e64 s[0:1], |v140|, s2
	s_nop 1
	v_cndmask_b32_e64 v140, v140, v141, s[0:1]
	v_cndmask_b32_e32 v141, 0, v213, vcc
	v_sub_f32_e32 v140, v140, v141
	v_mul_f32_e32 v141, 0xbfb8aa3b, v87
	v_exp_f32_e32 v141, v141
	s_nop 0
	v_add_f32_e32 v141, 1.0, v141
	v_rcp_f32_e32 v141, v141
	s_nop 0
	v_fma_f32 v141, v141, v154, v135
	v_cmp_gt_f32_e32 vcc, s33, v141
	s_nop 1
	v_cndmask_b32_e64 v160, 0, 32, vcc
	v_ldexp_f32 v141, v141, v160
	v_log_f32_e32 v141, v141
	s_nop 0
	v_mul_f32_e32 v160, 0x3f317217, v141
	v_fma_f32 v160, v141, s97, -v160
	v_fmac_f32_e32 v160, 0x3377d1cf, v141
	v_fmac_f32_e32 v160, 0x3f317217, v141
	v_cmp_lt_f32_e64 s[0:1], |v141|, s2
	s_nop 1
	v_cndmask_b32_e64 v141, v141, v160, s[0:1]
	v_cndmask_b32_e32 v160, 0, v213, vcc
	v_sub_f32_e32 v141, v141, v160
	v_mul_f32_e32 v160, 0xbfb8aa3b, v76
	v_exp_f32_e32 v160, v160
	v_cvt_pk_bf16_f32 v139, v140, v141
	v_add_f32_e32 v160, 1.0, v160
	v_rcp_f32_e32 v160, v160
	s_nop 0
	v_fma_f32 v160, v160, v158, v128
	v_cmp_gt_f32_e32 vcc, s33, v160
	s_nop 1
	v_cndmask_b32_e64 v161, 0, 32, vcc
	v_ldexp_f32 v160, v160, v161
	v_log_f32_e32 v160, v160
	s_nop 0
	v_mul_f32_e32 v161, 0x3f317217, v160
	v_fma_f32 v161, v160, s97, -v161
	v_fmac_f32_e32 v161, 0x3377d1cf, v160
	v_fmac_f32_e32 v161, 0x3f317217, v160
	v_cmp_lt_f32_e64 s[0:1], |v160|, s2
	s_nop 1
	v_cndmask_b32_e64 v160, v160, v161, s[0:1]
	v_cndmask_b32_e32 v161, 0, v213, vcc
	v_sub_f32_e32 v160, v160, v161
	v_mul_f32_e32 v161, 0xbfb8aa3b, v77
	v_exp_f32_e32 v161, v161
	s_nop 0
	v_add_f32_e32 v161, 1.0, v161
	v_rcp_f32_e32 v161, v161
	s_nop 0
	v_fma_f32 v161, v161, v136, v129
	v_cmp_gt_f32_e32 vcc, s33, v161
	s_nop 1
	v_cndmask_b32_e64 v162, 0, 32, vcc
	v_ldexp_f32 v161, v161, v162
	v_log_f32_e32 v161, v161
	s_nop 0
	v_mul_f32_e32 v162, 0x3f317217, v161
	v_fma_f32 v162, v161, s97, -v162
	v_fmac_f32_e32 v162, 0x3377d1cf, v161
	v_fmac_f32_e32 v162, 0x3f317217, v161
	v_cmp_lt_f32_e64 s[0:1], |v161|, s2
	s_nop 1
	v_cndmask_b32_e64 v161, v161, v162, s[0:1]
	v_cndmask_b32_e32 v162, 0, v213, vcc
	v_sub_f32_e32 v161, v161, v162
	v_mul_f32_e32 v162, 0xbfb8aa3b, v78
	v_exp_f32_e32 v162, v162
	v_cvt_pk_bf16_f32 v140, v160, v161
	v_add_f32_e32 v162, 1.0, v162
	v_rcp_f32_e32 v162, v162
	s_nop 0
	v_fma_f32 v162, v162, v155, v130
	v_cmp_gt_f32_e32 vcc, s33, v162
	s_nop 1
	v_cndmask_b32_e64 v163, 0, 32, vcc
	v_ldexp_f32 v162, v162, v163
	v_log_f32_e32 v162, v162
	s_nop 0
	v_mul_f32_e32 v163, 0x3f317217, v162
	v_fma_f32 v163, v162, s97, -v163
	v_fmac_f32_e32 v163, 0x3377d1cf, v162
	v_fmac_f32_e32 v163, 0x3f317217, v162
	v_cmp_lt_f32_e64 s[0:1], |v162|, s2
	s_nop 1
	v_cndmask_b32_e64 v162, v162, v163, s[0:1]
	v_cndmask_b32_e32 v163, 0, v213, vcc
	v_sub_f32_e32 v162, v162, v163
	v_mul_f32_e32 v163, 0xbfb8aa3b, v79
	v_exp_f32_e32 v163, v163
	s_nop 0
	v_add_f32_e32 v163, 1.0, v163
	v_rcp_f32_e32 v163, v163
	s_nop 0
	v_fma_f32 v163, v163, v137, v131
	v_cmp_gt_f32_e32 vcc, s33, v163
	s_nop 1
	v_cndmask_b32_e64 v164, 0, 32, vcc
	v_ldexp_f32 v163, v163, v164
	v_log_f32_e32 v163, v163
	s_nop 0
	v_mul_f32_e32 v164, 0x3f317217, v163
	v_fma_f32 v164, v163, s97, -v164
	v_fmac_f32_e32 v164, 0x3377d1cf, v163
	v_fmac_f32_e32 v164, 0x3f317217, v163
	v_cmp_lt_f32_e64 s[0:1], |v163|, s2
	s_nop 1
	v_cndmask_b32_e64 v163, v163, v164, s[0:1]
	v_cndmask_b32_e32 v164, 0, v213, vcc
	v_sub_f32_e32 v163, v163, v164
	v_cvt_pk_bf16_f32 v141, v162, v163
	global_store_dwordx4 v[142:143], v[138:141], off sc1
	s_nop 1
	v_mul_f32_e32 v138, 0xbfb8aa3b, v68
	v_exp_f32_e32 v138, v138
	s_nop 0
	v_add_f32_e32 v138, 1.0, v138
	v_rcp_f32_e32 v138, v138
	s_nop 0
	v_fma_f32 v138, v138, v159, v132
	v_cmp_gt_f32_e32 vcc, s33, v138
	s_nop 1
	v_cndmask_b32_e64 v139, 0, 32, vcc
	v_ldexp_f32 v138, v138, v139
	v_log_f32_e32 v138, v138
	s_nop 0
	v_mul_f32_e32 v139, 0x3f317217, v138
	v_fma_f32 v139, v138, s97, -v139
	v_fmac_f32_e32 v139, 0x3377d1cf, v138
	v_fmac_f32_e32 v139, 0x3f317217, v138
	v_cmp_lt_f32_e64 s[0:1], |v138|, s2
	s_nop 1
	v_cndmask_b32_e64 v138, v138, v139, s[0:1]
	v_cndmask_b32_e32 v139, 0, v213, vcc
	v_sub_f32_e32 v138, v138, v139
	v_mul_f32_e32 v139, 0xbfb8aa3b, v69
	v_exp_f32_e32 v139, v139
	s_nop 0
	v_add_f32_e32 v139, 1.0, v139
	v_rcp_f32_e32 v139, v139
	s_nop 0
	v_fma_f32 v139, v139, v157, v133
	v_cmp_gt_f32_e32 vcc, s33, v139
	s_nop 1
	v_cndmask_b32_e64 v140, 0, 32, vcc
	v_ldexp_f32 v139, v139, v140
	v_log_f32_e32 v139, v139
	s_nop 0
	v_mul_f32_e32 v140, 0x3f317217, v139
	v_fma_f32 v140, v139, s97, -v140
	v_fmac_f32_e32 v140, 0x3377d1cf, v139
	v_fmac_f32_e32 v140, 0x3f317217, v139
	v_cmp_lt_f32_e64 s[0:1], |v139|, s2
	s_nop 1
	v_cndmask_b32_e64 v139, v139, v140, s[0:1]
	v_cndmask_b32_e32 v140, 0, v213, vcc
	v_sub_f32_e32 v139, v139, v140
	v_mul_f32_e32 v140, 0xbfb8aa3b, v70
	v_exp_f32_e32 v140, v140
	v_cvt_pk_bf16_f32 v138, v138, v139
	v_add_f32_e32 v140, 1.0, v140
	v_rcp_f32_e32 v140, v140
	s_nop 0
	v_fma_f32 v140, v140, v156, v134
	v_cmp_gt_f32_e32 vcc, s33, v140
	s_nop 1
	v_cndmask_b32_e64 v141, 0, 32, vcc
	v_ldexp_f32 v140, v140, v141
	v_log_f32_e32 v140, v140
	s_nop 0
	v_mul_f32_e32 v141, 0x3f317217, v140
	v_fma_f32 v141, v140, s97, -v141
	v_fmac_f32_e32 v141, 0x3377d1cf, v140
	v_fmac_f32_e32 v141, 0x3f317217, v140
	v_cmp_lt_f32_e64 s[0:1], |v140|, s2
	s_nop 1
	v_cndmask_b32_e64 v140, v140, v141, s[0:1]
	v_cndmask_b32_e32 v141, 0, v213, vcc
	v_sub_f32_e32 v140, v140, v141
	v_mul_f32_e32 v141, 0xbfb8aa3b, v71
	v_exp_f32_e32 v141, v141
	s_nop 0
	v_add_f32_e32 v141, 1.0, v141
	v_rcp_f32_e32 v141, v141
	s_nop 0
	v_fma_f32 v141, v141, v154, v135
	v_cmp_gt_f32_e32 vcc, s33, v141
	s_nop 1
	v_cndmask_b32_e64 v142, 0, 32, vcc
	v_ldexp_f32 v141, v141, v142
	v_log_f32_e32 v141, v141
	s_nop 0
	v_mul_f32_e32 v142, 0x3f317217, v141
	v_fma_f32 v142, v141, s97, -v142
	v_fmac_f32_e32 v142, 0x3377d1cf, v141
	v_fmac_f32_e32 v142, 0x3f317217, v141
	v_cmp_lt_f32_e64 s[0:1], |v141|, s2
	s_nop 1
	v_cndmask_b32_e64 v141, v141, v142, s[0:1]
	v_cndmask_b32_e32 v142, 0, v213, vcc
	v_sub_f32_e32 v141, v141, v142
	v_mul_f32_e32 v142, 0xbfb8aa3b, v64
	v_exp_f32_e32 v142, v142
	v_cvt_pk_bf16_f32 v139, v140, v141
	v_add_f32_e32 v142, 1.0, v142
	v_rcp_f32_e32 v142, v142
	s_nop 0
	v_fma_f32 v142, v142, v158, v128
	v_cmp_gt_f32_e32 vcc, s33, v142
	s_nop 1
	v_cndmask_b32_e64 v143, 0, 32, vcc
	v_ldexp_f32 v142, v142, v143
	v_log_f32_e32 v142, v142
	s_nop 0
	v_mul_f32_e32 v143, 0x3f317217, v142
	v_fma_f32 v143, v142, s97, -v143
	v_fmac_f32_e32 v143, 0x3377d1cf, v142
	v_fmac_f32_e32 v143, 0x3f317217, v142
	v_cmp_lt_f32_e64 s[0:1], |v142|, s2
	s_nop 1
	v_cndmask_b32_e64 v142, v142, v143, s[0:1]
	v_cndmask_b32_e32 v143, 0, v213, vcc
	v_sub_f32_e32 v142, v142, v143
	v_mul_f32_e32 v143, 0xbfb8aa3b, v65
	v_exp_f32_e32 v143, v143
	s_nop 0
	v_add_f32_e32 v143, 1.0, v143
	v_rcp_f32_e32 v143, v143
	s_nop 0
	v_fma_f32 v143, v143, v136, v129
	v_cmp_gt_f32_e32 vcc, s33, v143
	s_nop 1
	v_cndmask_b32_e64 v160, 0, 32, vcc
	v_ldexp_f32 v143, v143, v160
	v_log_f32_e32 v143, v143
	s_nop 0
	v_mul_f32_e32 v160, 0x3f317217, v143
	v_fma_f32 v160, v143, s97, -v160
	v_fmac_f32_e32 v160, 0x3377d1cf, v143
	v_fmac_f32_e32 v160, 0x3f317217, v143
	v_cmp_lt_f32_e64 s[0:1], |v143|, s2
	s_nop 1
	v_cndmask_b32_e64 v143, v143, v160, s[0:1]
	v_cndmask_b32_e32 v160, 0, v213, vcc
	v_sub_f32_e32 v143, v143, v160
	v_mul_f32_e32 v160, 0xbfb8aa3b, v66
	v_exp_f32_e32 v160, v160
	v_cvt_pk_bf16_f32 v140, v142, v143
	v_lshl_add_u64 v[142:143], s[8:9], 0, v[144:145]
	v_lshl_add_u64 v[142:143], v[142:143], 0, v[172:173]
	v_add_f32_e32 v160, 1.0, v160
	v_rcp_f32_e32 v160, v160
	s_nop 0
	v_fma_f32 v160, v160, v155, v130
	v_cmp_gt_f32_e32 vcc, s33, v160
	s_nop 1
	v_cndmask_b32_e64 v161, 0, 32, vcc
	v_ldexp_f32 v160, v160, v161
	v_log_f32_e32 v160, v160
	s_nop 0
	v_mul_f32_e32 v161, 0x3f317217, v160
	v_fma_f32 v161, v160, s97, -v161
	v_fmac_f32_e32 v161, 0x3377d1cf, v160
	v_fmac_f32_e32 v161, 0x3f317217, v160
	v_cmp_lt_f32_e64 s[0:1], |v160|, s2
	s_nop 1
	v_cndmask_b32_e64 v160, v160, v161, s[0:1]
	v_cndmask_b32_e32 v161, 0, v213, vcc
	v_sub_f32_e32 v160, v160, v161
	v_mul_f32_e32 v161, 0xbfb8aa3b, v67
	v_exp_f32_e32 v161, v161
	s_nop 0
	v_add_f32_e32 v161, 1.0, v161
	v_rcp_f32_e32 v161, v161
	s_nop 0
	v_fma_f32 v161, v161, v137, v131
	v_cmp_gt_f32_e32 vcc, s33, v161
	s_nop 1
	v_cndmask_b32_e64 v162, 0, 32, vcc
	v_ldexp_f32 v161, v161, v162
	v_log_f32_e32 v161, v161
	s_nop 0
	v_mul_f32_e32 v162, 0x3f317217, v161
	v_fma_f32 v162, v161, s97, -v162
	v_fmac_f32_e32 v162, 0x3377d1cf, v161
	v_fmac_f32_e32 v162, 0x3f317217, v161
	v_cmp_lt_f32_e64 s[0:1], |v161|, s2
	s_nop 1
	v_cndmask_b32_e64 v161, v161, v162, s[0:1]
	v_cndmask_b32_e32 v162, 0, v213, vcc
	v_sub_f32_e32 v161, v161, v162
	v_cvt_pk_bf16_f32 v141, v160, v161
	global_store_dwordx4 v[142:143], v[138:141], off sc1
	s_nop 1
	v_mul_f32_e32 v138, 0xbfb8aa3b, v52
	v_exp_f32_e32 v138, v138
	s_nop 0
	v_add_f32_e32 v138, 1.0, v138
	v_rcp_f32_e32 v138, v138
	s_nop 0
	v_fma_f32 v138, v138, v159, v132
	v_cmp_gt_f32_e32 vcc, s33, v138
	s_nop 1
	v_cndmask_b32_e64 v139, 0, 32, vcc
	v_ldexp_f32 v138, v138, v139
	v_log_f32_e32 v138, v138
	s_nop 0
	v_mul_f32_e32 v139, 0x3f317217, v138
	v_fma_f32 v139, v138, s97, -v139
	v_fmac_f32_e32 v139, 0x3377d1cf, v138
	v_fmac_f32_e32 v139, 0x3f317217, v138
	v_cmp_lt_f32_e64 s[0:1], |v138|, s2
	s_nop 1
	v_cndmask_b32_e64 v138, v138, v139, s[0:1]
	v_cndmask_b32_e32 v139, 0, v213, vcc
	v_sub_f32_e32 v138, v138, v139
	v_mul_f32_e32 v139, 0xbfb8aa3b, v53
	v_exp_f32_e32 v139, v139
	s_nop 0
	v_add_f32_e32 v139, 1.0, v139
	v_rcp_f32_e32 v139, v139
	s_nop 0
	v_fma_f32 v139, v139, v157, v133
	v_cmp_gt_f32_e32 vcc, s33, v139
	s_nop 1
	v_cndmask_b32_e64 v140, 0, 32, vcc
	v_ldexp_f32 v139, v139, v140
	v_log_f32_e32 v139, v139
	s_nop 0
	v_mul_f32_e32 v140, 0x3f317217, v139
	v_fma_f32 v140, v139, s97, -v140
	v_fmac_f32_e32 v140, 0x3377d1cf, v139
	v_fmac_f32_e32 v140, 0x3f317217, v139
	v_cmp_lt_f32_e64 s[0:1], |v139|, s2
	s_nop 1
	v_cndmask_b32_e64 v139, v139, v140, s[0:1]
	v_cndmask_b32_e32 v140, 0, v213, vcc
	v_sub_f32_e32 v139, v139, v140
	v_mul_f32_e32 v140, 0xbfb8aa3b, v54
	v_exp_f32_e32 v140, v140
	v_cvt_pk_bf16_f32 v138, v138, v139
	v_add_f32_e32 v140, 1.0, v140
	v_rcp_f32_e32 v140, v140
	s_nop 0
	v_fma_f32 v140, v140, v156, v134
	v_cmp_gt_f32_e32 vcc, s33, v140
	s_nop 1
	v_cndmask_b32_e64 v141, 0, 32, vcc
	v_ldexp_f32 v140, v140, v141
	v_log_f32_e32 v140, v140
	s_nop 0
	v_mul_f32_e32 v141, 0x3f317217, v140
	v_fma_f32 v141, v140, s97, -v141
	v_fmac_f32_e32 v141, 0x3377d1cf, v140
	v_fmac_f32_e32 v141, 0x3f317217, v140
	v_cmp_lt_f32_e64 s[0:1], |v140|, s2
	s_nop 1
	v_cndmask_b32_e64 v140, v140, v141, s[0:1]
	v_cndmask_b32_e32 v141, 0, v213, vcc
	v_sub_f32_e32 v140, v140, v141
	v_mul_f32_e32 v141, 0xbfb8aa3b, v55
	v_exp_f32_e32 v141, v141
	s_nop 0
	v_add_f32_e32 v141, 1.0, v141
	v_rcp_f32_e32 v141, v141
	s_nop 0
	v_fma_f32 v141, v141, v154, v135
	v_cmp_gt_f32_e32 vcc, s33, v141
	s_nop 1
	v_cndmask_b32_e64 v142, 0, 32, vcc
	v_ldexp_f32 v141, v141, v142
	v_log_f32_e32 v141, v141
	s_nop 0
	v_mul_f32_e32 v142, 0x3f317217, v141
	v_fma_f32 v142, v141, s97, -v142
	v_fmac_f32_e32 v142, 0x3377d1cf, v141
	v_fmac_f32_e32 v142, 0x3f317217, v141
	v_cmp_lt_f32_e64 s[0:1], |v141|, s2
	s_nop 1
	v_cndmask_b32_e64 v141, v141, v142, s[0:1]
	v_cndmask_b32_e32 v142, 0, v213, vcc
	v_sub_f32_e32 v141, v141, v142
	v_mul_f32_e32 v142, 0xbfb8aa3b, v44
	v_exp_f32_e32 v142, v142
	v_cvt_pk_bf16_f32 v139, v140, v141
	v_add_f32_e32 v142, 1.0, v142
	v_rcp_f32_e32 v142, v142
	s_nop 0
	v_fma_f32 v142, v142, v158, v128
	v_cmp_gt_f32_e32 vcc, s33, v142
	s_nop 1
	v_cndmask_b32_e64 v143, 0, 32, vcc
	v_ldexp_f32 v142, v142, v143
	v_log_f32_e32 v142, v142
	s_nop 0
	v_mul_f32_e32 v143, 0x3f317217, v142
	v_fma_f32 v143, v142, s97, -v143
	v_fmac_f32_e32 v143, 0x3377d1cf, v142
	v_fmac_f32_e32 v143, 0x3f317217, v142
	v_cmp_lt_f32_e64 s[0:1], |v142|, s2
	s_nop 1
	v_cndmask_b32_e64 v142, v142, v143, s[0:1]
	v_cndmask_b32_e32 v143, 0, v213, vcc
	v_sub_f32_e32 v142, v142, v143
	v_mul_f32_e32 v143, 0xbfb8aa3b, v45
	v_exp_f32_e32 v143, v143
	s_nop 0
	v_add_f32_e32 v143, 1.0, v143
	v_rcp_f32_e32 v143, v143
	s_nop 0
	v_fma_f32 v143, v143, v136, v129
	v_cmp_gt_f32_e32 vcc, s33, v143
	s_nop 1
	v_cndmask_b32_e64 v144, 0, 32, vcc
	v_ldexp_f32 v143, v143, v144
	v_log_f32_e32 v143, v143
	s_nop 0
	v_mul_f32_e32 v144, 0x3f317217, v143
	v_fma_f32 v144, v143, s97, -v144
	v_fmac_f32_e32 v144, 0x3377d1cf, v143
	v_fmac_f32_e32 v144, 0x3f317217, v143
	v_cmp_lt_f32_e64 s[0:1], |v143|, s2
	s_nop 1
	v_cndmask_b32_e64 v143, v143, v144, s[0:1]
	v_cndmask_b32_e32 v144, 0, v213, vcc
	v_sub_f32_e32 v143, v143, v144
	v_mul_f32_e32 v144, 0xbfb8aa3b, v46
	v_exp_f32_e32 v144, v144
	v_cvt_pk_bf16_f32 v140, v142, v143
	v_lshl_add_u64 v[142:143], s[8:9], 0, v[146:147]
	v_lshl_add_u64 v[142:143], v[142:143], 0, v[172:173]
	v_add_f32_e32 v144, 1.0, v144
	v_rcp_f32_e32 v144, v144
	s_nop 0
	v_fma_f32 v144, v144, v155, v130
	v_cmp_gt_f32_e32 vcc, s33, v144
	s_nop 1
	v_cndmask_b32_e64 v145, 0, 32, vcc
	v_ldexp_f32 v144, v144, v145
	v_log_f32_e32 v144, v144
	s_nop 0
	v_mul_f32_e32 v145, 0x3f317217, v144
	v_fma_f32 v145, v144, s97, -v145
	v_fmac_f32_e32 v145, 0x3377d1cf, v144
	v_fmac_f32_e32 v145, 0x3f317217, v144
	v_cmp_lt_f32_e64 s[0:1], |v144|, s2
	s_nop 1
	v_cndmask_b32_e64 v144, v144, v145, s[0:1]
	v_cndmask_b32_e32 v145, 0, v213, vcc
	v_sub_f32_e32 v144, v144, v145
	v_mul_f32_e32 v145, 0xbfb8aa3b, v47
	v_exp_f32_e32 v145, v145
	s_nop 0
	v_add_f32_e32 v145, 1.0, v145
	v_rcp_f32_e32 v145, v145
	s_nop 0
	v_fma_f32 v145, v145, v137, v131
	v_cmp_gt_f32_e32 vcc, s33, v145
	s_nop 1
	v_cndmask_b32_e64 v160, 0, 32, vcc
	v_ldexp_f32 v145, v145, v160
	v_log_f32_e32 v145, v145
	s_nop 0
	v_mul_f32_e32 v160, 0x3f317217, v145
	v_fma_f32 v160, v145, s97, -v160
	v_fmac_f32_e32 v160, 0x3377d1cf, v145
	v_fmac_f32_e32 v160, 0x3f317217, v145
	v_cmp_lt_f32_e64 s[0:1], |v145|, s2
	s_nop 1
	v_cndmask_b32_e64 v145, v145, v160, s[0:1]
	v_cndmask_b32_e32 v160, 0, v213, vcc
	v_sub_f32_e32 v145, v145, v160
	v_cvt_pk_bf16_f32 v141, v144, v145
	global_store_dwordx4 v[142:143], v[138:141], off sc1
	s_nop 1
	v_mul_f32_e32 v138, 0xbfb8aa3b, v36
	v_exp_f32_e32 v138, v138
	s_nop 0
	v_add_f32_e32 v138, 1.0, v138
	v_rcp_f32_e32 v138, v138
	s_nop 0
	v_fma_f32 v138, v138, v159, v132
	v_cmp_gt_f32_e32 vcc, s33, v138
	s_nop 1
	v_cndmask_b32_e64 v139, 0, 32, vcc
	v_ldexp_f32 v138, v138, v139
	v_log_f32_e32 v138, v138
	s_nop 0
	v_mul_f32_e32 v139, 0x3f317217, v138
	v_fma_f32 v139, v138, s97, -v139
	v_fmac_f32_e32 v139, 0x3377d1cf, v138
	v_fmac_f32_e32 v139, 0x3f317217, v138
	v_cmp_lt_f32_e64 s[0:1], |v138|, s2
	s_nop 1
	v_cndmask_b32_e64 v138, v138, v139, s[0:1]
	v_cndmask_b32_e32 v139, 0, v213, vcc
	v_sub_f32_e32 v138, v138, v139
	v_mul_f32_e32 v139, 0xbfb8aa3b, v37
	v_exp_f32_e32 v139, v139
	s_nop 0
	v_add_f32_e32 v139, 1.0, v139
	v_rcp_f32_e32 v139, v139
	s_nop 0
	v_fma_f32 v139, v139, v157, v133
	v_cmp_gt_f32_e32 vcc, s33, v139
	s_nop 1
	v_cndmask_b32_e64 v140, 0, 32, vcc
	v_ldexp_f32 v139, v139, v140
	v_log_f32_e32 v139, v139
	s_nop 0
	v_mul_f32_e32 v140, 0x3f317217, v139
	v_fma_f32 v140, v139, s97, -v140
	v_fmac_f32_e32 v140, 0x3377d1cf, v139
	v_fmac_f32_e32 v140, 0x3f317217, v139
	v_cmp_lt_f32_e64 s[0:1], |v139|, s2
	s_nop 1
	v_cndmask_b32_e64 v139, v139, v140, s[0:1]
	v_cndmask_b32_e32 v140, 0, v213, vcc
	v_sub_f32_e32 v139, v139, v140
	v_mul_f32_e32 v140, 0xbfb8aa3b, v38
	v_exp_f32_e32 v140, v140
	v_cvt_pk_bf16_f32 v138, v138, v139
	v_add_f32_e32 v140, 1.0, v140
	v_rcp_f32_e32 v140, v140
	s_nop 0
	v_fma_f32 v140, v140, v156, v134
	v_cmp_gt_f32_e32 vcc, s33, v140
	s_nop 1
	v_cndmask_b32_e64 v141, 0, 32, vcc
	v_ldexp_f32 v140, v140, v141
	v_log_f32_e32 v140, v140
	s_nop 0
	v_mul_f32_e32 v141, 0x3f317217, v140
	v_fma_f32 v141, v140, s97, -v141
	v_fmac_f32_e32 v141, 0x3377d1cf, v140
	v_fmac_f32_e32 v141, 0x3f317217, v140
	v_cmp_lt_f32_e64 s[0:1], |v140|, s2
	s_nop 1
	v_cndmask_b32_e64 v140, v140, v141, s[0:1]
	v_cndmask_b32_e32 v141, 0, v213, vcc
	v_sub_f32_e32 v140, v140, v141
	v_mul_f32_e32 v141, 0xbfb8aa3b, v39
	v_exp_f32_e32 v141, v141
	s_nop 0
	v_add_f32_e32 v141, 1.0, v141
	v_rcp_f32_e32 v141, v141
	s_nop 0
	v_fma_f32 v141, v141, v154, v135
	v_cmp_gt_f32_e32 vcc, s33, v141
	s_nop 1
	v_cndmask_b32_e64 v142, 0, 32, vcc
	v_ldexp_f32 v141, v141, v142
	v_log_f32_e32 v141, v141
	s_nop 0
	v_mul_f32_e32 v142, 0x3f317217, v141
	v_fma_f32 v142, v141, s97, -v142
	v_fmac_f32_e32 v142, 0x3377d1cf, v141
	v_fmac_f32_e32 v142, 0x3f317217, v141
	v_cmp_lt_f32_e64 s[0:1], |v141|, s2
	s_nop 1
	v_cndmask_b32_e64 v141, v141, v142, s[0:1]
	v_cndmask_b32_e32 v142, 0, v213, vcc
	v_sub_f32_e32 v141, v141, v142
	v_mul_f32_e32 v142, 0xbfb8aa3b, v28
	v_exp_f32_e32 v142, v142
	v_cvt_pk_bf16_f32 v139, v140, v141
	v_add_f32_e32 v142, 1.0, v142
	v_rcp_f32_e32 v142, v142
	s_nop 0
	v_fma_f32 v142, v142, v158, v128
	v_cmp_gt_f32_e32 vcc, s33, v142
	s_nop 1
	v_cndmask_b32_e64 v143, 0, 32, vcc
	v_ldexp_f32 v142, v142, v143
	v_log_f32_e32 v142, v142
	s_nop 0
	v_mul_f32_e32 v143, 0x3f317217, v142
	v_fma_f32 v143, v142, s97, -v143
	v_fmac_f32_e32 v143, 0x3377d1cf, v142
	v_fmac_f32_e32 v143, 0x3f317217, v142
	v_cmp_lt_f32_e64 s[0:1], |v142|, s2
	s_nop 1
	v_cndmask_b32_e64 v142, v142, v143, s[0:1]
	v_cndmask_b32_e32 v143, 0, v213, vcc
	v_sub_f32_e32 v142, v142, v143
	v_mul_f32_e32 v143, 0xbfb8aa3b, v29
	v_exp_f32_e32 v143, v143
	s_nop 0
	v_add_f32_e32 v143, 1.0, v143
	v_rcp_f32_e32 v143, v143
	s_nop 0
	v_fma_f32 v143, v143, v136, v129
	v_cmp_gt_f32_e32 vcc, s33, v143
	s_nop 1
	v_cndmask_b32_e64 v144, 0, 32, vcc
	v_ldexp_f32 v143, v143, v144
	v_log_f32_e32 v143, v143
	s_nop 0
	v_mul_f32_e32 v144, 0x3f317217, v143
	v_fma_f32 v144, v143, s97, -v144
	v_fmac_f32_e32 v144, 0x3377d1cf, v143
	v_fmac_f32_e32 v144, 0x3f317217, v143
	v_cmp_lt_f32_e64 s[0:1], |v143|, s2
	s_nop 1
	v_cndmask_b32_e64 v143, v143, v144, s[0:1]
	v_cndmask_b32_e32 v144, 0, v213, vcc
	v_sub_f32_e32 v143, v143, v144
	v_mul_f32_e32 v144, 0xbfb8aa3b, v30
	v_exp_f32_e32 v144, v144
	v_cvt_pk_bf16_f32 v140, v142, v143
	v_lshl_add_u64 v[142:143], s[8:9], 0, v[148:149]
	v_lshl_add_u64 v[142:143], v[142:143], 0, v[172:173]
	v_add_f32_e32 v144, 1.0, v144
	v_rcp_f32_e32 v144, v144
	s_nop 0
	v_fma_f32 v144, v144, v155, v130
	v_cmp_gt_f32_e32 vcc, s33, v144
	s_nop 1
	v_cndmask_b32_e64 v145, 0, 32, vcc
	v_ldexp_f32 v144, v144, v145
	v_log_f32_e32 v144, v144
	s_nop 0
	v_mul_f32_e32 v145, 0x3f317217, v144
	v_fma_f32 v145, v144, s97, -v145
	v_fmac_f32_e32 v145, 0x3377d1cf, v144
	v_fmac_f32_e32 v145, 0x3f317217, v144
	v_cmp_lt_f32_e64 s[0:1], |v144|, s2
	s_nop 1
	v_cndmask_b32_e64 v144, v144, v145, s[0:1]
	v_cndmask_b32_e32 v145, 0, v213, vcc
	v_sub_f32_e32 v144, v144, v145
	v_mul_f32_e32 v145, 0xbfb8aa3b, v31
	v_exp_f32_e32 v145, v145
	s_nop 0
	v_add_f32_e32 v145, 1.0, v145
	v_rcp_f32_e32 v145, v145
	s_nop 0
	v_fma_f32 v145, v145, v137, v131
	v_cmp_gt_f32_e32 vcc, s33, v145
	s_nop 1
	v_cndmask_b32_e64 v146, 0, 32, vcc
	v_ldexp_f32 v145, v145, v146
	v_log_f32_e32 v145, v145
	s_nop 0
	v_mul_f32_e32 v146, 0x3f317217, v145
	v_fma_f32 v146, v145, s97, -v146
	v_fmac_f32_e32 v146, 0x3377d1cf, v145
	v_fmac_f32_e32 v146, 0x3f317217, v145
	v_cmp_lt_f32_e64 s[0:1], |v145|, s2
	s_nop 1
	v_cndmask_b32_e64 v145, v145, v146, s[0:1]
	v_cndmask_b32_e32 v146, 0, v213, vcc
	v_sub_f32_e32 v145, v145, v146
	v_cvt_pk_bf16_f32 v141, v144, v145
	global_store_dwordx4 v[142:143], v[138:141], off sc1
	s_nop 1
	v_mul_f32_e32 v138, 0xbfb8aa3b, v20
	v_exp_f32_e32 v138, v138
	s_nop 0
	v_add_f32_e32 v138, 1.0, v138
	v_rcp_f32_e32 v138, v138
	s_nop 0
	v_fma_f32 v138, v138, v159, v132
	v_cmp_gt_f32_e32 vcc, s33, v138
	s_nop 1
	v_cndmask_b32_e64 v139, 0, 32, vcc
	v_ldexp_f32 v138, v138, v139
	v_log_f32_e32 v138, v138
	s_nop 0
	v_mul_f32_e32 v139, 0x3f317217, v138
	v_fma_f32 v139, v138, s97, -v139
	v_fmac_f32_e32 v139, 0x3377d1cf, v138
	v_fmac_f32_e32 v139, 0x3f317217, v138
	v_cmp_lt_f32_e64 s[0:1], |v138|, s2
	s_nop 1
	v_cndmask_b32_e64 v138, v138, v139, s[0:1]
	v_cndmask_b32_e32 v139, 0, v213, vcc
	v_sub_f32_e32 v138, v138, v139
	v_mul_f32_e32 v139, 0xbfb8aa3b, v21
	v_exp_f32_e32 v139, v139
	s_nop 0
	v_add_f32_e32 v139, 1.0, v139
	v_rcp_f32_e32 v139, v139
	s_nop 0
	v_fma_f32 v139, v139, v157, v133
	v_cmp_gt_f32_e32 vcc, s33, v139
	s_nop 1
	v_cndmask_b32_e64 v140, 0, 32, vcc
	v_ldexp_f32 v139, v139, v140
	v_log_f32_e32 v139, v139
	s_nop 0
	v_mul_f32_e32 v140, 0x3f317217, v139
	v_fma_f32 v140, v139, s97, -v140
	v_fmac_f32_e32 v140, 0x3377d1cf, v139
	v_fmac_f32_e32 v140, 0x3f317217, v139
	v_cmp_lt_f32_e64 s[0:1], |v139|, s2
	s_nop 1
	v_cndmask_b32_e64 v139, v139, v140, s[0:1]
	v_cndmask_b32_e32 v140, 0, v213, vcc
	v_sub_f32_e32 v139, v139, v140
	v_mul_f32_e32 v140, 0xbfb8aa3b, v22
	v_exp_f32_e32 v140, v140
	v_cvt_pk_bf16_f32 v138, v138, v139
	v_add_f32_e32 v140, 1.0, v140
	v_rcp_f32_e32 v140, v140
	s_nop 0
	v_fma_f32 v140, v140, v156, v134
	v_cmp_gt_f32_e32 vcc, s33, v140
	s_nop 1
	v_cndmask_b32_e64 v141, 0, 32, vcc
	v_ldexp_f32 v140, v140, v141
	v_log_f32_e32 v140, v140
	s_nop 0
	v_mul_f32_e32 v141, 0x3f317217, v140
	v_fma_f32 v141, v140, s97, -v141
	v_fmac_f32_e32 v141, 0x3377d1cf, v140
	v_fmac_f32_e32 v141, 0x3f317217, v140
	v_cmp_lt_f32_e64 s[0:1], |v140|, s2
	s_nop 1
	v_cndmask_b32_e64 v140, v140, v141, s[0:1]
	v_cndmask_b32_e32 v141, 0, v213, vcc
	v_sub_f32_e32 v140, v140, v141
	v_mul_f32_e32 v141, 0xbfb8aa3b, v23
	v_exp_f32_e32 v141, v141
	s_nop 0
	v_add_f32_e32 v141, 1.0, v141
	v_rcp_f32_e32 v141, v141
	s_nop 0
	v_fma_f32 v141, v141, v154, v135
	v_cmp_gt_f32_e32 vcc, s33, v141
	s_nop 1
	v_cndmask_b32_e64 v142, 0, 32, vcc
	v_ldexp_f32 v141, v141, v142
	v_log_f32_e32 v141, v141
	s_nop 0
	v_mul_f32_e32 v142, 0x3f317217, v141
	v_fma_f32 v142, v141, s97, -v142
	v_fmac_f32_e32 v142, 0x3377d1cf, v141
	v_fmac_f32_e32 v142, 0x3f317217, v141
	v_cmp_lt_f32_e64 s[0:1], |v141|, s2
	s_nop 1
	v_cndmask_b32_e64 v141, v141, v142, s[0:1]
	v_cndmask_b32_e32 v142, 0, v213, vcc
	v_sub_f32_e32 v141, v141, v142
	v_mul_f32_e32 v142, 0xbfb8aa3b, v12
	v_exp_f32_e32 v142, v142
	v_cvt_pk_bf16_f32 v139, v140, v141
	v_add_f32_e32 v142, 1.0, v142
	v_rcp_f32_e32 v142, v142
	s_nop 0
	v_fma_f32 v142, v142, v158, v128
	v_cmp_gt_f32_e32 vcc, s33, v142
	s_nop 1
	v_cndmask_b32_e64 v143, 0, 32, vcc
	v_ldexp_f32 v142, v142, v143
	v_log_f32_e32 v142, v142
	s_nop 0
	v_mul_f32_e32 v143, 0x3f317217, v142
	v_fma_f32 v143, v142, s97, -v143
	v_fmac_f32_e32 v143, 0x3377d1cf, v142
	v_fmac_f32_e32 v143, 0x3f317217, v142
	v_cmp_lt_f32_e64 s[0:1], |v142|, s2
	s_nop 1
	v_cndmask_b32_e64 v142, v142, v143, s[0:1]
	v_cndmask_b32_e32 v143, 0, v213, vcc
	v_sub_f32_e32 v142, v142, v143
	v_mul_f32_e32 v143, 0xbfb8aa3b, v13
	v_exp_f32_e32 v143, v143
	s_nop 0
	v_add_f32_e32 v143, 1.0, v143
	v_rcp_f32_e32 v143, v143
	s_nop 0
	v_fma_f32 v143, v143, v136, v129
	v_cmp_gt_f32_e32 vcc, s33, v143
	s_nop 1
	v_cndmask_b32_e64 v144, 0, 32, vcc
	v_ldexp_f32 v143, v143, v144
	v_log_f32_e32 v143, v143
	s_nop 0
	v_mul_f32_e32 v144, 0x3f317217, v143
	v_fma_f32 v144, v143, s97, -v144
	v_fmac_f32_e32 v144, 0x3377d1cf, v143
	v_fmac_f32_e32 v144, 0x3f317217, v143
	v_cmp_lt_f32_e64 s[0:1], |v143|, s2
	s_nop 1
	v_cndmask_b32_e64 v143, v143, v144, s[0:1]
	v_cndmask_b32_e32 v144, 0, v213, vcc
	v_sub_f32_e32 v143, v143, v144
	v_mul_f32_e32 v144, 0xbfb8aa3b, v14
	v_exp_f32_e32 v144, v144
	v_cvt_pk_bf16_f32 v140, v142, v143
	v_lshl_add_u64 v[142:143], s[8:9], 0, v[152:153]
	v_lshl_add_u64 v[142:143], v[142:143], 0, v[172:173]
	v_add_f32_e32 v144, 1.0, v144
	v_rcp_f32_e32 v144, v144
	s_nop 0
	v_fma_f32 v144, v144, v155, v130
	v_cmp_gt_f32_e32 vcc, s33, v144
	s_nop 1
	v_cndmask_b32_e64 v145, 0, 32, vcc
	v_ldexp_f32 v144, v144, v145
	v_log_f32_e32 v144, v144
	s_nop 0
	v_mul_f32_e32 v145, 0x3f317217, v144
	v_fma_f32 v145, v144, s97, -v145
	v_fmac_f32_e32 v145, 0x3377d1cf, v144
	v_fmac_f32_e32 v145, 0x3f317217, v144
	v_cmp_lt_f32_e64 s[0:1], |v144|, s2
	s_nop 1
	v_cndmask_b32_e64 v144, v144, v145, s[0:1]
	v_cndmask_b32_e32 v145, 0, v213, vcc
	v_sub_f32_e32 v144, v144, v145
	v_mul_f32_e32 v145, 0xbfb8aa3b, v15
	v_exp_f32_e32 v145, v145
	s_nop 0
	v_add_f32_e32 v145, 1.0, v145
	v_rcp_f32_e32 v145, v145
	s_nop 0
	v_fma_f32 v145, v145, v137, v131
	v_cmp_gt_f32_e32 vcc, s33, v145
	s_nop 1
	v_cndmask_b32_e64 v146, 0, 32, vcc
	v_ldexp_f32 v145, v145, v146
	v_log_f32_e32 v145, v145
	s_nop 0
	v_mul_f32_e32 v146, 0x3f317217, v145
	v_fma_f32 v146, v145, s97, -v146
	v_fmac_f32_e32 v146, 0x3377d1cf, v145
	v_fmac_f32_e32 v146, 0x3f317217, v145
	v_cmp_lt_f32_e64 s[0:1], |v145|, s2
	s_nop 1
	v_cndmask_b32_e64 v145, v145, v146, s[0:1]
	v_cndmask_b32_e32 v146, 0, v213, vcc
	v_sub_f32_e32 v145, v145, v146
	v_cvt_pk_bf16_f32 v141, v144, v145
	global_store_dwordx4 v[142:143], v[138:141], off sc1
	s_nop 1
	v_mul_f32_e32 v138, 0xbfb8aa3b, v4
	v_exp_f32_e32 v138, v138
	s_nop 0
	v_add_f32_e32 v138, 1.0, v138
	v_rcp_f32_e32 v138, v138
	s_nop 0
	v_fma_f32 v132, v138, v159, v132
	v_cmp_gt_f32_e32 vcc, s33, v132
	s_nop 1
	v_cndmask_b32_e64 v138, 0, 32, vcc
	v_ldexp_f32 v132, v132, v138
	v_log_f32_e32 v132, v132
	s_nop 0
	v_mul_f32_e32 v138, 0x3f317217, v132
	v_fma_f32 v138, v132, s97, -v138
	v_fmac_f32_e32 v138, 0x3377d1cf, v132
	v_fmac_f32_e32 v138, 0x3f317217, v132
	v_cmp_lt_f32_e64 s[0:1], |v132|, s2
	s_nop 1
	v_cndmask_b32_e64 v132, v132, v138, s[0:1]
	v_cndmask_b32_e32 v138, 0, v213, vcc
	v_sub_f32_e32 v132, v132, v138
	v_mul_f32_e32 v138, 0xbfb8aa3b, v5
	v_exp_f32_e32 v138, v138
	s_nop 0
	v_add_f32_e32 v138, 1.0, v138
	v_rcp_f32_e32 v138, v138
	s_nop 0
	v_fma_f32 v133, v138, v157, v133
	v_cmp_gt_f32_e32 vcc, s33, v133
	s_nop 1
	v_cndmask_b32_e64 v138, 0, 32, vcc
	v_ldexp_f32 v133, v133, v138
	v_log_f32_e32 v133, v133
	s_nop 0
	v_mul_f32_e32 v138, 0x3f317217, v133
	v_fma_f32 v138, v133, s97, -v138
	v_fmac_f32_e32 v138, 0x3377d1cf, v133
	v_fmac_f32_e32 v138, 0x3f317217, v133
	v_cmp_lt_f32_e64 s[0:1], |v133|, s2
	s_nop 1
	v_cndmask_b32_e64 v133, v133, v138, s[0:1]
	v_cndmask_b32_e32 v138, 0, v213, vcc
	v_sub_f32_e32 v133, v133, v138
	v_mul_f32_e32 v138, 0xbfb8aa3b, v6
	v_exp_f32_e32 v138, v138
	s_nop 0
	v_add_f32_e32 v138, 1.0, v138
	v_rcp_f32_e32 v138, v138
	s_nop 0
	v_fma_f32 v134, v138, v156, v134
	v_cmp_gt_f32_e32 vcc, s33, v134
	s_nop 1
	v_cndmask_b32_e64 v138, 0, 32, vcc
	v_ldexp_f32 v134, v134, v138
	v_log_f32_e32 v134, v134
	s_nop 0
	v_mul_f32_e32 v138, 0x3f317217, v134
	v_fma_f32 v138, v134, s97, -v138
	v_fmac_f32_e32 v138, 0x3377d1cf, v134
	v_fmac_f32_e32 v138, 0x3f317217, v134
	v_cmp_lt_f32_e64 s[0:1], |v134|, s2
	s_nop 1
	v_cndmask_b32_e64 v134, v134, v138, s[0:1]
	v_cndmask_b32_e32 v138, 0, v213, vcc
	v_sub_f32_e32 v134, v134, v138
	v_mul_f32_e32 v138, 0xbfb8aa3b, v7
	v_exp_f32_e32 v138, v138
	s_nop 0
	v_add_f32_e32 v138, 1.0, v138
	v_rcp_f32_e32 v138, v138
	s_nop 0
	v_fmac_f32_e32 v135, v138, v154
	v_cmp_gt_f32_e32 vcc, s33, v135
	s_nop 1
	v_cndmask_b32_e64 v138, 0, 32, vcc
	v_ldexp_f32 v135, v135, v138
	v_log_f32_e32 v135, v135
	s_nop 0
	v_mul_f32_e32 v138, 0x3f317217, v135
	v_fma_f32 v138, v135, s97, -v138
	v_fmac_f32_e32 v138, 0x3377d1cf, v135
	v_fmac_f32_e32 v138, 0x3f317217, v135
	v_cmp_lt_f32_e64 s[0:1], |v135|, s2
	s_nop 1
	v_cndmask_b32_e64 v135, v135, v138, s[0:1]
	v_cndmask_b32_e32 v138, 0, v213, vcc
	v_sub_f32_e32 v135, v135, v138
	v_mul_f32_e32 v138, 0xbfb8aa3b, v0
	v_exp_f32_e32 v138, v138
	s_nop 0
	v_add_f32_e32 v138, 1.0, v138
	v_rcp_f32_e32 v138, v138
	s_nop 0
	v_fma_f32 v128, v138, v158, v128
	v_cmp_gt_f32_e32 vcc, s33, v128
	s_nop 1
	v_cndmask_b32_e64 v138, 0, 32, vcc
	v_ldexp_f32 v128, v128, v138
	v_log_f32_e32 v128, v128
	s_nop 0
	v_mul_f32_e32 v138, 0x3f317217, v128
	v_fma_f32 v138, v128, s97, -v138
	v_fmac_f32_e32 v138, 0x3377d1cf, v128
	v_fmac_f32_e32 v138, 0x3f317217, v128
	v_cmp_lt_f32_e64 s[0:1], |v128|, s2
	s_nop 1
	v_cndmask_b32_e64 v128, v128, v138, s[0:1]
	v_cndmask_b32_e32 v138, 0, v213, vcc
	v_sub_f32_e32 v138, v128, v138
	v_mul_f32_e32 v128, 0xbfb8aa3b, v1
	v_exp_f32_e32 v128, v128
	s_nop 0
	v_add_f32_e32 v128, 1.0, v128
	v_rcp_f32_e32 v128, v128
	s_nop 0
	v_fma_f32 v128, v128, v136, v129
	v_cmp_gt_f32_e32 vcc, s33, v128
	s_nop 1
	v_cndmask_b32_e64 v129, 0, 32, vcc
	v_ldexp_f32 v128, v128, v129
	v_log_f32_e32 v128, v128
	s_nop 0
	v_mul_f32_e32 v129, 0x3f317217, v128
	v_fma_f32 v129, v128, s97, -v129
	v_fmac_f32_e32 v129, 0x3377d1cf, v128
	v_fmac_f32_e32 v129, 0x3f317217, v128
	v_cmp_lt_f32_e64 s[0:1], |v128|, s2
	s_nop 1
	v_cndmask_b32_e64 v128, v128, v129, s[0:1]
	v_cndmask_b32_e32 v129, 0, v213, vcc
	v_sub_f32_e32 v136, v128, v129
	v_mul_f32_e32 v128, 0xbfb8aa3b, v2
	v_exp_f32_e32 v128, v128
	s_nop 0
	v_add_f32_e32 v128, 1.0, v128
	v_rcp_f32_e32 v128, v128
	s_nop 0
	v_fma_f32 v128, v128, v155, v130
	v_cmp_gt_f32_e32 vcc, s33, v128
	v_cvt_pk_bf16_f32 v130, v138, v136
	s_nop 0
	v_cndmask_b32_e64 v129, 0, 32, vcc
	v_ldexp_f32 v128, v128, v129
	v_log_f32_e32 v128, v128
	s_nop 0
	v_mul_f32_e32 v129, 0x3f317217, v128
	v_fma_f32 v129, v128, s97, -v129
	v_fmac_f32_e32 v129, 0x3377d1cf, v128
	v_fmac_f32_e32 v129, 0x3f317217, v128
	v_cmp_lt_f32_e64 s[0:1], |v128|, s2
	s_nop 1
	v_cndmask_b32_e64 v128, v128, v129, s[0:1]
	v_cndmask_b32_e32 v129, 0, v213, vcc
	v_sub_f32_e32 v139, v128, v129
	v_mul_f32_e32 v128, 0xbfb8aa3b, v3
	v_exp_f32_e32 v128, v128
	s_nop 0
	v_add_f32_e32 v128, 1.0, v128
	v_rcp_f32_e32 v128, v128
	s_nop 0
	v_fmac_f32_e32 v131, v128, v137
	v_cmp_gt_f32_e32 vcc, s33, v131
	s_nop 1
	v_cndmask_b32_e64 v128, 0, 32, vcc
	v_ldexp_f32 v128, v131, v128
	v_log_f32_e32 v128, v128
	s_nop 0
	v_mul_f32_e32 v129, 0x3f317217, v128
	v_fma_f32 v129, v128, s97, -v129
	v_fmac_f32_e32 v129, 0x3377d1cf, v128
	v_fmac_f32_e32 v129, 0x3f317217, v128
	v_cmp_lt_f32_e64 s[0:1], |v128|, s2
	s_nop 1
	v_cndmask_b32_e64 v128, v128, v129, s[0:1]
	v_cndmask_b32_e32 v129, 0, v213, vcc
	v_sub_f32_e32 v131, v128, v129
	v_cvt_pk_bf16_f32 v128, v132, v133
	v_lshl_add_u64 v[132:133], s[8:9], 0, v[150:151]
	v_cvt_pk_bf16_f32 v129, v134, v135
	v_cvt_pk_bf16_f32 v131, v139, v131
	v_lshl_add_u64 v[132:133], v[132:133], 0, v[172:173]
	global_store_dwordx4 v[132:133], v[128:131], off sc1

.LBB0_411:
	s_andn2_b64 vcc, exec, s[0:1]
	s_cbranch_vccnz .LBB0_413
	v_mul_f32_e32 v132, 0xbfb8aa3b, v120
	v_mul_f32_e32 v133, 0xbfb8aa3b, v121
	v_mul_f32_e32 v136, 0xbfb8aa3b, v122
	v_mul_f32_e32 v137, 0xbfb8aa3b, v123
	v_exp_f32_e32 v132, v132
	v_exp_f32_e32 v133, v133
	v_exp_f32_e32 v136, v136
	v_exp_f32_e32 v137, v137
	v_mul_f32_e32 v128, 0xbfb8aa3b, v124
	v_mul_f32_e32 v129, 0xbfb8aa3b, v125
	v_exp_f32_e32 v128, v128
	v_exp_f32_e32 v129, v129
	v_mul_f32_e32 v130, 0xbfb8aa3b, v126
	v_mul_f32_e32 v131, 0xbfb8aa3b, v127
	v_exp_f32_e32 v130, v130
	v_exp_f32_e32 v131, v131
	v_add_f32_e32 v132, 1.0, v132
	v_add_f32_e32 v133, 1.0, v133
	v_add_f32_e32 v136, 1.0, v136
	v_add_f32_e32 v137, 1.0, v137
	v_rcp_f32_e32 v132, v132
	v_rcp_f32_e32 v133, v133
	v_rcp_f32_e32 v136, v136
	v_rcp_f32_e32 v137, v137
	v_add_f32_e32 v128, 1.0, v128
	v_add_f32_e32 v129, 1.0, v129
	v_rcp_f32_e32 v128, v128
	v_rcp_f32_e32 v129, v129
	v_add_f32_e32 v130, 1.0, v130
	v_add_f32_e32 v131, 1.0, v131
	v_rcp_f32_e32 v130, v130
	v_rcp_f32_e32 v131, v131
	v_pk_mul_f32 v[132:133], v[120:121], v[132:133]
	v_pk_mul_f32 v[136:137], v[122:123], v[136:137]
	v_cvt_pk_bf16_f32 v132, v132, v133
	v_cvt_pk_bf16_f32 v133, v136, v137
	v_mul_f32_e32 v136, 0xbfb8aa3b, v112
	v_mul_f32_e32 v137, 0xbfb8aa3b, v113
	v_readlane_b32 s0, v251, 56
	v_exp_f32_e32 v136, v136
	v_exp_f32_e32 v137, v137
	v_lshlrev_b32_e32 v172, 1, v223
	v_readlane_b32 s1, v251, 57
	v_pk_mul_f32 v[128:129], v[124:125], v[128:129]
	v_ashrrev_i32_e32 v187, 31, v186
	v_lshl_add_u64 v[134:135], s[0:1], 0, v[172:173]
	v_pk_mul_f32 v[138:139], v[126:127], v[130:131]
	v_cvt_pk_bf16_f32 v130, v128, v129
	v_lshlrev_b64 v[128:129], 11, v[186:187]
	v_cvt_pk_bf16_f32 v131, v138, v139
	v_lshl_add_u64 v[128:129], v[134:135], 0, v[128:129]
	global_store_dwordx4 v[128:129], v[130:133], off sc1
	v_mul_f32_e32 v138, 0xbfb8aa3b, v106
	v_mul_f32_e32 v139, 0xbfb8aa3b, v107
	v_add_f32_e32 v130, 1.0, v136
	v_add_f32_e32 v131, 1.0, v137
	v_mul_f32_e32 v136, 0xbfb8aa3b, v104
	v_mul_f32_e32 v137, 0xbfb8aa3b, v105
	v_exp_f32_e32 v136, v136
	v_exp_f32_e32 v137, v137
	v_mul_f32_e32 v132, 0xbfb8aa3b, v114
	v_mul_f32_e32 v133, 0xbfb8aa3b, v115
	v_exp_f32_e32 v132, v132
	v_exp_f32_e32 v133, v133
	v_exp_f32_e32 v138, v138
	v_exp_f32_e32 v139, v139
	v_rcp_f32_e32 v130, v130
	v_rcp_f32_e32 v131, v131
	v_add_f32_e32 v136, 1.0, v136
	v_add_f32_e32 v137, 1.0, v137
	v_rcp_f32_e32 v136, v136
	v_rcp_f32_e32 v137, v137
	v_add_f32_e32 v132, 1.0, v132
	v_add_f32_e32 v133, 1.0, v133
	v_add_f32_e32 v138, 1.0, v138
	v_add_f32_e32 v139, 1.0, v139
	v_rcp_f32_e32 v132, v132
	v_rcp_f32_e32 v133, v133
	v_rcp_f32_e32 v138, v138
	v_rcp_f32_e32 v139, v139
	v_pk_mul_f32 v[130:131], v[112:113], v[130:131]
	v_pk_mul_f32 v[140:141], v[104:105], v[136:137]
	v_cvt_pk_bf16_f32 v136, v130, v131
	v_or_b32_e32 v130, 16, v186
	v_ashrrev_i32_e32 v131, 31, v130
	v_pk_mul_f32 v[132:133], v[114:115], v[132:133]
	v_pk_mul_f32 v[142:143], v[106:107], v[138:139]
	v_lshlrev_b64 v[130:131], 11, v[130:131]
	v_cvt_pk_bf16_f32 v137, v132, v133
	v_cvt_pk_bf16_f32 v138, v140, v141
	v_cvt_pk_bf16_f32 v139, v142, v143
	v_lshl_add_u64 v[130:131], v[134:135], 0, v[130:131]
	global_store_dwordx4 v[130:131], v[136:139], off sc1
	v_mul_f32_e32 v140, 0xbfb8aa3b, v90
	v_mul_f32_e32 v141, 0xbfb8aa3b, v91
	v_mul_f32_e32 v138, 0xbfb8aa3b, v88
	v_mul_f32_e32 v139, 0xbfb8aa3b, v89
	v_mul_f32_e32 v132, 0xbfb8aa3b, v96
	v_mul_f32_e32 v133, 0xbfb8aa3b, v97
	v_exp_f32_e32 v138, v138
	v_exp_f32_e32 v139, v139
	v_exp_f32_e32 v140, v140
	v_exp_f32_e32 v141, v141
	v_exp_f32_e32 v132, v132
	v_exp_f32_e32 v133, v133
	v_mul_f32_e32 v136, 0xbfb8aa3b, v98
	v_mul_f32_e32 v137, 0xbfb8aa3b, v99
	v_exp_f32_e32 v136, v136
	v_exp_f32_e32 v137, v137
	v_add_f32_e32 v138, 1.0, v138
	v_add_f32_e32 v139, 1.0, v139
	v_add_f32_e32 v140, 1.0, v140
	v_add_f32_e32 v141, 1.0, v141
	v_add_f32_e32 v132, 1.0, v132
	v_add_f32_e32 v133, 1.0, v133
	v_rcp_f32_e32 v138, v138
	v_rcp_f32_e32 v139, v139
	v_rcp_f32_e32 v140, v140
	v_rcp_f32_e32 v141, v141
	v_rcp_f32_e32 v132, v132
	v_rcp_f32_e32 v133, v133
	v_add_f32_e32 v136, 1.0, v136
	v_add_f32_e32 v137, 1.0, v137
	v_rcp_f32_e32 v136, v136
	v_rcp_f32_e32 v137, v137
	v_pk_mul_f32 v[138:139], v[88:89], v[138:139]
	v_pk_mul_f32 v[140:141], v[90:91], v[140:141]
	v_pk_mul_f32 v[132:133], v[96:97], v[132:133]
	v_cvt_pk_bf16_f32 v138, v138, v139
	v_cvt_pk_bf16_f32 v139, v140, v141
	v_mul_f32_e32 v140, 0xbfb8aa3b, v80
	v_mul_f32_e32 v141, 0xbfb8aa3b, v81
	v_pk_mul_f32 v[142:143], v[98:99], v[136:137]
	v_cvt_pk_bf16_f32 v136, v132, v133
	v_or_b32_e32 v132, 32, v186
	v_exp_f32_e32 v140, v140
	v_exp_f32_e32 v141, v141
	v_ashrrev_i32_e32 v133, 31, v132
	v_lshlrev_b64 v[132:133], 11, v[132:133]
	v_cvt_pk_bf16_f32 v137, v142, v143
	v_lshl_add_u64 v[132:133], v[134:135], 0, v[132:133]
	global_store_dwordx4 v[132:133], v[136:139], off sc1
	v_mul_f32_e32 v142, 0xbfb8aa3b, v74
	v_mul_f32_e32 v143, 0xbfb8aa3b, v75
	v_add_f32_e32 v136, 1.0, v140
	v_add_f32_e32 v137, 1.0, v141
	v_mul_f32_e32 v138, 0xbfb8aa3b, v82
	v_mul_f32_e32 v139, 0xbfb8aa3b, v83
	v_mul_f32_e32 v140, 0xbfb8aa3b, v72
	v_mul_f32_e32 v141, 0xbfb8aa3b, v73
	v_exp_f32_e32 v138, v138
	v_exp_f32_e32 v139, v139
	v_exp_f32_e32 v140, v140
	v_exp_f32_e32 v141, v141
	v_add_f32_e32 v138, 1.0, v138
	v_add_f32_e32 v139, 1.0, v139
	v_add_f32_e32 v140, 1.0, v140
	v_add_f32_e32 v141, 1.0, v141
	v_exp_f32_e32 v142, v142
	v_exp_f32_e32 v143, v143
	v_rcp_f32_e32 v136, v136
	v_rcp_f32_e32 v137, v137
	v_rcp_f32_e32 v138, v138
	v_rcp_f32_e32 v139, v139
	v_rcp_f32_e32 v140, v140
	v_rcp_f32_e32 v141, v141
	v_add_f32_e32 v142, 1.0, v142
	v_add_f32_e32 v143, 1.0, v143
	v_rcp_f32_e32 v142, v142
	v_rcp_f32_e32 v143, v143
	v_pk_mul_f32 v[136:137], v[80:81], v[136:137]
	v_pk_mul_f32 v[138:139], v[82:83], v[138:139]
	v_pk_mul_f32 v[140:141], v[72:73], v[140:141]
	v_cvt_pk_bf16_f32 v136, v136, v137
	v_cvt_pk_bf16_f32 v137, v138, v139
	v_cvt_pk_bf16_f32 v138, v140, v141
	v_or_b32_e32 v140, 48, v186
	v_ashrrev_i32_e32 v141, 31, v140
	v_lshlrev_b64 v[140:141], 11, v[140:141]
	v_pk_mul_f32 v[142:143], v[74:75], v[142:143]
	v_lshl_add_u64 v[134:135], v[134:135], 0, v[140:141]
	v_mul_f32_e32 v140, 0xbfb8aa3b, v60
	v_mul_f32_e32 v141, 0xbfb8aa3b, v61
	v_cvt_pk_bf16_f32 v139, v142, v143
	v_exp_f32_e32 v140, v140
	v_exp_f32_e32 v141, v141
	global_store_dwordx4 v[134:135], v[136:139], off sc1
	v_mul_f32_e32 v142, 0xbfb8aa3b, v58
	v_mul_f32_e32 v143, 0xbfb8aa3b, v59
	v_mul_f32_e32 v138, 0xbfb8aa3b, v62
	v_mul_f32_e32 v139, 0xbfb8aa3b, v63
	v_exp_f32_e32 v138, v138
	v_exp_f32_e32 v139, v139
	v_add_f32_e32 v136, 1.0, v140
	v_add_f32_e32 v137, 1.0, v141
	v_mul_f32_e32 v140, 0xbfb8aa3b, v56
	v_mul_f32_e32 v141, 0xbfb8aa3b, v57
	v_exp_f32_e32 v140, v140
	v_exp_f32_e32 v141, v141
	v_exp_f32_e32 v142, v142
	v_exp_f32_e32 v143, v143
	v_add_f32_e32 v138, 1.0, v138
	v_add_f32_e32 v139, 1.0, v139
	v_rcp_f32_e32 v138, v138
	v_rcp_f32_e32 v139, v139
	v_add_f32_e32 v140, 1.0, v140
	v_add_f32_e32 v141, 1.0, v141
	v_add_f32_e32 v142, 1.0, v142
	v_add_f32_e32 v143, 1.0, v143
	v_rcp_f32_e32 v140, v140
	v_rcp_f32_e32 v141, v141
	v_rcp_f32_e32 v142, v142
	v_rcp_f32_e32 v143, v143
	v_rcp_f32_e32 v136, v136
	v_rcp_f32_e32 v137, v137
	v_pk_mul_f32 v[144:145], v[62:63], v[138:139]
	v_pk_mul_f32 v[140:141], v[56:57], v[140:141]
	v_cvt_pk_bf16_f32 v139, v144, v145
	v_mul_f32_e32 v144, 0xbfb8aa3b, v48
	v_mul_f32_e32 v145, 0xbfb8aa3b, v49
	v_exp_f32_e32 v144, v144
	v_exp_f32_e32 v145, v145
	v_pk_mul_f32 v[142:143], v[58:59], v[142:143]
	v_pk_mul_f32 v[136:137], v[60:61], v[136:137]
	v_cvt_pk_bf16_f32 v140, v140, v141
	v_cvt_pk_bf16_f32 v141, v142, v143
	v_add_co_u32_e32 v142, vcc, s93, v128
	v_cvt_pk_bf16_f32 v138, v136, v137
	s_nop 0
	v_addc_co_u32_e32 v143, vcc, 0, v129, vcc
	global_store_dwordx4 v[142:143], v[138:141], off sc1
	v_mul_f32_e32 v142, 0xbfb8aa3b, v40
	v_mul_f32_e32 v143, 0xbfb8aa3b, v41
	v_add_f32_e32 v138, 1.0, v144
	v_add_f32_e32 v139, 1.0, v145
	v_mul_f32_e32 v140, 0xbfb8aa3b, v50
	v_mul_f32_e32 v141, 0xbfb8aa3b, v51
	v_mul_f32_e32 v144, 0xbfb8aa3b, v42
	v_mul_f32_e32 v145, 0xbfb8aa3b, v43
	v_exp_f32_e32 v140, v140
	v_exp_f32_e32 v141, v141
	v_exp_f32_e32 v142, v142
	v_exp_f32_e32 v143, v143
	v_exp_f32_e32 v144, v144
	v_exp_f32_e32 v145, v145
	v_add_f32_e32 v140, 1.0, v140
	v_add_f32_e32 v141, 1.0, v141
	v_add_f32_e32 v142, 1.0, v142
	v_add_f32_e32 v143, 1.0, v143
	v_add_f32_e32 v144, 1.0, v144
	v_add_f32_e32 v145, 1.0, v145
	v_rcp_f32_e32 v140, v140
	v_rcp_f32_e32 v141, v141
	v_rcp_f32_e32 v142, v142
	v_rcp_f32_e32 v143, v143
	v_rcp_f32_e32 v144, v144
	v_rcp_f32_e32 v145, v145
	v_rcp_f32_e32 v138, v138
	v_rcp_f32_e32 v139, v139
	v_pk_mul_f32 v[146:147], v[50:51], v[140:141]
	v_pk_mul_f32 v[142:143], v[40:41], v[142:143]
	v_pk_mul_f32 v[144:145], v[42:43], v[144:145]
	v_pk_mul_f32 v[138:139], v[48:49], v[138:139]
	v_cvt_pk_bf16_f32 v141, v146, v147
	v_cvt_pk_bf16_f32 v142, v142, v143
	v_cvt_pk_bf16_f32 v143, v144, v145
	v_add_co_u32_e32 v144, vcc, s96, v128
	v_mul_f32_e32 v146, 0xbfb8aa3b, v32
	v_mul_f32_e32 v147, 0xbfb8aa3b, v33
	v_cvt_pk_bf16_f32 v140, v138, v139
	v_addc_co_u32_e32 v145, vcc, 0, v129, vcc
	v_exp_f32_e32 v146, v146
	v_exp_f32_e32 v147, v147
	global_store_dwordx4 v[144:145], v[140:143], off sc1
	v_mul_f32_e32 v144, 0xbfb8aa3b, v24
	v_mul_f32_e32 v145, 0xbfb8aa3b, v25
	v_mul_f32_e32 v142, 0xbfb8aa3b, v34
	v_mul_f32_e32 v143, 0xbfb8aa3b, v35
	v_exp_f32_e32 v142, v142
	v_exp_f32_e32 v143, v143
	v_add_f32_e32 v140, 1.0, v146
	v_add_f32_e32 v141, 1.0, v147
	v_mul_f32_e32 v146, 0xbfb8aa3b, v26
	v_mul_f32_e32 v147, 0xbfb8aa3b, v27
	v_exp_f32_e32 v144, v144
	v_exp_f32_e32 v145, v145
	v_exp_f32_e32 v146, v146
	v_exp_f32_e32 v147, v147
	v_add_f32_e32 v142, 1.0, v142
	v_add_f32_e32 v143, 1.0, v143
	v_rcp_f32_e32 v142, v142
	v_rcp_f32_e32 v143, v143
	v_rcp_f32_e32 v140, v140
	v_rcp_f32_e32 v141, v141
	v_add_f32_e32 v144, 1.0, v144
	v_add_f32_e32 v145, 1.0, v145
	v_add_f32_e32 v146, 1.0, v146
	v_add_f32_e32 v147, 1.0, v147
	v_rcp_f32_e32 v144, v144
	v_rcp_f32_e32 v145, v145
	v_rcp_f32_e32 v146, v146
	v_rcp_f32_e32 v147, v147
	v_pk_mul_f32 v[148:149], v[34:35], v[142:143]
	s_mov_b64 s[0:1], 0x48000
	v_cvt_pk_bf16_f32 v143, v148, v149
	v_mul_f32_e32 v148, 0xbfb8aa3b, v16
	v_mul_f32_e32 v149, 0xbfb8aa3b, v17
	v_lshl_add_u64 v[138:139], v[128:129], 0, s[0:1]
	v_pk_mul_f32 v[140:141], v[32:33], v[140:141]
	s_mov_b64 s[0:1], 0x50000
	v_exp_f32_e32 v148, v148
	v_exp_f32_e32 v149, v149
	v_pk_mul_f32 v[144:145], v[24:25], v[144:145]
	v_pk_mul_f32 v[146:147], v[26:27], v[146:147]
	v_cvt_pk_bf16_f32 v142, v140, v141
	v_lshl_add_u64 v[140:141], v[128:129], 0, s[0:1]
	s_mov_b32 s0, 0x50000
	v_cvt_pk_bf16_f32 v144, v144, v145
	v_cvt_pk_bf16_f32 v145, v146, v147
	v_add_co_u32_e32 v146, vcc, s0, v128
	s_mov_b64 s[0:1], 0x58000
	s_nop 0
	v_addc_co_u32_e32 v147, vcc, 0, v129, vcc
	global_store_dwordx4 v[146:147], v[142:145], off sc1
	v_mul_f32_e32 v146, 0xbfb8aa3b, v8
	v_mul_f32_e32 v147, 0xbfb8aa3b, v9
	v_add_f32_e32 v142, 1.0, v148
	v_add_f32_e32 v143, 1.0, v149
	v_mul_f32_e32 v144, 0xbfb8aa3b, v18
	v_mul_f32_e32 v145, 0xbfb8aa3b, v19
	v_mul_f32_e32 v148, 0xbfb8aa3b, v10
	v_mul_f32_e32 v149, 0xbfb8aa3b, v11
	v_exp_f32_e32 v144, v144
	v_exp_f32_e32 v145, v145
	v_exp_f32_e32 v146, v146
	v_exp_f32_e32 v147, v147
	v_exp_f32_e32 v148, v148
	v_exp_f32_e32 v149, v149
	v_rcp_f32_e32 v142, v142
	v_rcp_f32_e32 v143, v143
	v_add_f32_e32 v144, 1.0, v144
	v_add_f32_e32 v145, 1.0, v145
	v_add_f32_e32 v146, 1.0, v146
	v_add_f32_e32 v147, 1.0, v147
	v_add_f32_e32 v148, 1.0, v148
	v_add_f32_e32 v149, 1.0, v149
	v_rcp_f32_e32 v144, v144
	v_rcp_f32_e32 v145, v145
	v_rcp_f32_e32 v146, v146
	v_rcp_f32_e32 v147, v147
	v_rcp_f32_e32 v148, v148
	v_rcp_f32_e32 v149, v149
	v_pk_mul_f32 v[142:143], v[16:17], v[142:143]
	v_pk_mul_f32 v[150:151], v[18:19], v[144:145]
	v_pk_mul_f32 v[146:147], v[8:9], v[146:147]
	v_pk_mul_f32 v[148:149], v[10:11], v[148:149]
	v_cvt_pk_bf16_f32 v144, v142, v143
	v_lshl_add_u64 v[142:143], v[128:129], 0, s[0:1]
	s_mov_b32 s0, 0x58000
	v_cvt_pk_bf16_f32 v146, v146, v147
	v_cvt_pk_bf16_f32 v147, v148, v149
	v_add_co_u32_e32 v148, vcc, s0, v128
	v_cvt_pk_bf16_f32 v145, v150, v151
	s_nop 0
	v_addc_co_u32_e32 v149, vcc, 0, v129, vcc
	v_mul_f32_e32 v150, 0xbfb8aa3b, v116
	v_mul_f32_e32 v151, 0xbfb8aa3b, v117
	v_exp_f32_e32 v150, v150
	v_exp_f32_e32 v151, v151
	global_store_dwordx4 v[148:149], v[144:147], off sc1
	v_mul_f32_e32 v148, 0xbfb8aa3b, v108
	v_mul_f32_e32 v149, 0xbfb8aa3b, v109
	v_mul_f32_e32 v146, 0xbfb8aa3b, v118
	v_mul_f32_e32 v147, 0xbfb8aa3b, v119
	v_exp_f32_e32 v146, v146
	v_exp_f32_e32 v147, v147
	v_exp_f32_e32 v148, v148
	v_exp_f32_e32 v149, v149
	v_add_f32_e32 v144, 1.0, v150
	v_add_f32_e32 v145, 1.0, v151
	v_mul_f32_e32 v150, 0xbfb8aa3b, v110
	v_mul_f32_e32 v151, 0xbfb8aa3b, v111
	v_add_f32_e32 v146, 1.0, v146
	v_add_f32_e32 v147, 1.0, v147
	v_add_f32_e32 v148, 1.0, v148
	v_add_f32_e32 v149, 1.0, v149
	v_exp_f32_e32 v150, v150
	v_exp_f32_e32 v151, v151
	v_rcp_f32_e32 v144, v144
	v_rcp_f32_e32 v145, v145
	v_rcp_f32_e32 v146, v146
	v_rcp_f32_e32 v147, v147
	v_rcp_f32_e32 v148, v148
	v_rcp_f32_e32 v149, v149
	v_add_f32_e32 v150, 1.0, v150
	v_add_f32_e32 v151, 1.0, v151
	v_rcp_f32_e32 v150, v150
	v_rcp_f32_e32 v151, v151
	v_pk_mul_f32 v[144:145], v[116:117], v[144:145]
	v_pk_mul_f32 v[146:147], v[118:119], v[146:147]
	v_pk_mul_f32 v[148:149], v[108:109], v[148:149]
	v_cvt_pk_bf16_f32 v144, v144, v145
	v_cvt_pk_bf16_f32 v145, v146, v147
	v_cvt_pk_bf16_f32 v146, v148, v149
	v_mul_f32_e32 v148, 0xbfb8aa3b, v100
	v_mul_f32_e32 v149, 0xbfb8aa3b, v101
	v_exp_f32_e32 v148, v148
	v_exp_f32_e32 v149, v149
	v_pk_mul_f32 v[150:151], v[110:111], v[150:151]
	v_lshl_add_u64 v[136:137], v[128:129], 0, s[4:5]
	v_cvt_pk_bf16_f32 v147, v150, v151
	global_store_dwordx4 v[128:129], v[144:147], off offset:256 sc1
	v_add_f32_e32 v128, 1.0, v148
	v_add_f32_e32 v129, 1.0, v149
	v_mul_f32_e32 v144, 0xbfb8aa3b, v102
	v_mul_f32_e32 v145, 0xbfb8aa3b, v103
	v_mul_f32_e32 v146, 0xbfb8aa3b, v92
	v_mul_f32_e32 v147, 0xbfb8aa3b, v93
	v_mul_f32_e32 v148, 0xbfb8aa3b, v94
	v_mul_f32_e32 v149, 0xbfb8aa3b, v95
	v_exp_f32_e32 v144, v144
	v_exp_f32_e32 v145, v145
	v_exp_f32_e32 v146, v146
	v_exp_f32_e32 v147, v147
	v_exp_f32_e32 v148, v148
	v_exp_f32_e32 v149, v149
	v_add_f32_e32 v144, 1.0, v144
	v_add_f32_e32 v145, 1.0, v145
	v_add_f32_e32 v146, 1.0, v146
	v_add_f32_e32 v147, 1.0, v147
	v_add_f32_e32 v148, 1.0, v148
	v_add_f32_e32 v149, 1.0, v149
	v_rcp_f32_e32 v128, v128
	v_rcp_f32_e32 v129, v129
	v_rcp_f32_e32 v144, v144
	v_rcp_f32_e32 v145, v145
	v_rcp_f32_e32 v146, v146
	v_rcp_f32_e32 v147, v147
	v_rcp_f32_e32 v148, v148
	v_rcp_f32_e32 v149, v149
	v_pk_mul_f32 v[128:129], v[100:101], v[128:129]
	v_pk_mul_f32 v[150:151], v[102:103], v[144:145]
	v_pk_mul_f32 v[146:147], v[92:93], v[146:147]
	v_pk_mul_f32 v[148:149], v[94:95], v[148:149]
	v_cvt_pk_bf16_f32 v144, v128, v129
	v_cvt_pk_bf16_f32 v145, v150, v151
	v_cvt_pk_bf16_f32 v146, v146, v147
	v_cvt_pk_bf16_f32 v147, v148, v149
	v_mul_f32_e32 v128, 0xbfb8aa3b, v84
	v_mul_f32_e32 v129, 0xbfb8aa3b, v85
	global_store_dwordx4 v[130:131], v[144:147], off offset:256 sc1
	v_mul_f32_e32 v130, 0xbfb8aa3b, v86
	v_mul_f32_e32 v131, 0xbfb8aa3b, v87
	v_mul_f32_e32 v144, 0xbfb8aa3b, v76
	v_mul_f32_e32 v145, 0xbfb8aa3b, v77
	v_mul_f32_e32 v146, 0xbfb8aa3b, v78
	v_mul_f32_e32 v147, 0xbfb8aa3b, v79
	v_exp_f32_e32 v128, v128
	v_exp_f32_e32 v129, v129
	v_exp_f32_e32 v130, v130
	v_exp_f32_e32 v131, v131
	v_exp_f32_e32 v144, v144
	v_exp_f32_e32 v145, v145
	v_exp_f32_e32 v146, v146
	v_exp_f32_e32 v147, v147
	v_add_f32_e32 v128, 1.0, v128
	v_add_f32_e32 v129, 1.0, v129
	v_add_f32_e32 v130, 1.0, v130
	v_add_f32_e32 v131, 1.0, v131
	v_add_f32_e32 v144, 1.0, v144
	v_add_f32_e32 v145, 1.0, v145
	v_add_f32_e32 v146, 1.0, v146
	v_add_f32_e32 v147, 1.0, v147
	v_rcp_f32_e32 v128, v128
	v_rcp_f32_e32 v129, v129
	v_rcp_f32_e32 v130, v130
	v_rcp_f32_e32 v131, v131
	v_rcp_f32_e32 v144, v144
	v_rcp_f32_e32 v145, v145
	v_rcp_f32_e32 v146, v146
	v_rcp_f32_e32 v147, v147
	v_pk_mul_f32 v[128:129], v[84:85], v[128:129]
	v_pk_mul_f32 v[130:131], v[86:87], v[130:131]
	v_pk_mul_f32 v[144:145], v[76:77], v[144:145]
	v_pk_mul_f32 v[146:147], v[78:79], v[146:147]
	v_cvt_pk_bf16_f32 v128, v128, v129
	v_cvt_pk_bf16_f32 v129, v130, v131
	v_cvt_pk_bf16_f32 v130, v144, v145
	v_cvt_pk_bf16_f32 v131, v146, v147
	v_mul_f32_e32 v144, 0xbfb8aa3b, v68
	v_mul_f32_e32 v145, 0xbfb8aa3b, v69
	v_exp_f32_e32 v144, v144
	v_exp_f32_e32 v145, v145
	global_store_dwordx4 v[132:133], v[128:131], off offset:256 sc1
	v_mul_f32_e32 v132, 0xbfb8aa3b, v64
	v_mul_f32_e32 v133, 0xbfb8aa3b, v65
	v_mul_f32_e32 v130, 0xbfb8aa3b, v70
	v_mul_f32_e32 v131, 0xbfb8aa3b, v71
	v_exp_f32_e32 v130, v130
	v_exp_f32_e32 v131, v131
	v_exp_f32_e32 v132, v132
	v_exp_f32_e32 v133, v133
	v_add_f32_e32 v128, 1.0, v144
	v_add_f32_e32 v129, 1.0, v145
	v_mul_f32_e32 v144, 0xbfb8aa3b, v66
	v_mul_f32_e32 v145, 0xbfb8aa3b, v67
	v_add_f32_e32 v130, 1.0, v130
	v_add_f32_e32 v131, 1.0, v131
	v_add_f32_e32 v132, 1.0, v132
	v_add_f32_e32 v133, 1.0, v133
	v_exp_f32_e32 v144, v144
	v_exp_f32_e32 v145, v145
	v_rcp_f32_e32 v128, v128
	v_rcp_f32_e32 v129, v129
	v_rcp_f32_e32 v130, v130
	v_rcp_f32_e32 v131, v131
	v_rcp_f32_e32 v132, v132
	v_rcp_f32_e32 v133, v133
	v_add_f32_e32 v144, 1.0, v144
	v_add_f32_e32 v145, 1.0, v145
	v_rcp_f32_e32 v144, v144
	v_rcp_f32_e32 v145, v145
	v_pk_mul_f32 v[128:129], v[68:69], v[128:129]
	v_pk_mul_f32 v[130:131], v[70:71], v[130:131]
	v_pk_mul_f32 v[132:133], v[64:65], v[132:133]
	v_cvt_pk_bf16_f32 v128, v128, v129
	v_cvt_pk_bf16_f32 v129, v130, v131
	v_cvt_pk_bf16_f32 v130, v132, v133
	v_mul_f32_e32 v132, 0xbfb8aa3b, v52
	v_mul_f32_e32 v133, 0xbfb8aa3b, v53
	v_exp_f32_e32 v132, v132
	v_exp_f32_e32 v133, v133
	v_pk_mul_f32 v[144:145], v[66:67], v[144:145]
	s_nop 0
	v_cvt_pk_bf16_f32 v131, v144, v145
	global_store_dwordx4 v[134:135], v[128:131], off offset:256 sc1
	v_mul_f32_e32 v134, 0xbfb8aa3b, v46
	v_mul_f32_e32 v135, 0xbfb8aa3b, v47
	v_add_f32_e32 v128, 1.0, v132
	v_add_f32_e32 v129, 1.0, v133
	v_mul_f32_e32 v130, 0xbfb8aa3b, v54
	v_mul_f32_e32 v131, 0xbfb8aa3b, v55
	v_mul_f32_e32 v132, 0xbfb8aa3b, v44
	v_mul_f32_e32 v133, 0xbfb8aa3b, v45
	v_exp_f32_e32 v130, v130
	v_exp_f32_e32 v131, v131
	v_exp_f32_e32 v132, v132
	v_exp_f32_e32 v133, v133
	v_add_f32_e32 v130, 1.0, v130
	v_add_f32_e32 v131, 1.0, v131
	v_add_f32_e32 v132, 1.0, v132
	v_add_f32_e32 v133, 1.0, v133
	v_exp_f32_e32 v134, v134
	v_exp_f32_e32 v135, v135
	v_rcp_f32_e32 v128, v128
	v_rcp_f32_e32 v129, v129
	v_rcp_f32_e32 v130, v130
	v_rcp_f32_e32 v131, v131
	v_rcp_f32_e32 v132, v132
	v_rcp_f32_e32 v133, v133
	v_add_f32_e32 v134, 1.0, v134
	v_add_f32_e32 v135, 1.0, v135
	v_rcp_f32_e32 v134, v134
	v_rcp_f32_e32 v135, v135
	v_pk_mul_f32 v[128:129], v[52:53], v[128:129]
	v_pk_mul_f32 v[130:131], v[54:55], v[130:131]
	v_pk_mul_f32 v[132:133], v[44:45], v[132:133]
	v_cvt_pk_bf16_f32 v128, v128, v129
	v_cvt_pk_bf16_f32 v129, v130, v131
	v_cvt_pk_bf16_f32 v130, v132, v133
	v_mul_f32_e32 v132, 0xbfb8aa3b, v36
	v_mul_f32_e32 v133, 0xbfb8aa3b, v37
	v_exp_f32_e32 v132, v132
	v_exp_f32_e32 v133, v133
	v_pk_mul_f32 v[134:135], v[46:47], v[134:135]
	s_nop 0
	v_cvt_pk_bf16_f32 v131, v134, v135
	global_store_dwordx4 v[136:137], v[128:131], off offset:256 sc1
	v_mul_f32_e32 v134, 0xbfb8aa3b, v30
	v_mul_f32_e32 v135, 0xbfb8aa3b, v31
	v_add_f32_e32 v128, 1.0, v132
	v_add_f32_e32 v129, 1.0, v133
	v_mul_f32_e32 v130, 0xbfb8aa3b, v38
	v_mul_f32_e32 v131, 0xbfb8aa3b, v39
	v_mul_f32_e32 v132, 0xbfb8aa3b, v28
	v_mul_f32_e32 v133, 0xbfb8aa3b, v29
	v_exp_f32_e32 v130, v130
	v_exp_f32_e32 v131, v131
	v_exp_f32_e32 v132, v132
	v_exp_f32_e32 v133, v133
	v_add_f32_e32 v130, 1.0, v130
	v_add_f32_e32 v131, 1.0, v131
	v_add_f32_e32 v132, 1.0, v132
	v_add_f32_e32 v133, 1.0, v133
	v_exp_f32_e32 v134, v134
	v_exp_f32_e32 v135, v135
	v_rcp_f32_e32 v128, v128
	v_rcp_f32_e32 v129, v129
	v_rcp_f32_e32 v130, v130
	v_rcp_f32_e32 v131, v131
	v_rcp_f32_e32 v132, v132
	v_rcp_f32_e32 v133, v133
	v_add_f32_e32 v134, 1.0, v134
	v_add_f32_e32 v135, 1.0, v135
	v_rcp_f32_e32 v134, v134
	v_rcp_f32_e32 v135, v135
	v_pk_mul_f32 v[128:129], v[36:37], v[128:129]
	v_pk_mul_f32 v[130:131], v[38:39], v[130:131]
	v_pk_mul_f32 v[132:133], v[28:29], v[132:133]
	v_cvt_pk_bf16_f32 v128, v128, v129
	v_cvt_pk_bf16_f32 v129, v130, v131
	v_cvt_pk_bf16_f32 v130, v132, v133
	v_mul_f32_e32 v132, 0xbfb8aa3b, v20
	v_mul_f32_e32 v133, 0xbfb8aa3b, v21
	v_exp_f32_e32 v132, v132
	v_exp_f32_e32 v133, v133
	v_pk_mul_f32 v[134:135], v[30:31], v[134:135]
	s_nop 0
	v_cvt_pk_bf16_f32 v131, v134, v135
	global_store_dwordx4 v[138:139], v[128:131], off offset:256 sc1
	v_mul_f32_e32 v134, 0xbfb8aa3b, v14
	v_mul_f32_e32 v135, 0xbfb8aa3b, v15
	v_add_f32_e32 v128, 1.0, v132
	v_add_f32_e32 v129, 1.0, v133
	v_mul_f32_e32 v130, 0xbfb8aa3b, v22
	v_mul_f32_e32 v131, 0xbfb8aa3b, v23
	v_mul_f32_e32 v132, 0xbfb8aa3b, v12
	v_mul_f32_e32 v133, 0xbfb8aa3b, v13
	v_exp_f32_e32 v130, v130
	v_exp_f32_e32 v131, v131
	v_exp_f32_e32 v132, v132
	v_exp_f32_e32 v133, v133
	v_add_f32_e32 v130, 1.0, v130
	v_add_f32_e32 v131, 1.0, v131
	v_add_f32_e32 v132, 1.0, v132
	v_add_f32_e32 v133, 1.0, v133
	v_exp_f32_e32 v134, v134
	v_exp_f32_e32 v135, v135
	v_rcp_f32_e32 v128, v128
	v_rcp_f32_e32 v129, v129
	v_rcp_f32_e32 v130, v130
	v_rcp_f32_e32 v131, v131
	v_rcp_f32_e32 v132, v132
	v_rcp_f32_e32 v133, v133
	v_add_f32_e32 v134, 1.0, v134
	v_add_f32_e32 v135, 1.0, v135
	v_rcp_f32_e32 v134, v134
	v_rcp_f32_e32 v135, v135
	v_pk_mul_f32 v[128:129], v[20:21], v[128:129]
	v_pk_mul_f32 v[130:131], v[22:23], v[130:131]
	v_pk_mul_f32 v[132:133], v[12:13], v[132:133]
	v_cvt_pk_bf16_f32 v128, v128, v129
	v_cvt_pk_bf16_f32 v129, v130, v131
	v_cvt_pk_bf16_f32 v130, v132, v133
	v_mul_f32_e32 v132, 0xbfb8aa3b, v4
	v_mul_f32_e32 v133, 0xbfb8aa3b, v5
	v_exp_f32_e32 v132, v132
	v_exp_f32_e32 v133, v133
	v_pk_mul_f32 v[134:135], v[14:15], v[134:135]
	s_nop 0
	v_cvt_pk_bf16_f32 v131, v134, v135
	global_store_dwordx4 v[140:141], v[128:131], off offset:256 sc1
	v_mul_f32_e32 v134, 0xbfb8aa3b, v2
	v_mul_f32_e32 v135, 0xbfb8aa3b, v3
	v_add_f32_e32 v128, 1.0, v132
	v_add_f32_e32 v129, 1.0, v133
	v_mul_f32_e32 v130, 0xbfb8aa3b, v6
	v_mul_f32_e32 v131, 0xbfb8aa3b, v7
	v_mul_f32_e32 v132, 0xbfb8aa3b, v0
	v_mul_f32_e32 v133, 0xbfb8aa3b, v1
	v_exp_f32_e32 v130, v130
	v_exp_f32_e32 v131, v131
	v_exp_f32_e32 v132, v132
	v_exp_f32_e32 v133, v133
	v_exp_f32_e32 v134, v134
	v_exp_f32_e32 v135, v135
	v_add_f32_e32 v130, 1.0, v130
	v_add_f32_e32 v131, 1.0, v131
	v_add_f32_e32 v132, 1.0, v132
	v_add_f32_e32 v133, 1.0, v133
	v_add_f32_e32 v134, 1.0, v134
	v_add_f32_e32 v135, 1.0, v135
	v_rcp_f32_e32 v128, v128
	v_rcp_f32_e32 v129, v129
	v_rcp_f32_e32 v130, v130
	v_rcp_f32_e32 v131, v131
	v_rcp_f32_e32 v132, v132
	v_rcp_f32_e32 v133, v133
	v_rcp_f32_e32 v134, v134
	v_rcp_f32_e32 v135, v135
	v_pk_mul_f32 v[128:129], v[4:5], v[128:129]
	v_pk_mul_f32 v[130:131], v[6:7], v[130:131]
	v_pk_mul_f32 v[132:133], v[0:1], v[132:133]
	v_pk_mul_f32 v[134:135], v[2:3], v[134:135]
	v_cvt_pk_bf16_f32 v128, v128, v129
	v_cvt_pk_bf16_f32 v129, v130, v131
	v_cvt_pk_bf16_f32 v130, v132, v133
	v_cvt_pk_bf16_f32 v131, v134, v135
	global_store_dwordx4 v[142:143], v[128:131], off offset:256 sc1

.LBB0_414:
	s_andn2_b64 vcc, exec, s[0:1]
	s_cbranch_vccnz .LBB0_416
	v_lshlrev_b32_e32 v172, 1, v223
	v_ashrrev_i32_e32 v187, 31, v186
	v_or_b32_e32 v136, 16, v186
	v_lshl_add_u64 v[132:133], s[86:87], 0, v[172:173]
	v_lshlrev_b64 v[134:135], 11, v[186:187]
	v_ashrrev_i32_e32 v137, 31, v136
	v_or_b32_e32 v138, 32, v186
	v_cvt_pk_bf16_f32 v128, v124, v125
	v_cvt_pk_bf16_f32 v129, v126, v127
	v_cvt_pk_bf16_f32 v130, v120, v121
	v_cvt_pk_bf16_f32 v131, v122, v123
	v_lshl_add_u64 v[134:135], v[132:133], 0, v[134:135]
	v_lshlrev_b64 v[136:137], 11, v[136:137]
	v_ashrrev_i32_e32 v139, 31, v138
	v_or_b32_e32 v140, 48, v186
	global_store_dwordx4 v[134:135], v[128:131], off sc1
	v_lshl_add_u64 v[136:137], v[132:133], 0, v[136:137]
	v_lshlrev_b64 v[138:139], 11, v[138:139]
	v_cvt_pk_bf16_f32 v128, v112, v113
	v_cvt_pk_bf16_f32 v129, v114, v115
	v_cvt_pk_bf16_f32 v130, v104, v105
	v_cvt_pk_bf16_f32 v131, v106, v107
	v_ashrrev_i32_e32 v141, 31, v140
	global_store_dwordx4 v[136:137], v[128:131], off sc1
	v_lshl_add_u64 v[138:139], v[132:133], 0, v[138:139]
	v_lshlrev_b64 v[140:141], 11, v[140:141]
	v_cvt_pk_bf16_f32 v128, v96, v97
	v_cvt_pk_bf16_f32 v129, v98, v99
	v_cvt_pk_bf16_f32 v130, v88, v89
	v_cvt_pk_bf16_f32 v131, v90, v91
	v_add_co_u32_e32 v142, vcc, s93, v134
	global_store_dwordx4 v[138:139], v[128:131], off sc1
	v_lshl_add_u64 v[132:133], v[132:133], 0, v[140:141]
	v_addc_co_u32_e32 v143, vcc, 0, v135, vcc
	v_cvt_pk_bf16_f32 v128, v80, v81
	v_cvt_pk_bf16_f32 v129, v82, v83
	v_cvt_pk_bf16_f32 v130, v72, v73
	v_cvt_pk_bf16_f32 v131, v74, v75
	global_store_dwordx4 v[132:133], v[128:131], off sc1
	s_mov_b64 s[0:1], 0x48000
	v_add_co_u32_e32 v144, vcc, s96, v134
	v_cvt_pk_bf16_f32 v128, v60, v61
	v_cvt_pk_bf16_f32 v129, v62, v63
	v_cvt_pk_bf16_f32 v130, v56, v57
	v_cvt_pk_bf16_f32 v131, v58, v59
	global_store_dwordx4 v[142:143], v[128:131], off sc1
	v_lshl_add_u64 v[142:143], v[134:135], 0, s[0:1]
	v_addc_co_u32_e32 v145, vcc, 0, v135, vcc
	v_cvt_pk_bf16_f32 v128, v48, v49
	v_cvt_pk_bf16_f32 v129, v50, v51
	v_cvt_pk_bf16_f32 v130, v40, v41
	v_cvt_pk_bf16_f32 v131, v42, v43
	s_mov_b64 s[0:1], 0x50000
	global_store_dwordx4 v[144:145], v[128:131], off sc1
	v_lshl_add_u64 v[144:145], v[134:135], 0, s[0:1]
	s_mov_b32 s0, 0x50000
	v_add_co_u32_e32 v146, vcc, s0, v134
	v_cvt_pk_bf16_f32 v128, v32, v33
	v_cvt_pk_bf16_f32 v129, v34, v35
	v_cvt_pk_bf16_f32 v130, v24, v25
	v_cvt_pk_bf16_f32 v131, v26, v27
	v_addc_co_u32_e32 v147, vcc, 0, v135, vcc
	s_mov_b64 s[0:1], 0x58000
	global_store_dwordx4 v[146:147], v[128:131], off sc1
	v_lshl_add_u64 v[146:147], v[134:135], 0, s[0:1]
	s_mov_b32 s0, 0x58000
	v_add_co_u32_e32 v148, vcc, s0, v134
	v_cvt_pk_bf16_f32 v128, v16, v17
	v_cvt_pk_bf16_f32 v129, v18, v19
	v_cvt_pk_bf16_f32 v130, v8, v9
	v_cvt_pk_bf16_f32 v131, v10, v11
	v_addc_co_u32_e32 v149, vcc, 0, v135, vcc
	global_store_dwordx4 v[148:149], v[128:131], off sc1
	v_lshl_add_u64 v[140:141], v[134:135], 0, s[4:5]
	s_nop 0
	v_cvt_pk_bf16_f32 v128, v116, v117
	v_cvt_pk_bf16_f32 v129, v118, v119
	v_cvt_pk_bf16_f32 v130, v108, v109
	v_cvt_pk_bf16_f32 v131, v110, v111
	global_store_dwordx4 v[134:135], v[128:131], off offset:256 sc1
	s_nop 1
	v_cvt_pk_bf16_f32 v128, v100, v101
	v_cvt_pk_bf16_f32 v129, v102, v103
	v_cvt_pk_bf16_f32 v130, v92, v93
	v_cvt_pk_bf16_f32 v131, v94, v95
	global_store_dwordx4 v[136:137], v[128:131], off offset:256 sc1
	s_nop 1
	v_cvt_pk_bf16_f32 v128, v84, v85
	v_cvt_pk_bf16_f32 v129, v86, v87
	v_cvt_pk_bf16_f32 v130, v76, v77
	v_cvt_pk_bf16_f32 v131, v78, v79
	global_store_dwordx4 v[138:139], v[128:131], off offset:256 sc1
	s_nop 1
	v_cvt_pk_bf16_f32 v128, v68, v69
	v_cvt_pk_bf16_f32 v129, v70, v71
	v_cvt_pk_bf16_f32 v130, v64, v65
	v_cvt_pk_bf16_f32 v131, v66, v67
	global_store_dwordx4 v[132:133], v[128:131], off offset:256 sc1
	s_nop 1
	v_cvt_pk_bf16_f32 v128, v52, v53
	v_cvt_pk_bf16_f32 v129, v54, v55
	v_cvt_pk_bf16_f32 v130, v44, v45
	v_cvt_pk_bf16_f32 v131, v46, v47
	global_store_dwordx4 v[140:141], v[128:131], off offset:256 sc1
	s_nop 1
	v_cvt_pk_bf16_f32 v128, v36, v37
	v_cvt_pk_bf16_f32 v129, v38, v39
	v_cvt_pk_bf16_f32 v130, v28, v29
	v_cvt_pk_bf16_f32 v131, v30, v31
	global_store_dwordx4 v[142:143], v[128:131], off offset:256 sc1
	s_nop 1
	v_cvt_pk_bf16_f32 v128, v20, v21
	v_cvt_pk_bf16_f32 v129, v22, v23
	v_cvt_pk_bf16_f32 v130, v12, v13
	v_cvt_pk_bf16_f32 v131, v14, v15
	global_store_dwordx4 v[144:145], v[128:131], off offset:256 sc1
	s_nop 1
	v_cvt_pk_bf16_f32 v128, v4, v5
	v_cvt_pk_bf16_f32 v129, v6, v7
	v_cvt_pk_bf16_f32 v130, v0, v1
	v_cvt_pk_bf16_f32 v131, v2, v3
	global_store_dwordx4 v[146:147], v[128:131], off offset:256 sc1

.LBB0_417:
	s_lshl_b32 s0, s38, 7
	s_add_i32 s0, s89, s0
	v_pk_mul_f32 v[116:117], v[124:125], v[116:117]
	v_ashrrev_i32_e32 v187, 31, v186
	v_or_b32_e32 v172, s0, v222
	v_pk_mul_f32 v[118:119], v[126:127], v[118:119]
	v_pk_mul_f32 v[122:123], v[122:123], v[110:111]
	v_pk_mul_f32 v[110:111], v[120:121], v[108:109]
	v_cvt_pk_bf16_f32 v108, v116, v117
	v_lshlrev_b64 v[116:117], 11, v[186:187]
	v_cvt_pk_bf16_f32 v109, v118, v119
	v_lshl_add_u64 v[116:117], s[34:35], 0, v[116:117]
	v_lshlrev_b64 v[118:119], 1, v[172:173]
	v_lshl_add_u64 v[116:117], v[116:117], 0, v[118:119]
	v_pk_mul_f32 v[52:53], v[60:61], v[52:53]
	v_pk_mul_f32 v[58:59], v[58:59], v[46:47]
	v_pk_mul_f32 v[46:47], v[56:57], v[44:45]
	v_cvt_pk_bf16_f32 v44, v52, v53
	v_add_co_u32_e32 v52, vcc, s93, v116
	v_pk_mul_f32 v[36:37], v[48:49], v[36:37]
	s_nop 0
	v_addc_co_u32_e32 v53, vcc, 0, v117, vcc
	v_pk_mul_f32 v[100:101], v[112:113], v[100:101]
	v_pk_mul_f32 v[84:85], v[96:97], v[84:85]
	v_pk_mul_f32 v[68:69], v[80:81], v[68:69]
	v_pk_mul_f32 v[42:43], v[42:43], v[30:31]
	v_pk_mul_f32 v[30:31], v[40:41], v[28:29]
	v_cvt_pk_bf16_f32 v28, v36, v37
	v_add_co_u32_e32 v36, vcc, s96, v116
	v_pk_mul_f32 v[106:107], v[106:107], v[94:95]
	v_pk_mul_f32 v[94:95], v[104:105], v[92:93]
	v_cvt_pk_bf16_f32 v92, v100, v101
	v_or_b32_e32 v100, 16, v186
	v_pk_mul_f32 v[90:91], v[90:91], v[78:79]
	v_pk_mul_f32 v[78:79], v[88:89], v[76:77]
	v_cvt_pk_bf16_f32 v76, v84, v85
	v_or_b32_e32 v84, 32, v186
	v_pk_mul_f32 v[74:75], v[74:75], v[66:67]
	v_pk_mul_f32 v[66:67], v[72:73], v[64:65]
	v_cvt_pk_bf16_f32 v64, v68, v69
	v_or_b32_e32 v68, 48, v186
	v_addc_co_u32_e32 v37, vcc, 0, v117, vcc
	v_pk_mul_f32 v[20:21], v[32:33], v[20:21]
	s_mov_b32 s0, 0x50000
	v_ashrrev_i32_e32 v101, 31, v100
	v_ashrrev_i32_e32 v85, 31, v84
	v_ashrrev_i32_e32 v69, 31, v68
	v_pk_mul_f32 v[26:27], v[26:27], v[14:15]
	v_pk_mul_f32 v[14:15], v[24:25], v[12:13]
	v_cvt_pk_bf16_f32 v12, v20, v21
	v_add_co_u32_e32 v20, vcc, s0, v116
	v_lshlrev_b64 v[100:101], 11, v[100:101]
	v_lshlrev_b64 v[84:85], 11, v[84:85]
	v_lshlrev_b64 v[68:69], 11, v[68:69]
	v_addc_co_u32_e32 v21, vcc, 0, v117, vcc
	v_pk_mul_f32 v[4:5], v[16:17], v[4:5]
	v_pk_mul_f32 v[102:103], v[114:115], v[102:103]
	v_lshl_add_u64 v[100:101], s[34:35], 0, v[100:101]
	v_pk_mul_f32 v[86:87], v[98:99], v[86:87]
	v_lshl_add_u64 v[84:85], s[34:35], 0, v[84:85]
	v_pk_mul_f32 v[70:71], v[82:83], v[70:71]
	v_lshl_add_u64 v[68:69], s[34:35], 0, v[68:69]
	v_pk_mul_f32 v[54:55], v[62:63], v[54:55]
	v_pk_mul_f32 v[38:39], v[50:51], v[38:39]
	v_pk_mul_f32 v[22:23], v[34:35], v[22:23]
	v_pk_mul_f32 v[6:7], v[18:19], v[6:7]
	v_pk_mul_f32 v[10:11], v[10:11], v[2:3]
	v_pk_mul_f32 v[2:3], v[8:9], v[0:1]
	v_cvt_pk_bf16_f32 v0, v4, v5
	v_add_co_u32_e32 v4, vcc, 0x58000, v116
	v_cvt_pk_bf16_f32 v110, v110, v111
	v_cvt_pk_bf16_f32 v111, v122, v123
	v_cvt_pk_bf16_f32 v93, v102, v103
	v_cvt_pk_bf16_f32 v94, v94, v95
	v_cvt_pk_bf16_f32 v95, v106, v107
	v_lshl_add_u64 v[100:101], v[100:101], 0, v[118:119]
	v_cvt_pk_bf16_f32 v77, v86, v87
	v_cvt_pk_bf16_f32 v78, v78, v79
	v_cvt_pk_bf16_f32 v79, v90, v91
	v_lshl_add_u64 v[84:85], v[84:85], 0, v[118:119]
	v_cvt_pk_bf16_f32 v65, v70, v71
	v_cvt_pk_bf16_f32 v66, v66, v67
	v_cvt_pk_bf16_f32 v67, v74, v75
	v_lshl_add_u64 v[68:69], v[68:69], 0, v[118:119]
	v_cvt_pk_bf16_f32 v45, v54, v55
	v_cvt_pk_bf16_f32 v46, v46, v47
	v_cvt_pk_bf16_f32 v47, v58, v59
	v_cvt_pk_bf16_f32 v29, v38, v39
	v_cvt_pk_bf16_f32 v30, v30, v31
	v_cvt_pk_bf16_f32 v31, v42, v43
	v_cvt_pk_bf16_f32 v13, v22, v23
	v_cvt_pk_bf16_f32 v14, v14, v15
	v_cvt_pk_bf16_f32 v15, v26, v27
	v_cvt_pk_bf16_f32 v1, v6, v7
	v_cvt_pk_bf16_f32 v2, v2, v3
	v_cvt_pk_bf16_f32 v3, v10, v11
	v_addc_co_u32_e32 v5, vcc, 0, v117, vcc
	global_store_dwordx4 v[116:117], v[108:111], off sc1
	global_store_dwordx4 v[100:101], v[92:95], off sc1
	global_store_dwordx4 v[84:85], v[76:79], off sc1
	global_store_dwordx4 v[68:69], v[64:67], off sc1
	global_store_dwordx4 v[52:53], v[44:47], off sc1
	global_store_dwordx4 v[36:37], v[28:31], off sc1
	global_store_dwordx4 v[20:21], v[12:15], off sc1
	global_store_dwordx4 v[4:5], v[0:3], off sc1
	s_andn2_b64 vcc, exec, s[36:37]
	s_mov_b64 s[0:1], -1
	s_cbranch_vccnz .LBB0_382

.LBB0_859:
	v_mov_b32_e32 v131, v132
	s_lshl_b32 s24, s24, 8
	s_add_i32 s24, s24, s70
	v_and_or_b32 v130, v131, 15, s24
	s_lshl_b32 s24, s25, 8
	v_lshrrev_b32_e32 v131, 1, v131
	v_and_or_b32 v131, v131, 24, s24
	v_or_b32_e32 v136, s71, v131
	v_ashrrev_i32_e32 v131, 31, v130
	v_ashrrev_i32_e32 v137, 31, v136
	v_lshlrev_b64 v[138:139], 11, v[130:131]
	v_lshl_add_u64 v[138:139], s[2:3], 0, v[138:139]
	v_lshlrev_b64 v[136:137], 1, v[136:137]
	v_lshl_add_u64 v[138:139], v[138:139], 0, v[136:137]
	v_cvt_pk_bf16_f32 v60, v60, v61
	v_cvt_pk_bf16_f32 v61, v62, v63
	v_cvt_pk_bf16_f32 v62, v56, v57
	v_add_co_u32_e32 v56, vcc, s93, v138
	v_cvt_pk_bf16_f32 v68, v68, v69
	v_cvt_pk_bf16_f32 v69, v70, v71
	v_cvt_pk_bf16_f32 v70, v64, v65
	v_lshl_add_u64 v[64:65], v[138:139], 0, s[4:5]
	v_addc_co_u32_e32 v57, vcc, 0, v139, vcc
	v_cvt_pk_bf16_f32 v44, v44, v45
	v_cvt_pk_bf16_f32 v45, v46, v47
	v_cvt_pk_bf16_f32 v46, v40, v41
	v_cvt_pk_bf16_f32 v47, v42, v43
	s_mov_b64 s[24:25], 0x48000
	v_cvt_pk_bf16_f32 v108, v108, v109
	v_cvt_pk_bf16_f32 v109, v110, v111
	v_cvt_pk_bf16_f32 v110, v104, v105
	v_or_b32_e32 v104, 16, v130
	global_store_dwordx4 v[64:65], v[44:47], off offset:256 sc1
	v_cvt_pk_bf16_f32 v28, v28, v29
	v_cvt_pk_bf16_f32 v29, v30, v31
	v_lshl_add_u64 v[44:45], v[138:139], 0, s[24:25]
	v_add_co_u32_e32 v46, vcc, s96, v138
	v_cvt_pk_bf16_f32 v30, v24, v25
	v_cvt_pk_bf16_f32 v31, v26, v27
	s_mov_b64 s[24:25], 0x50000
	v_ashrrev_i32_e32 v105, 31, v104
	v_cvt_pk_bf16_f32 v92, v92, v93
	v_cvt_pk_bf16_f32 v93, v94, v95
	v_cvt_pk_bf16_f32 v94, v88, v89
	v_or_b32_e32 v88, 32, v130
	v_addc_co_u32_e32 v47, vcc, 0, v139, vcc
	global_store_dwordx4 v[44:45], v[28:31], off offset:256 sc1
	v_lshlrev_b64 v[104:105], 11, v[104:105]
	v_ashrrev_i32_e32 v89, 31, v88
	v_lshl_add_u64 v[28:29], v[138:139], 0, s[24:25]
	s_mov_b32 s24, 0x50000
	v_cvt_pk_bf16_f32 v76, v76, v77
	v_cvt_pk_bf16_f32 v77, v78, v79
	v_cvt_pk_bf16_f32 v78, v72, v73
	v_or_b32_e32 v72, 48, v130
	v_add_co_u32_e32 v30, vcc, s24, v138
	v_cvt_pk_bf16_f32 v12, v12, v13
	v_cvt_pk_bf16_f32 v13, v14, v15
	v_cvt_pk_bf16_f32 v14, v8, v9
	v_cvt_pk_bf16_f32 v15, v10, v11
	s_mov_b64 s[24:25], 0x58000
	v_cvt_pk_bf16_f32 v111, v106, v107
	v_lshl_add_u64 v[104:105], s[2:3], 0, v[104:105]
	v_lshlrev_b64 v[88:89], 11, v[88:89]
	v_ashrrev_i32_e32 v73, 31, v72
	v_addc_co_u32_e32 v31, vcc, 0, v139, vcc
	global_store_dwordx4 v[28:29], v[12:15], off offset:256 sc1
	global_store_dwordx4 v[138:139], v[108:111], off offset:256 sc1
	v_cvt_pk_bf16_f32 v95, v90, v91
	v_lshl_add_u64 v[12:13], v[138:139], 0, s[24:25]
	s_mov_b32 s24, 0x58000
	v_lshl_add_u64 v[108:109], v[104:105], 0, v[136:137]
	v_lshl_add_u64 v[88:89], s[2:3], 0, v[88:89]
	v_lshlrev_b64 v[72:73], 11, v[72:73]
	v_add_co_u32_e32 v14, vcc, s24, v138
	global_store_dwordx4 v[108:109], v[92:95], off offset:256 sc1
	v_cvt_pk_bf16_f32 v79, v74, v75
	v_lshl_add_u64 v[72:73], s[2:3], 0, v[72:73]
	v_lshl_add_u64 v[92:93], v[88:89], 0, v[136:137]
	v_addc_co_u32_e32 v15, vcc, 0, v139, vcc
	v_cvt_pk_bf16_f32 v124, v124, v125
	v_cvt_pk_bf16_f32 v125, v126, v127
	v_cvt_pk_bf16_f32 v126, v120, v121
	v_cvt_pk_bf16_f32 v127, v122, v123
	v_cvt_pk_bf16_f32 v104, v116, v117
	v_cvt_pk_bf16_f32 v105, v118, v119
	v_cvt_pk_bf16_f32 v106, v112, v113
	v_cvt_pk_bf16_f32 v107, v114, v115
	v_cvt_pk_bf16_f32 v88, v100, v101
	v_cvt_pk_bf16_f32 v89, v102, v103
	v_cvt_pk_bf16_f32 v90, v96, v97
	v_cvt_pk_bf16_f32 v91, v98, v99
	global_store_dwordx4 v[92:93], v[76:79], off offset:256 sc1
	v_cvt_pk_bf16_f32 v74, v80, v81
	v_cvt_pk_bf16_f32 v75, v82, v83
	v_lshl_add_u64 v[76:77], v[72:73], 0, v[136:137]
	v_cvt_pk_bf16_f32 v72, v84, v85
	v_cvt_pk_bf16_f32 v73, v86, v87
	v_cvt_pk_bf16_f32 v71, v66, v67
	v_cvt_pk_bf16_f32 v63, v58, v59
	v_cvt_pk_bf16_f32 v40, v52, v53
	v_cvt_pk_bf16_f32 v41, v54, v55
	v_cvt_pk_bf16_f32 v42, v48, v49
	v_cvt_pk_bf16_f32 v43, v50, v51
	v_cvt_pk_bf16_f32 v24, v36, v37
	v_cvt_pk_bf16_f32 v25, v38, v39
	v_cvt_pk_bf16_f32 v26, v32, v33
	v_cvt_pk_bf16_f32 v27, v34, v35
	v_cvt_pk_bf16_f32 v8, v20, v21
	v_cvt_pk_bf16_f32 v9, v22, v23
	v_cvt_pk_bf16_f32 v10, v16, v17
	v_cvt_pk_bf16_f32 v11, v18, v19
	v_cvt_pk_bf16_f32 v4, v4, v5
	v_cvt_pk_bf16_f32 v5, v6, v7
	v_cvt_pk_bf16_f32 v6, v0, v1
	v_cvt_pk_bf16_f32 v7, v2, v3
	s_andn2_b64 vcc, exec, s[36:37]
	s_mov_b64 s[24:25], -1
	global_store_dwordx4 v[138:139], v[124:127], off sc1
	global_store_dwordx4 v[108:109], v[104:107], off sc1
	global_store_dwordx4 v[92:93], v[88:91], off sc1
	global_store_dwordx4 v[76:77], v[72:75], off sc1
	global_store_dwordx4 v[76:77], v[68:71], off offset:256 sc1
	global_store_dwordx4 v[56:57], v[60:63], off sc1
	global_store_dwordx4 v[46:47], v[40:43], off sc1
	global_store_dwordx4 v[30:31], v[24:27], off sc1
	global_store_dwordx4 v[14:15], v[8:11], off sc1
	global_store_dwordx4 v[12:13], v[4:7], off offset:256 sc1
	s_cbranch_vccnz .LBB0_848
	s_andn2_b64 vcc, exec, s[0:1]
	s_cbranch_vccnz .LBB0_847
	s_barrier
	s_branch .LBB0_847

.LBB0_973:
	v_mov_b32_e32 v136, v138
	s_lshl_b32 s21, s28, 8
	s_add_i32 s21, s21, s55
	v_and_or_b32 v144, v136, 15, s21
	s_lshl_b32 s21, s29, 7
	v_lshrrev_b32_e32 v136, 1, v136
	v_and_or_b32 v136, v136, 24, s21
	v_or_b32_e32 v146, s56, v136
	v_mul_f32_e32 v136, 0xbfb8aa3b, v124
	v_exp_f32_e32 v136, v136
	v_mul_f32_e32 v137, 0xbfb8aa3b, v125
	v_exp_f32_e32 v137, v137
	v_mul_f32_e32 v145, 0xbfb8aa3b, v126
	v_add_f32_e32 v136, 1.0, v136
	v_rcp_f32_e32 v148, v136
	v_add_f32_e32 v136, 1.0, v137
	v_rcp_f32_e32 v149, v136
	v_exp_f32_e32 v145, v145
	v_ashrrev_i32_e32 v147, 31, v146
	v_mov_b64_e32 v[136:137], s[8:9]
	v_pk_mul_f32 v[124:125], v[124:125], v[148:149]
	v_mul_f32_e32 v148, 0xbfb8aa3b, v127
	v_exp_f32_e32 v148, v148
	v_pk_mul_f32 v[120:121], v[124:125], v[120:121]
	v_add_f32_e32 v124, 1.0, v145
	v_mul_f32_e32 v145, 0xbfb8aa3b, v112
	v_add_f32_e32 v125, 1.0, v148
	v_rcp_f32_e32 v124, v124
	v_rcp_f32_e32 v125, v125
	v_exp_f32_e32 v145, v145
	v_mul_f32_e32 v148, 0xbfb8aa3b, v113
	v_exp_f32_e32 v148, v148
	v_pk_mul_f32 v[124:125], v[126:127], v[124:125]
	v_add_f32_e32 v126, 1.0, v145
	v_mul_f32_e32 v145, 0xbfb8aa3b, v114
	v_add_f32_e32 v127, 1.0, v148
	v_exp_f32_e32 v145, v145
	v_mul_f32_e32 v148, 0xbfb8aa3b, v115
	v_exp_f32_e32 v149, v148
	v_rcp_f32_e32 v126, v126
	v_add_f32_e32 v145, 1.0, v145
	v_rcp_f32_e32 v127, v127
	v_rcp_f32_e32 v148, v145
	v_add_f32_e32 v145, 1.0, v149
	v_rcp_f32_e32 v149, v145
	v_pk_mul_f32 v[112:113], v[112:113], v[126:127]
	v_mad_i64_i32 v[150:151], s[28:29], v144, s58, v[136:137]
	v_pk_mul_f32 v[116:117], v[112:113], v[116:117]
	v_pk_mul_f32 v[112:113], v[114:115], v[148:149]
	v_cvt_pk_bf16_f32 v116, v116, v117
	v_pk_mul_f32 v[118:119], v[112:113], v[118:119]
	v_pk_mul_f32 v[122:123], v[124:125], v[122:123]
	v_cvt_pk_bf16_f32 v117, v118, v119
	v_mul_f32_e32 v118, 0xbfb8aa3b, v108
	v_mul_f32_e32 v119, 0xbfb8aa3b, v109
	v_exp_f32_e32 v118, v118
	v_exp_f32_e32 v119, v119
	v_lshlrev_b64 v[112:113], 1, v[146:147]
	v_lshl_add_u64 v[124:125], v[150:151], 0, v[112:113]
	v_cvt_pk_bf16_f32 v114, v120, v121
	v_cvt_pk_bf16_f32 v115, v122, v123
	global_store_dwordx4 v[124:125], v[114:117], off sc1
	s_andn2_b64 vcc, exec, s[36:37]
	s_nop 0
	v_add_f32_e32 v114, 1.0, v118
	v_add_f32_e32 v115, 1.0, v119
	v_rcp_f32_e32 v114, v114
	v_rcp_f32_e32 v115, v115
	v_or_b32_e32 v116, 16, v144
	v_mad_i64_i32 v[116:117], s[28:29], v116, s58, v[136:137]
	v_pk_mul_f32 v[108:109], v[108:109], v[114:115]
	v_mul_f32_e32 v114, 0xbfb8aa3b, v110
	v_mul_f32_e32 v115, 0xbfb8aa3b, v111
	v_exp_f32_e32 v114, v114
	v_exp_f32_e32 v115, v115
	v_pk_mul_f32 v[104:105], v[108:109], v[104:105]
	v_add_f32_e32 v108, 1.0, v114
	v_add_f32_e32 v109, 1.0, v115
	v_mul_f32_e32 v114, 0xbfb8aa3b, v96
	v_mul_f32_e32 v115, 0xbfb8aa3b, v97
	v_rcp_f32_e32 v108, v108
	v_rcp_f32_e32 v109, v109
	v_exp_f32_e32 v114, v114
	v_exp_f32_e32 v115, v115
	v_pk_mul_f32 v[108:109], v[110:111], v[108:109]
	v_add_f32_e32 v110, 1.0, v114
	v_add_f32_e32 v111, 1.0, v115
	v_mul_f32_e32 v114, 0xbfb8aa3b, v98
	v_mul_f32_e32 v115, 0xbfb8aa3b, v99
	v_exp_f32_e32 v114, v114
	v_exp_f32_e32 v115, v115
	v_rcp_f32_e32 v110, v110
	v_rcp_f32_e32 v111, v111
	v_add_f32_e32 v114, 1.0, v114
	v_add_f32_e32 v115, 1.0, v115
	v_rcp_f32_e32 v114, v114
	v_rcp_f32_e32 v115, v115
	v_pk_mul_f32 v[96:97], v[96:97], v[110:111]
	v_pk_mul_f32 v[106:107], v[108:109], v[106:107]
	v_pk_mul_f32 v[100:101], v[96:97], v[100:101]
	v_pk_mul_f32 v[96:97], v[98:99], v[114:115]
	v_cvt_pk_bf16_f32 v98, v100, v101
	v_mul_f32_e32 v100, 0xbfb8aa3b, v92
	v_mul_f32_e32 v101, 0xbfb8aa3b, v93
	v_exp_f32_e32 v100, v100
	v_exp_f32_e32 v101, v101
	v_pk_mul_f32 v[102:103], v[96:97], v[102:103]
	v_lshl_add_u64 v[108:109], v[116:117], 0, v[112:113]
	v_cvt_pk_bf16_f32 v96, v104, v105
	v_cvt_pk_bf16_f32 v97, v106, v107
	v_cvt_pk_bf16_f32 v99, v102, v103
	global_store_dwordx4 v[108:109], v[96:99], off sc1
	s_nop 1
	v_add_f32_e32 v96, 1.0, v100
	v_add_f32_e32 v97, 1.0, v101
	v_rcp_f32_e32 v96, v96
	v_rcp_f32_e32 v97, v97
	v_or_b32_e32 v98, 32, v144
	v_mad_i64_i32 v[98:99], s[28:29], v98, s58, v[136:137]
	v_pk_mul_f32 v[92:93], v[92:93], v[96:97]
	v_mul_f32_e32 v96, 0xbfb8aa3b, v94
	v_mul_f32_e32 v97, 0xbfb8aa3b, v95
	v_exp_f32_e32 v96, v96
	v_exp_f32_e32 v97, v97
	v_pk_mul_f32 v[88:89], v[92:93], v[88:89]
	v_add_f32_e32 v92, 1.0, v96
	v_add_f32_e32 v93, 1.0, v97
	v_mul_f32_e32 v96, 0xbfb8aa3b, v80
	v_mul_f32_e32 v97, 0xbfb8aa3b, v81
	v_rcp_f32_e32 v92, v92
	v_rcp_f32_e32 v93, v93
	v_exp_f32_e32 v96, v96
	v_exp_f32_e32 v97, v97
	v_pk_mul_f32 v[92:93], v[94:95], v[92:93]
	v_add_f32_e32 v94, 1.0, v96
	v_add_f32_e32 v95, 1.0, v97
	v_mul_f32_e32 v96, 0xbfb8aa3b, v82
	v_mul_f32_e32 v97, 0xbfb8aa3b, v83
	v_exp_f32_e32 v96, v96
	v_exp_f32_e32 v97, v97
	v_rcp_f32_e32 v94, v94
	v_rcp_f32_e32 v95, v95
	v_add_f32_e32 v96, 1.0, v96
	v_add_f32_e32 v97, 1.0, v97
	v_rcp_f32_e32 v96, v96
	v_rcp_f32_e32 v97, v97
	v_pk_mul_f32 v[80:81], v[80:81], v[94:95]
	v_pk_mul_f32 v[90:91], v[92:93], v[90:91]
	v_pk_mul_f32 v[84:85], v[80:81], v[84:85]
	v_pk_mul_f32 v[80:81], v[82:83], v[96:97]
	v_cvt_pk_bf16_f32 v82, v84, v85
	v_mul_f32_e32 v84, 0xbfb8aa3b, v76
	v_mul_f32_e32 v85, 0xbfb8aa3b, v77
	v_exp_f32_e32 v84, v84
	v_exp_f32_e32 v85, v85
	v_pk_mul_f32 v[86:87], v[80:81], v[86:87]
	v_lshl_add_u64 v[92:93], v[98:99], 0, v[112:113]
	v_cvt_pk_bf16_f32 v80, v88, v89
	v_cvt_pk_bf16_f32 v81, v90, v91
	v_cvt_pk_bf16_f32 v83, v86, v87
	global_store_dwordx4 v[92:93], v[80:83], off sc1
	s_nop 1
	v_add_f32_e32 v80, 1.0, v84
	v_add_f32_e32 v81, 1.0, v85
	v_rcp_f32_e32 v80, v80
	v_rcp_f32_e32 v81, v81
	v_or_b32_e32 v82, 48, v144
	v_mad_i64_i32 v[82:83], s[28:29], v82, s58, v[136:137]
	v_pk_mul_f32 v[76:77], v[76:77], v[80:81]
	v_mul_f32_e32 v80, 0xbfb8aa3b, v78
	v_mul_f32_e32 v81, 0xbfb8aa3b, v79
	v_exp_f32_e32 v80, v80
	v_exp_f32_e32 v81, v81
	v_pk_mul_f32 v[72:73], v[76:77], v[72:73]
	v_add_f32_e32 v76, 1.0, v80
	v_add_f32_e32 v77, 1.0, v81
	v_mul_f32_e32 v80, 0xbfb8aa3b, v64
	v_mul_f32_e32 v81, 0xbfb8aa3b, v65
	v_rcp_f32_e32 v76, v76
	v_rcp_f32_e32 v77, v77
	v_exp_f32_e32 v80, v80
	v_exp_f32_e32 v81, v81
	v_pk_mul_f32 v[76:77], v[78:79], v[76:77]
	v_add_f32_e32 v78, 1.0, v80
	v_add_f32_e32 v79, 1.0, v81
	v_mul_f32_e32 v80, 0xbfb8aa3b, v66
	v_mul_f32_e32 v81, 0xbfb8aa3b, v67
	v_exp_f32_e32 v80, v80
	v_exp_f32_e32 v81, v81
	v_rcp_f32_e32 v78, v78
	v_rcp_f32_e32 v79, v79
	v_add_f32_e32 v80, 1.0, v80
	v_add_f32_e32 v81, 1.0, v81
	v_rcp_f32_e32 v80, v80
	v_rcp_f32_e32 v81, v81
	v_pk_mul_f32 v[64:65], v[64:65], v[78:79]
	v_pk_mul_f32 v[74:75], v[76:77], v[74:75]
	v_pk_mul_f32 v[68:69], v[64:65], v[68:69]
	v_pk_mul_f32 v[64:65], v[66:67], v[80:81]
	v_cvt_pk_bf16_f32 v66, v68, v69
	v_mul_f32_e32 v68, 0xbfb8aa3b, v60
	v_mul_f32_e32 v69, 0xbfb8aa3b, v61
	v_exp_f32_e32 v68, v68
	v_exp_f32_e32 v69, v69
	v_pk_mul_f32 v[70:71], v[64:65], v[70:71]
	v_lshl_add_u64 v[76:77], v[82:83], 0, v[112:113]
	v_cvt_pk_bf16_f32 v64, v72, v73
	v_cvt_pk_bf16_f32 v65, v74, v75
	v_cvt_pk_bf16_f32 v67, v70, v71
	global_store_dwordx4 v[76:77], v[64:67], off sc1
	s_nop 1
	v_add_f32_e32 v64, 1.0, v68
	v_add_f32_e32 v65, 1.0, v69
	v_rcp_f32_e32 v64, v64
	v_rcp_f32_e32 v65, v65
	v_add_u32_e32 v66, 0x80, v144
	v_mad_i64_i32 v[66:67], s[28:29], v66, s58, v[136:137]
	v_pk_mul_f32 v[60:61], v[60:61], v[64:65]
	v_mul_f32_e32 v64, 0xbfb8aa3b, v62
	v_mul_f32_e32 v65, 0xbfb8aa3b, v63
	v_exp_f32_e32 v64, v64
	v_exp_f32_e32 v65, v65
	v_pk_mul_f32 v[56:57], v[60:61], v[56:57]
	v_add_f32_e32 v60, 1.0, v64
	v_add_f32_e32 v61, 1.0, v65
	v_mul_f32_e32 v64, 0xbfb8aa3b, v48
	v_mul_f32_e32 v65, 0xbfb8aa3b, v49
	v_rcp_f32_e32 v60, v60
	v_rcp_f32_e32 v61, v61
	v_exp_f32_e32 v64, v64
	v_exp_f32_e32 v65, v65
	v_pk_mul_f32 v[60:61], v[62:63], v[60:61]
	v_add_f32_e32 v62, 1.0, v64
	v_add_f32_e32 v63, 1.0, v65
	v_mul_f32_e32 v64, 0xbfb8aa3b, v50
	v_mul_f32_e32 v65, 0xbfb8aa3b, v51
	v_exp_f32_e32 v64, v64
	v_exp_f32_e32 v65, v65
	v_rcp_f32_e32 v62, v62
	v_rcp_f32_e32 v63, v63
	v_add_f32_e32 v64, 1.0, v64
	v_add_f32_e32 v65, 1.0, v65
	v_rcp_f32_e32 v64, v64
	v_rcp_f32_e32 v65, v65
	v_pk_mul_f32 v[48:49], v[48:49], v[62:63]
	v_pk_mul_f32 v[58:59], v[60:61], v[58:59]
	v_pk_mul_f32 v[52:53], v[48:49], v[52:53]
	v_pk_mul_f32 v[48:49], v[50:51], v[64:65]
	v_cvt_pk_bf16_f32 v50, v52, v53
	v_mul_f32_e32 v52, 0xbfb8aa3b, v44
	v_mul_f32_e32 v53, 0xbfb8aa3b, v45
	v_exp_f32_e32 v52, v52
	v_exp_f32_e32 v53, v53
	v_pk_mul_f32 v[54:55], v[48:49], v[54:55]
	v_lshl_add_u64 v[60:61], v[66:67], 0, v[112:113]
	v_cvt_pk_bf16_f32 v48, v56, v57
	v_cvt_pk_bf16_f32 v49, v58, v59
	v_cvt_pk_bf16_f32 v51, v54, v55
	global_store_dwordx4 v[60:61], v[48:51], off sc1
	s_nop 1
	v_add_f32_e32 v48, 1.0, v52
	v_add_f32_e32 v49, 1.0, v53
	v_rcp_f32_e32 v48, v48
	v_rcp_f32_e32 v49, v49
	v_add_u32_e32 v50, 0x90, v144
	v_mad_i64_i32 v[50:51], s[28:29], v50, s58, v[136:137]
	v_pk_mul_f32 v[44:45], v[44:45], v[48:49]
	v_mul_f32_e32 v48, 0xbfb8aa3b, v46
	v_mul_f32_e32 v49, 0xbfb8aa3b, v47
	v_exp_f32_e32 v48, v48
	v_exp_f32_e32 v49, v49
	v_pk_mul_f32 v[40:41], v[44:45], v[40:41]
	v_add_f32_e32 v44, 1.0, v48
	v_add_f32_e32 v45, 1.0, v49
	v_mul_f32_e32 v48, 0xbfb8aa3b, v32
	v_mul_f32_e32 v49, 0xbfb8aa3b, v33
	v_rcp_f32_e32 v44, v44
	v_rcp_f32_e32 v45, v45
	v_exp_f32_e32 v48, v48
	v_exp_f32_e32 v49, v49
	v_pk_mul_f32 v[44:45], v[46:47], v[44:45]
	v_add_f32_e32 v46, 1.0, v48
	v_add_f32_e32 v47, 1.0, v49
	v_mul_f32_e32 v48, 0xbfb8aa3b, v34
	v_mul_f32_e32 v49, 0xbfb8aa3b, v35
	v_exp_f32_e32 v48, v48
	v_exp_f32_e32 v49, v49
	v_rcp_f32_e32 v46, v46
	v_rcp_f32_e32 v47, v47
	v_add_f32_e32 v48, 1.0, v48
	v_add_f32_e32 v49, 1.0, v49
	v_rcp_f32_e32 v48, v48
	v_rcp_f32_e32 v49, v49
	v_pk_mul_f32 v[32:33], v[32:33], v[46:47]
	v_pk_mul_f32 v[42:43], v[44:45], v[42:43]
	v_pk_mul_f32 v[36:37], v[32:33], v[36:37]
	v_pk_mul_f32 v[32:33], v[34:35], v[48:49]
	v_cvt_pk_bf16_f32 v34, v36, v37
	v_mul_f32_e32 v36, 0xbfb8aa3b, v28
	v_mul_f32_e32 v37, 0xbfb8aa3b, v29
	v_exp_f32_e32 v36, v36
	v_exp_f32_e32 v37, v37
	v_pk_mul_f32 v[38:39], v[32:33], v[38:39]
	v_lshl_add_u64 v[44:45], v[50:51], 0, v[112:113]
	v_cvt_pk_bf16_f32 v32, v40, v41
	v_cvt_pk_bf16_f32 v33, v42, v43
	v_cvt_pk_bf16_f32 v35, v38, v39
	global_store_dwordx4 v[44:45], v[32:35], off sc1
	s_nop 1
	v_add_f32_e32 v32, 1.0, v36
	v_add_f32_e32 v33, 1.0, v37
	v_rcp_f32_e32 v32, v32
	v_rcp_f32_e32 v33, v33
	v_add_u32_e32 v34, 0xa0, v144
	v_mad_i64_i32 v[34:35], s[28:29], v34, s58, v[136:137]
	v_pk_mul_f32 v[28:29], v[28:29], v[32:33]
	v_mul_f32_e32 v32, 0xbfb8aa3b, v30
	v_mul_f32_e32 v33, 0xbfb8aa3b, v31
	v_exp_f32_e32 v32, v32
	v_exp_f32_e32 v33, v33
	v_pk_mul_f32 v[24:25], v[28:29], v[24:25]
	v_add_f32_e32 v28, 1.0, v32
	v_add_f32_e32 v29, 1.0, v33
	v_mul_f32_e32 v32, 0xbfb8aa3b, v16
	v_mul_f32_e32 v33, 0xbfb8aa3b, v17
	v_rcp_f32_e32 v28, v28
	v_rcp_f32_e32 v29, v29
	v_exp_f32_e32 v32, v32
	v_exp_f32_e32 v33, v33
	v_pk_mul_f32 v[28:29], v[30:31], v[28:29]
	v_add_f32_e32 v30, 1.0, v32
	v_add_f32_e32 v31, 1.0, v33
	v_mul_f32_e32 v32, 0xbfb8aa3b, v18
	v_mul_f32_e32 v33, 0xbfb8aa3b, v19
	v_exp_f32_e32 v32, v32
	v_exp_f32_e32 v33, v33
	v_rcp_f32_e32 v30, v30
	v_rcp_f32_e32 v31, v31
	v_add_f32_e32 v32, 1.0, v32
	v_add_f32_e32 v33, 1.0, v33
	v_rcp_f32_e32 v32, v32
	v_rcp_f32_e32 v33, v33
	v_pk_mul_f32 v[16:17], v[16:17], v[30:31]
	v_pk_mul_f32 v[26:27], v[28:29], v[26:27]
	v_pk_mul_f32 v[20:21], v[16:17], v[20:21]
	v_pk_mul_f32 v[16:17], v[18:19], v[32:33]
	v_cvt_pk_bf16_f32 v18, v20, v21
	v_mul_f32_e32 v20, 0xbfb8aa3b, v12
	v_mul_f32_e32 v21, 0xbfb8aa3b, v13
	v_exp_f32_e32 v20, v20
	v_exp_f32_e32 v21, v21
	v_pk_mul_f32 v[22:23], v[16:17], v[22:23]
	v_lshl_add_u64 v[28:29], v[34:35], 0, v[112:113]
	v_cvt_pk_bf16_f32 v16, v24, v25
	v_cvt_pk_bf16_f32 v17, v26, v27
	v_cvt_pk_bf16_f32 v19, v22, v23
	global_store_dwordx4 v[28:29], v[16:19], off sc1
	s_nop 1
	v_add_f32_e32 v16, 1.0, v20
	v_add_f32_e32 v17, 1.0, v21
	v_rcp_f32_e32 v16, v16
	v_rcp_f32_e32 v17, v17
	v_add_u32_e32 v18, 0xb0, v144
	v_mad_i64_i32 v[18:19], s[28:29], v18, s58, v[136:137]
	v_pk_mul_f32 v[12:13], v[12:13], v[16:17]
	v_mul_f32_e32 v16, 0xbfb8aa3b, v14
	v_mul_f32_e32 v17, 0xbfb8aa3b, v15
	v_exp_f32_e32 v16, v16
	v_exp_f32_e32 v17, v17
	v_pk_mul_f32 v[8:9], v[12:13], v[8:9]
	s_mov_b64 s[28:29], -1
	v_add_f32_e32 v12, 1.0, v16
	v_add_f32_e32 v13, 1.0, v17
	v_mul_f32_e32 v16, 0xbfb8aa3b, v0
	v_mul_f32_e32 v17, 0xbfb8aa3b, v1
	v_rcp_f32_e32 v12, v12
	v_rcp_f32_e32 v13, v13
	v_exp_f32_e32 v16, v16
	v_exp_f32_e32 v17, v17
	v_pk_mul_f32 v[12:13], v[14:15], v[12:13]
	v_add_f32_e32 v14, 1.0, v16
	v_add_f32_e32 v15, 1.0, v17
	v_mul_f32_e32 v16, 0xbfb8aa3b, v2
	v_mul_f32_e32 v17, 0xbfb8aa3b, v3
	v_exp_f32_e32 v16, v16
	v_exp_f32_e32 v17, v17
	v_rcp_f32_e32 v14, v14
	v_rcp_f32_e32 v15, v15
	v_add_f32_e32 v16, 1.0, v16
	v_add_f32_e32 v17, 1.0, v17
	v_rcp_f32_e32 v16, v16
	v_rcp_f32_e32 v17, v17
	v_pk_mul_f32 v[0:1], v[0:1], v[14:15]
	v_pk_mul_f32 v[10:11], v[12:13], v[10:11]
	v_pk_mul_f32 v[4:5], v[0:1], v[4:5]
	v_pk_mul_f32 v[0:1], v[2:3], v[16:17]
	v_lshl_add_u64 v[12:13], v[18:19], 0, v[112:113]
	v_pk_mul_f32 v[6:7], v[0:1], v[6:7]
	v_cvt_pk_bf16_f32 v0, v8, v9
	v_cvt_pk_bf16_f32 v1, v10, v11
	v_cvt_pk_bf16_f32 v2, v4, v5
	v_cvt_pk_bf16_f32 v3, v6, v7
	global_store_dwordx4 v[12:13], v[0:3], off sc1
	s_cbranch_vccnz .LBB0_966
	s_andn2_b64 vcc, exec, s[6:7]
	s_cbranch_vccnz .LBB0_965
	s_barrier
	s_branch .LBB0_965

.LBB0_1049:
	v_mov_b32_e32 v137, v138
	s_lshl_b32 s22, s53, 8
	s_add_i32 s22, s22, s46
	v_and_or_b32 v136, v137, 15, s22
	s_lshl_b32 s22, s54, 8
	v_lshrrev_b32_e32 v137, 1, v137
	v_and_or_b32 v137, v137, 24, s22
	v_or_b32_e32 v144, s47, v137
	v_ashrrev_i32_e32 v137, 31, v136
	v_ashrrev_i32_e32 v145, 31, v144
	v_lshlrev_b64 v[146:147], 11, v[136:137]
	v_lshl_add_u64 v[146:147], s[10:11], 0, v[146:147]
	v_lshlrev_b64 v[144:145], 1, v[144:145]
	v_lshl_add_u64 v[146:147], v[146:147], 0, v[144:145]
	s_mov_b64 s[22:23], 0x40000
	v_cvt_pk_bf16_f32 v68, v68, v69
	v_cvt_pk_bf16_f32 v69, v70, v71
	v_cvt_pk_bf16_f32 v70, v64, v65
	v_lshl_add_u64 v[64:65], v[146:147], 0, s[22:23]
	s_mov_b32 s22, 0x40000
	v_cvt_pk_bf16_f32 v60, v60, v61
	v_cvt_pk_bf16_f32 v61, v62, v63
	v_cvt_pk_bf16_f32 v62, v56, v57
	v_add_co_u32_e32 v56, vcc, s22, v146
	v_cvt_pk_bf16_f32 v44, v44, v45
	v_cvt_pk_bf16_f32 v45, v46, v47
	v_cvt_pk_bf16_f32 v46, v40, v41
	v_cvt_pk_bf16_f32 v47, v42, v43
	s_mov_b64 s[22:23], 0x48000
	v_addc_co_u32_e32 v57, vcc, 0, v147, vcc
	global_store_dwordx4 v[64:65], v[44:47], off offset:256 sc1
	v_cvt_pk_bf16_f32 v108, v108, v109
	v_cvt_pk_bf16_f32 v109, v110, v111
	v_lshl_add_u64 v[44:45], v[146:147], 0, s[22:23]
	s_mov_b32 s22, 0x48000
	v_cvt_pk_bf16_f32 v110, v104, v105
	v_or_b32_e32 v104, 16, v136
	v_add_co_u32_e32 v46, vcc, s22, v146
	v_cvt_pk_bf16_f32 v28, v28, v29
	v_cvt_pk_bf16_f32 v29, v30, v31
	v_cvt_pk_bf16_f32 v30, v24, v25
	v_cvt_pk_bf16_f32 v31, v26, v27
	s_mov_b64 s[22:23], 0x50000
	v_ashrrev_i32_e32 v105, 31, v104
	v_cvt_pk_bf16_f32 v92, v92, v93
	v_cvt_pk_bf16_f32 v93, v94, v95
	v_cvt_pk_bf16_f32 v94, v88, v89
	v_or_b32_e32 v88, 32, v136
	v_addc_co_u32_e32 v47, vcc, 0, v147, vcc
	global_store_dwordx4 v[44:45], v[28:31], off offset:256 sc1
	v_lshlrev_b64 v[104:105], 11, v[104:105]
	v_ashrrev_i32_e32 v89, 31, v88
	v_lshl_add_u64 v[28:29], v[146:147], 0, s[22:23]
	s_mov_b32 s22, 0x50000
	v_cvt_pk_bf16_f32 v76, v76, v77
	v_cvt_pk_bf16_f32 v77, v78, v79
	v_cvt_pk_bf16_f32 v78, v72, v73
	v_or_b32_e32 v72, 48, v136
	v_add_co_u32_e32 v30, vcc, s22, v146
	v_cvt_pk_bf16_f32 v111, v106, v107
	v_lshl_add_u64 v[104:105], s[10:11], 0, v[104:105]
	v_lshlrev_b64 v[88:89], 11, v[88:89]
	v_ashrrev_i32_e32 v73, 31, v72
	v_addc_co_u32_e32 v31, vcc, 0, v147, vcc
	v_cvt_pk_bf16_f32 v12, v12, v13
	v_cvt_pk_bf16_f32 v13, v14, v15
	v_cvt_pk_bf16_f32 v14, v8, v9
	v_cvt_pk_bf16_f32 v15, v10, v11
	s_mov_b32 s22, 0x58000
	global_store_dwordx4 v[146:147], v[108:111], off offset:256 sc1
	v_cvt_pk_bf16_f32 v95, v90, v91
	v_lshl_add_u64 v[88:89], s[10:11], 0, v[88:89]
	v_lshl_add_u64 v[108:109], v[104:105], 0, v[144:145]
	v_lshlrev_b64 v[72:73], 11, v[72:73]
	global_store_dwordx4 v[28:29], v[12:15], off offset:256 sc1
	global_store_dwordx4 v[108:109], v[92:95], off offset:256 sc1
	v_cvt_pk_bf16_f32 v79, v74, v75
	v_add_co_u32_e32 v14, vcc, s22, v146
	v_lshl_add_u64 v[92:93], v[88:89], 0, v[144:145]
	v_lshl_add_u64 v[72:73], s[10:11], 0, v[72:73]
	v_addc_co_u32_e32 v15, vcc, 0, v147, vcc
	v_cvt_pk_bf16_f32 v124, v124, v125
	v_cvt_pk_bf16_f32 v125, v126, v127
	v_cvt_pk_bf16_f32 v126, v120, v121
	v_cvt_pk_bf16_f32 v127, v122, v123
	v_cvt_pk_bf16_f32 v104, v116, v117
	v_cvt_pk_bf16_f32 v105, v118, v119
	v_cvt_pk_bf16_f32 v106, v112, v113
	v_cvt_pk_bf16_f32 v107, v114, v115
	v_cvt_pk_bf16_f32 v88, v100, v101
	v_cvt_pk_bf16_f32 v89, v102, v103
	v_cvt_pk_bf16_f32 v90, v96, v97
	v_cvt_pk_bf16_f32 v91, v98, v99
	global_store_dwordx4 v[92:93], v[76:79], off offset:256 sc1
	v_cvt_pk_bf16_f32 v74, v80, v81
	v_cvt_pk_bf16_f32 v75, v82, v83
	v_lshl_add_u64 v[76:77], v[72:73], 0, v[144:145]
	v_cvt_pk_bf16_f32 v72, v84, v85
	v_cvt_pk_bf16_f32 v73, v86, v87
	v_cvt_pk_bf16_f32 v71, v66, v67
	v_cvt_pk_bf16_f32 v63, v58, v59
	v_cvt_pk_bf16_f32 v40, v52, v53
	v_cvt_pk_bf16_f32 v41, v54, v55
	v_cvt_pk_bf16_f32 v42, v48, v49
	v_cvt_pk_bf16_f32 v43, v50, v51
	v_cvt_pk_bf16_f32 v24, v36, v37
	v_cvt_pk_bf16_f32 v25, v38, v39
	v_cvt_pk_bf16_f32 v26, v32, v33
	v_cvt_pk_bf16_f32 v27, v34, v35
	v_lshl_add_u64 v[12:13], v[146:147], 0, s[2:3]
	v_cvt_pk_bf16_f32 v8, v20, v21
	v_cvt_pk_bf16_f32 v9, v22, v23
	v_cvt_pk_bf16_f32 v10, v16, v17
	v_cvt_pk_bf16_f32 v11, v18, v19
	v_cvt_pk_bf16_f32 v4, v4, v5
	v_cvt_pk_bf16_f32 v5, v6, v7
	v_cvt_pk_bf16_f32 v6, v0, v1
	v_cvt_pk_bf16_f32 v7, v2, v3
	s_and_b64 vcc, exec, s[36:37]
	s_mov_b64 s[22:23], -1
	global_store_dwordx4 v[146:147], v[124:127], off sc1
	global_store_dwordx4 v[108:109], v[104:107], off sc1
	global_store_dwordx4 v[92:93], v[88:91], off sc1
	global_store_dwordx4 v[76:77], v[72:75], off sc1
	global_store_dwordx4 v[76:77], v[68:71], off offset:256 sc1
	global_store_dwordx4 v[56:57], v[60:63], off sc1
	global_store_dwordx4 v[46:47], v[40:43], off sc1
	global_store_dwordx4 v[30:31], v[24:27], off sc1
	global_store_dwordx4 v[14:15], v[8:11], off sc1
	global_store_dwordx4 v[12:13], v[4:7], off offset:256 sc1
	s_cbranch_vccnz .LBB0_1034
	s_andn2_b64 vcc, exec, s[8:9]
	s_cbranch_vccnz .LBB0_1033
	s_barrier
	s_branch .LBB0_1033
